# v38 + GEMM K-loops: the s_nop 0 between each M0 write and its LDS-DMA load replaced by one of the segment's trailing ds_read_b128
# baseline (speedup 1.0000x reference)
.LBB0_161:
	s_ashr_i32 s23, s22, 31
	s_lshl_b64 s[8:9], s[22:23], 20
	v_readlane_b32 s20, v254, 38
	v_readlane_b32 s21, v254, 39
	s_add_u32 s8, s20, s8
	s_addc_u32 s9, s21, s9
	s_and_b64 s[20:21], s[40:41], exec
	s_cselect_b32 s13, s9, s43
	s_cselect_b32 s20, s8, s42
	s_ashr_i32 s19, s18, 31
	s_lshl_b64 s[28:29], s[18:19], 20
	v_readlane_b32 s30, v254, 22
	v_readlane_b32 s31, v254, 23
	s_add_u32 s28, s30, s28
	s_addc_u32 s29, s31, s29
	s_and_b64 s[30:31], s[40:41], exec
	s_cselect_b32 s19, s29, s45
	s_cselect_b32 s21, s28, s44
	s_add_u32 s42, s42, 0x80080
	s_addc_u32 s43, s43, 0
	s_add_u32 s23, s44, 0x100
	s_addc_u32 s25, s45, 0
	s_mov_b32 s30, -2
	v_readlane_b32 s52, v255, 20
	v_readlane_b32 s53, v255, 21
	v_readlane_b32 s72, v255, 22
	v_readlane_b32 s73, v255, 23
	s_mov_b64 s[74:75], 0x80
	s_add_u32 s31, s42, 0xfff80080
	s_addc_u32 s44, s43, -1
	s_add_i32 s47, 0, 0x10000
	s_cmp_eq_u32 s30, 28
	s_cselect_b32 s49, s13, s44
	s_cselect_b32 s48, s20, s31
	ds_read_b128 v[144:147], v1
	ds_read_b128 v[148:151], v141
	s_cselect_b32 s45, s19, s25
	s_cselect_b32 s44, s21, s23
	s_add_i32 s31, 0, 0x14000
	ds_read_b128 v[152:155], v1 offset:2048
	ds_read_b128 v[156:159], v141 offset:2048
	ds_read_b128 v[160:163], v1 offset:16384
	ds_read_b128 v[164:167], v141 offset:16384
	ds_read_b128 v[168:171], v1 offset:18432
	ds_read_b128 v[172:175], v141 offset:18432
	s_add_i32 m0, s34, 0xc000
	ds_read_b128 v[176:179], v142
	ds_read_b128 v[184:187], v142 offset:2048
	ds_read_b128 v[188:191], v143
	ds_read_b128 v[192:195], v143 offset:2048
	ds_read_b128 v[196:199], v142 offset:4096
	ds_read_b128 v[200:203], v142 offset:6144
	ds_read_b128 v[204:207], v143 offset:4096
	global_load_lds_dwordx4 v138, s[42:43]
	s_add_i32 m0, s34, 0xe000
	ds_read_b128 v[208:211], v143 offset:6144
	global_load_lds_dwordx4 v134, s[42:43]
	s_waitcnt vmcnt(8)
	s_waitcnt lgkmcnt(0)
	s_barrier
	v_mfma_f32_16x16x32_bf16 v[128:131], v[144:147], v[176:179], 0
	v_mfma_f32_16x16x32_bf16 v[124:127], v[152:155], v[176:179], 0
	v_mfma_f32_16x16x32_bf16 v[112:115], v[144:147], v[184:187], 0
	v_mfma_f32_16x16x32_bf16 v[108:111], v[152:155], v[184:187], 0
	v_mfma_f32_16x16x32_bf16 v[96:99], v[144:147], v[196:199], 0
	v_mfma_f32_16x16x32_bf16 v[92:95], v[152:155], v[196:199], 0
	v_mfma_f32_16x16x32_bf16 v[80:83], v[144:147], v[200:203], 0
	v_mfma_f32_16x16x32_bf16 v[76:79], v[152:155], v[200:203], 0
	v_mfma_f32_16x16x32_bf16 v[128:131], v[148:151], v[188:191], v[128:131]
	v_mfma_f32_16x16x32_bf16 v[124:127], v[156:159], v[188:191], v[124:127]
	v_mfma_f32_16x16x32_bf16 v[112:115], v[148:151], v[192:195], v[112:115]
	v_mfma_f32_16x16x32_bf16 v[108:111], v[156:159], v[192:195], v[108:111]
	v_mfma_f32_16x16x32_bf16 v[96:99], v[148:151], v[204:207], v[96:99]
	v_mfma_f32_16x16x32_bf16 v[92:95], v[156:159], v[204:207], v[92:95]
	v_mfma_f32_16x16x32_bf16 v[80:83], v[148:151], v[208:211], v[80:83]
	v_mfma_f32_16x16x32_bf16 v[76:79], v[156:159], v[208:211], v[76:79]
	v_mfma_f32_16x16x32_bf16 v[120:123], v[160:163], v[176:179], 0
	v_mfma_f32_16x16x32_bf16 v[116:119], v[168:171], v[176:179], 0
	v_mfma_f32_16x16x32_bf16 v[104:107], v[160:163], v[184:187], 0
	v_mfma_f32_16x16x32_bf16 v[100:103], v[168:171], v[184:187], 0
	v_mfma_f32_16x16x32_bf16 v[88:91], v[160:163], v[196:199], 0
	v_mfma_f32_16x16x32_bf16 v[84:87], v[168:171], v[196:199], 0
	v_mfma_f32_16x16x32_bf16 v[72:75], v[160:163], v[200:203], 0
	v_mfma_f32_16x16x32_bf16 v[68:71], v[168:171], v[200:203], 0
	v_mfma_f32_16x16x32_bf16 v[120:123], v[164:167], v[188:191], v[120:123]
	v_mfma_f32_16x16x32_bf16 v[116:119], v[172:175], v[188:191], v[116:119]
	v_mfma_f32_16x16x32_bf16 v[104:107], v[164:167], v[192:195], v[104:107]
	v_mfma_f32_16x16x32_bf16 v[100:103], v[172:175], v[192:195], v[100:103]
	v_mfma_f32_16x16x32_bf16 v[88:91], v[164:167], v[204:207], v[88:91]
	v_mfma_f32_16x16x32_bf16 v[84:87], v[172:175], v[204:207], v[84:87]
	v_mfma_f32_16x16x32_bf16 v[72:75], v[164:167], v[208:211], v[72:75]
	v_mfma_f32_16x16x32_bf16 v[68:71], v[172:175], v[208:211], v[68:71]
	s_barrier
	s_add_i32 s47, s47, s33
	s_mov_b32 m0, s47
	ds_read_b128 v[176:179], v142 offset:16384
	ds_read_b128 v[184:187], v142 offset:18432
	ds_read_b128 v[188:191], v143 offset:16384
	ds_read_b128 v[192:195], v143 offset:18432
	global_load_lds_dwordx4 v136, s[44:45]
	s_add_i32 m0, s47, 0x2000
	s_add_u32 s50, s44, 0x80000
	s_addc_u32 s51, s45, 0
	s_add_i32 s31, s31, s33
	global_load_lds_dwordx4 v132, s[44:45]
	s_mov_b32 m0, s31
	ds_read_b128 v[196:199], v142 offset:20480
	global_load_lds_dwordx4 v136, s[50:51]
	s_add_i32 m0, s31, 0x2000
	ds_read_b128 v[200:203], v142 offset:22528
	global_load_lds_dwordx4 v132, s[50:51]
	s_mov_b32 m0, s34
	ds_read_b128 v[204:207], v143 offset:20480
	global_load_lds_dwordx4 v138, s[48:49]
	s_mov_b32 m0, s35
	ds_read_b128 v[208:211], v143 offset:22528
	global_load_lds_dwordx4 v134, s[48:49]
	s_waitcnt vmcnt(8)
	s_waitcnt lgkmcnt(0)
	s_barrier
	v_mfma_f32_16x16x32_bf16 v[64:67], v[144:147], v[176:179], 0
	v_mfma_f32_16x16x32_bf16 v[60:63], v[152:155], v[176:179], 0
	v_mfma_f32_16x16x32_bf16 v[48:51], v[144:147], v[184:187], 0
	v_mfma_f32_16x16x32_bf16 v[44:47], v[152:155], v[184:187], 0
	v_mfma_f32_16x16x32_bf16 v[30:33], v[144:147], v[196:199], 0
	v_mfma_f32_16x16x32_bf16 v[26:29], v[152:155], v[196:199], 0
	v_mfma_f32_16x16x32_bf16 v[14:17], v[144:147], v[200:203], 0
	v_mfma_f32_16x16x32_bf16 v[10:13], v[152:155], v[200:203], 0
	v_mfma_f32_16x16x32_bf16 v[64:67], v[148:151], v[188:191], v[64:67]
	v_mfma_f32_16x16x32_bf16 v[60:63], v[156:159], v[188:191], v[60:63]
	v_mfma_f32_16x16x32_bf16 v[48:51], v[148:151], v[192:195], v[48:51]
	v_mfma_f32_16x16x32_bf16 v[44:47], v[156:159], v[192:195], v[44:47]
	v_mfma_f32_16x16x32_bf16 v[30:33], v[148:151], v[204:207], v[30:33]
	v_mfma_f32_16x16x32_bf16 v[26:29], v[156:159], v[204:207], v[26:29]
	v_mfma_f32_16x16x32_bf16 v[14:17], v[148:151], v[208:211], v[14:17]
	v_mfma_f32_16x16x32_bf16 v[10:13], v[156:159], v[208:211], v[10:13]
	v_mfma_f32_16x16x32_bf16 v[56:59], v[160:163], v[176:179], 0
	v_mfma_f32_16x16x32_bf16 v[52:55], v[168:171], v[176:179], 0
	v_mfma_f32_16x16x32_bf16 v[40:43], v[160:163], v[184:187], 0
	v_mfma_f32_16x16x32_bf16 v[36:39], v[168:171], v[184:187], 0
	v_mfma_f32_16x16x32_bf16 v[22:25], v[160:163], v[196:199], 0
	v_mfma_f32_16x16x32_bf16 v[18:21], v[168:171], v[196:199], 0
	v_mfma_f32_16x16x32_bf16 v[6:9], v[160:163], v[200:203], 0
	v_mfma_f32_16x16x32_bf16 v[2:5], v[168:171], v[200:203], 0
	v_mfma_f32_16x16x32_bf16 v[56:59], v[164:167], v[188:191], v[56:59]
	v_mfma_f32_16x16x32_bf16 v[52:55], v[172:175], v[188:191], v[52:55]
	v_mfma_f32_16x16x32_bf16 v[40:43], v[164:167], v[192:195], v[40:43]
	v_mfma_f32_16x16x32_bf16 v[36:39], v[172:175], v[192:195], v[36:39]
	v_mfma_f32_16x16x32_bf16 v[22:25], v[164:167], v[204:207], v[22:25]
	v_mfma_f32_16x16x32_bf16 v[18:21], v[172:175], v[204:207], v[18:21]
	v_mfma_f32_16x16x32_bf16 v[6:9], v[164:167], v[208:211], v[6:9]
	v_mfma_f32_16x16x32_bf16 v[2:5], v[172:175], v[208:211], v[2:5]
	s_barrier
	s_add_i32 s31, 0, 0x18000
	ds_read_b128 v[144:147], v1 offset:32768
	ds_read_b128 v[148:151], v141 offset:32768
	s_add_i32 s47, 0, 0x1c000
	ds_read_b128 v[152:155], v1 offset:34816
	ds_read_b128 v[156:159], v141 offset:34816
	ds_read_b128 v[160:163], v1 offset:49152
	ds_read_b128 v[164:167], v141 offset:49152
	ds_read_b128 v[168:171], v1 offset:51200
	ds_read_b128 v[172:175], v141 offset:51200
	s_mov_b64 s[100:101], s[48:49]
	s_add_u32 s48, s48, 0x80000
	s_addc_u32 s49, s49, 0
	s_mov_b32 m0, s54
	ds_read_b128 v[176:179], v142 offset:32768
	ds_read_b128 v[184:187], v142 offset:34816
	ds_read_b128 v[188:191], v143 offset:32768
	ds_read_b128 v[192:195], v143 offset:34816
	ds_read_b128 v[196:199], v142 offset:36864
	ds_read_b128 v[200:203], v142 offset:38912
	ds_read_b128 v[204:207], v143 offset:36864
	global_load_lds_dwordx4 v138, s[48:49]
	s_mov_b32 m0, s55
	ds_read_b128 v[208:211], v143 offset:38912
	global_load_lds_dwordx4 v134, s[48:49]
	s_waitcnt vmcnt(8)
	s_waitcnt lgkmcnt(0)
	s_barrier
	v_mfma_f32_16x16x32_bf16 v[128:131], v[144:147], v[176:179], v[128:131]
	v_mfma_f32_16x16x32_bf16 v[124:127], v[152:155], v[176:179], v[124:127]
	v_mfma_f32_16x16x32_bf16 v[112:115], v[144:147], v[184:187], v[112:115]
	v_mfma_f32_16x16x32_bf16 v[108:111], v[152:155], v[184:187], v[108:111]
	v_mfma_f32_16x16x32_bf16 v[96:99], v[144:147], v[196:199], v[96:99]
	v_mfma_f32_16x16x32_bf16 v[92:95], v[152:155], v[196:199], v[92:95]
	v_mfma_f32_16x16x32_bf16 v[80:83], v[144:147], v[200:203], v[80:83]
	v_mfma_f32_16x16x32_bf16 v[76:79], v[152:155], v[200:203], v[76:79]
	v_mfma_f32_16x16x32_bf16 v[128:131], v[148:151], v[188:191], v[128:131]
	v_mfma_f32_16x16x32_bf16 v[124:127], v[156:159], v[188:191], v[124:127]
	v_mfma_f32_16x16x32_bf16 v[112:115], v[148:151], v[192:195], v[112:115]
	v_mfma_f32_16x16x32_bf16 v[108:111], v[156:159], v[192:195], v[108:111]
	v_mfma_f32_16x16x32_bf16 v[96:99], v[148:151], v[204:207], v[96:99]
	v_mfma_f32_16x16x32_bf16 v[92:95], v[156:159], v[204:207], v[92:95]
	v_mfma_f32_16x16x32_bf16 v[80:83], v[148:151], v[208:211], v[80:83]
	v_mfma_f32_16x16x32_bf16 v[76:79], v[156:159], v[208:211], v[76:79]
	v_mfma_f32_16x16x32_bf16 v[120:123], v[160:163], v[176:179], v[120:123]
	v_mfma_f32_16x16x32_bf16 v[116:119], v[168:171], v[176:179], v[116:119]
	v_mfma_f32_16x16x32_bf16 v[104:107], v[160:163], v[184:187], v[104:107]
	v_mfma_f32_16x16x32_bf16 v[100:103], v[168:171], v[184:187], v[100:103]
	v_mfma_f32_16x16x32_bf16 v[88:91], v[160:163], v[196:199], v[88:91]
	v_mfma_f32_16x16x32_bf16 v[84:87], v[168:171], v[196:199], v[84:87]
	v_mfma_f32_16x16x32_bf16 v[72:75], v[160:163], v[200:203], v[72:75]
	v_mfma_f32_16x16x32_bf16 v[68:71], v[168:171], v[200:203], v[68:71]
	v_mfma_f32_16x16x32_bf16 v[120:123], v[164:167], v[188:191], v[120:123]
	v_mfma_f32_16x16x32_bf16 v[116:119], v[172:175], v[188:191], v[116:119]
	v_mfma_f32_16x16x32_bf16 v[104:107], v[164:167], v[192:195], v[104:107]
	v_mfma_f32_16x16x32_bf16 v[100:103], v[172:175], v[192:195], v[100:103]
	v_mfma_f32_16x16x32_bf16 v[88:91], v[164:167], v[204:207], v[88:91]
	v_mfma_f32_16x16x32_bf16 v[84:87], v[172:175], v[204:207], v[84:87]
	v_mfma_f32_16x16x32_bf16 v[72:75], v[164:167], v[208:211], v[72:75]
	v_mfma_f32_16x16x32_bf16 v[68:71], v[172:175], v[208:211], v[68:71]
	s_barrier
	s_add_i32 s31, s31, s33
	s_add_i32 m0, s31, 0xffffff80
	ds_read_b128 v[176:179], v142 offset:49152
	ds_read_b128 v[184:187], v142 offset:51200
	ds_read_b128 v[188:191], v143 offset:49152
	ds_read_b128 v[192:195], v143 offset:51200
	global_load_lds_dwordx4 v136, s[44:45] offset:128
	s_add_i32 m0, s31, 0x1f80
	s_mov_b64 s[98:99], s[44:45]
	s_add_u32 s44, s44, 0x80080
	s_addc_u32 s45, s45, 0
	s_add_i32 s31, s47, s33
	global_load_lds_dwordx4 v132, s[98:99] offset:128
	s_mov_b32 m0, s31
	ds_read_b128 v[196:199], v142 offset:53248
	global_load_lds_dwordx4 v136, s[44:45]
	s_add_i32 m0, s31, 0x2000
	ds_read_b128 v[200:203], v142 offset:55296
	global_load_lds_dwordx4 v132, s[44:45]
	s_add_i32 m0, s56, 0xffffff80
	ds_read_b128 v[204:207], v143 offset:53248
	global_load_lds_dwordx4 v138, s[100:101] offset:128
	s_add_i32 m0, s57, 0xffffff80
	ds_read_b128 v[208:211], v143 offset:55296
	global_load_lds_dwordx4 v134, s[100:101] offset:128
	s_waitcnt vmcnt(8)
	s_waitcnt lgkmcnt(0)
	s_barrier
	v_mfma_f32_16x16x32_bf16 v[64:67], v[144:147], v[176:179], v[64:67]
	v_mfma_f32_16x16x32_bf16 v[60:63], v[152:155], v[176:179], v[60:63]
	v_mfma_f32_16x16x32_bf16 v[48:51], v[144:147], v[184:187], v[48:51]
	v_mfma_f32_16x16x32_bf16 v[44:47], v[152:155], v[184:187], v[44:47]
	v_mfma_f32_16x16x32_bf16 v[30:33], v[144:147], v[196:199], v[30:33]
	v_mfma_f32_16x16x32_bf16 v[26:29], v[152:155], v[196:199], v[26:29]
	v_mfma_f32_16x16x32_bf16 v[14:17], v[144:147], v[200:203], v[14:17]
	v_mfma_f32_16x16x32_bf16 v[10:13], v[152:155], v[200:203], v[10:13]
	v_mfma_f32_16x16x32_bf16 v[64:67], v[148:151], v[188:191], v[64:67]
	v_mfma_f32_16x16x32_bf16 v[60:63], v[156:159], v[188:191], v[60:63]
	v_mfma_f32_16x16x32_bf16 v[48:51], v[148:151], v[192:195], v[48:51]
	v_mfma_f32_16x16x32_bf16 v[44:47], v[156:159], v[192:195], v[44:47]
	v_mfma_f32_16x16x32_bf16 v[30:33], v[148:151], v[204:207], v[30:33]
	v_mfma_f32_16x16x32_bf16 v[26:29], v[156:159], v[204:207], v[26:29]
	v_mfma_f32_16x16x32_bf16 v[14:17], v[148:151], v[208:211], v[14:17]
	v_mfma_f32_16x16x32_bf16 v[10:13], v[156:159], v[208:211], v[10:13]
	v_mfma_f32_16x16x32_bf16 v[56:59], v[160:163], v[176:179], v[56:59]
	v_mfma_f32_16x16x32_bf16 v[52:55], v[168:171], v[176:179], v[52:55]
	v_mfma_f32_16x16x32_bf16 v[40:43], v[160:163], v[184:187], v[40:43]
	v_mfma_f32_16x16x32_bf16 v[36:39], v[168:171], v[184:187], v[36:39]
	v_mfma_f32_16x16x32_bf16 v[22:25], v[160:163], v[196:199], v[22:25]
	v_mfma_f32_16x16x32_bf16 v[18:21], v[168:171], v[196:199], v[18:21]
	v_mfma_f32_16x16x32_bf16 v[6:9], v[160:163], v[200:203], v[6:9]
	v_mfma_f32_16x16x32_bf16 v[2:5], v[168:171], v[200:203], v[2:5]
	v_mfma_f32_16x16x32_bf16 v[56:59], v[164:167], v[188:191], v[56:59]
	v_mfma_f32_16x16x32_bf16 v[52:55], v[172:175], v[188:191], v[52:55]
	v_mfma_f32_16x16x32_bf16 v[40:43], v[164:167], v[192:195], v[40:43]
	v_mfma_f32_16x16x32_bf16 v[36:39], v[172:175], v[192:195], v[36:39]
	v_mfma_f32_16x16x32_bf16 v[22:25], v[164:167], v[204:207], v[22:25]
	v_mfma_f32_16x16x32_bf16 v[18:21], v[172:175], v[204:207], v[18:21]
	v_mfma_f32_16x16x32_bf16 v[6:9], v[164:167], v[208:211], v[6:9]
	v_mfma_f32_16x16x32_bf16 v[2:5], v[172:175], v[208:211], v[2:5]
	s_barrier
	s_add_i32 s30, s30, 2
	s_add_u32 s42, s42, 0x100
	s_addc_u32 s43, s43, 0
	s_add_u32 s23, s23, 0x100
	s_addc_u32 s25, s25, 0
	s_cmp_gt_u32 s30, 29
	s_cbranch_scc1 .Lpeel_done_P1
.LBB0_162:
	s_add_u32 s31, s42, 0xfff80080
	s_addc_u32 s44, s43, -1
	s_add_i32 s47, 0, 0x10000
	s_cmp_eq_u32 s30, 28
	s_cselect_b32 s49, s13, s44
	s_cselect_b32 s48, s20, s31
	ds_read_b128 v[144:147], v1
	ds_read_b128 v[148:151], v141
	s_cselect_b32 s45, s19, s25
	s_cselect_b32 s44, s21, s23
	s_add_i32 s31, 0, 0x14000
	ds_read_b128 v[152:155], v1 offset:2048
	ds_read_b128 v[156:159], v141 offset:2048
	ds_read_b128 v[160:163], v1 offset:16384
	ds_read_b128 v[164:167], v141 offset:16384
	ds_read_b128 v[168:171], v1 offset:18432
	ds_read_b128 v[172:175], v141 offset:18432
	s_add_i32 m0, s34, 0xc000
	ds_read_b128 v[176:179], v142
	ds_read_b128 v[184:187], v142 offset:2048
	ds_read_b128 v[188:191], v143
	ds_read_b128 v[192:195], v143 offset:2048
	ds_read_b128 v[196:199], v142 offset:4096
	ds_read_b128 v[200:203], v142 offset:6144
	ds_read_b128 v[204:207], v143 offset:4096
	global_load_lds_dwordx4 v138, s[42:43]
	s_add_i32 m0, s34, 0xe000
	ds_read_b128 v[208:211], v143 offset:6144
	global_load_lds_dwordx4 v134, s[42:43]
	s_waitcnt vmcnt(8)
	s_waitcnt lgkmcnt(0)
	s_barrier
	v_mfma_f32_16x16x32_bf16 v[128:131], v[144:147], v[176:179], v[128:131]
	v_mfma_f32_16x16x32_bf16 v[124:127], v[152:155], v[176:179], v[124:127]
	v_mfma_f32_16x16x32_bf16 v[112:115], v[144:147], v[184:187], v[112:115]
	v_mfma_f32_16x16x32_bf16 v[108:111], v[152:155], v[184:187], v[108:111]
	v_mfma_f32_16x16x32_bf16 v[96:99], v[144:147], v[196:199], v[96:99]
	v_mfma_f32_16x16x32_bf16 v[92:95], v[152:155], v[196:199], v[92:95]
	v_mfma_f32_16x16x32_bf16 v[80:83], v[144:147], v[200:203], v[80:83]
	v_mfma_f32_16x16x32_bf16 v[76:79], v[152:155], v[200:203], v[76:79]
	v_mfma_f32_16x16x32_bf16 v[128:131], v[148:151], v[188:191], v[128:131]
	v_mfma_f32_16x16x32_bf16 v[124:127], v[156:159], v[188:191], v[124:127]
	v_mfma_f32_16x16x32_bf16 v[112:115], v[148:151], v[192:195], v[112:115]
	v_mfma_f32_16x16x32_bf16 v[108:111], v[156:159], v[192:195], v[108:111]
	v_mfma_f32_16x16x32_bf16 v[96:99], v[148:151], v[204:207], v[96:99]
	v_mfma_f32_16x16x32_bf16 v[92:95], v[156:159], v[204:207], v[92:95]
	v_mfma_f32_16x16x32_bf16 v[80:83], v[148:151], v[208:211], v[80:83]
	v_mfma_f32_16x16x32_bf16 v[76:79], v[156:159], v[208:211], v[76:79]
	v_mfma_f32_16x16x32_bf16 v[120:123], v[160:163], v[176:179], v[120:123]
	v_mfma_f32_16x16x32_bf16 v[116:119], v[168:171], v[176:179], v[116:119]
	v_mfma_f32_16x16x32_bf16 v[104:107], v[160:163], v[184:187], v[104:107]
	v_mfma_f32_16x16x32_bf16 v[100:103], v[168:171], v[184:187], v[100:103]
	v_mfma_f32_16x16x32_bf16 v[88:91], v[160:163], v[196:199], v[88:91]
	v_mfma_f32_16x16x32_bf16 v[84:87], v[168:171], v[196:199], v[84:87]
	v_mfma_f32_16x16x32_bf16 v[72:75], v[160:163], v[200:203], v[72:75]
	v_mfma_f32_16x16x32_bf16 v[68:71], v[168:171], v[200:203], v[68:71]
	v_mfma_f32_16x16x32_bf16 v[120:123], v[164:167], v[188:191], v[120:123]
	v_mfma_f32_16x16x32_bf16 v[116:119], v[172:175], v[188:191], v[116:119]
	v_mfma_f32_16x16x32_bf16 v[104:107], v[164:167], v[192:195], v[104:107]
	v_mfma_f32_16x16x32_bf16 v[100:103], v[172:175], v[192:195], v[100:103]
	v_mfma_f32_16x16x32_bf16 v[88:91], v[164:167], v[204:207], v[88:91]
	v_mfma_f32_16x16x32_bf16 v[84:87], v[172:175], v[204:207], v[84:87]
	v_mfma_f32_16x16x32_bf16 v[72:75], v[164:167], v[208:211], v[72:75]
	v_mfma_f32_16x16x32_bf16 v[68:71], v[172:175], v[208:211], v[68:71]
	s_barrier
	s_add_i32 s47, s47, s33
	s_mov_b32 m0, s47
	ds_read_b128 v[176:179], v142 offset:16384
	ds_read_b128 v[184:187], v142 offset:18432
	ds_read_b128 v[188:191], v143 offset:16384
	ds_read_b128 v[192:195], v143 offset:18432
	global_load_lds_dwordx4 v136, s[44:45]
	s_add_i32 m0, s47, 0x2000
	s_add_u32 s50, s44, 0x80000
	s_addc_u32 s51, s45, 0
	s_add_i32 s31, s31, s33
	global_load_lds_dwordx4 v132, s[44:45]
	s_mov_b32 m0, s31
	ds_read_b128 v[196:199], v142 offset:20480
	global_load_lds_dwordx4 v136, s[50:51]
	s_add_i32 m0, s31, 0x2000
	ds_read_b128 v[200:203], v142 offset:22528
	global_load_lds_dwordx4 v132, s[50:51]
	s_mov_b32 m0, s34
	ds_read_b128 v[204:207], v143 offset:20480
	global_load_lds_dwordx4 v138, s[48:49]
	s_mov_b32 m0, s35
	ds_read_b128 v[208:211], v143 offset:22528
	global_load_lds_dwordx4 v134, s[48:49]
	s_waitcnt vmcnt(8)
	s_waitcnt lgkmcnt(0)
	s_barrier
	v_mfma_f32_16x16x32_bf16 v[64:67], v[144:147], v[176:179], v[64:67]
	v_mfma_f32_16x16x32_bf16 v[60:63], v[152:155], v[176:179], v[60:63]
	v_mfma_f32_16x16x32_bf16 v[48:51], v[144:147], v[184:187], v[48:51]
	v_mfma_f32_16x16x32_bf16 v[44:47], v[152:155], v[184:187], v[44:47]
	v_mfma_f32_16x16x32_bf16 v[30:33], v[144:147], v[196:199], v[30:33]
	v_mfma_f32_16x16x32_bf16 v[26:29], v[152:155], v[196:199], v[26:29]
	v_mfma_f32_16x16x32_bf16 v[14:17], v[144:147], v[200:203], v[14:17]
	v_mfma_f32_16x16x32_bf16 v[10:13], v[152:155], v[200:203], v[10:13]
	v_mfma_f32_16x16x32_bf16 v[64:67], v[148:151], v[188:191], v[64:67]
	v_mfma_f32_16x16x32_bf16 v[60:63], v[156:159], v[188:191], v[60:63]
	v_mfma_f32_16x16x32_bf16 v[48:51], v[148:151], v[192:195], v[48:51]
	v_mfma_f32_16x16x32_bf16 v[44:47], v[156:159], v[192:195], v[44:47]
	v_mfma_f32_16x16x32_bf16 v[30:33], v[148:151], v[204:207], v[30:33]
	v_mfma_f32_16x16x32_bf16 v[26:29], v[156:159], v[204:207], v[26:29]
	v_mfma_f32_16x16x32_bf16 v[14:17], v[148:151], v[208:211], v[14:17]
	v_mfma_f32_16x16x32_bf16 v[10:13], v[156:159], v[208:211], v[10:13]
	v_mfma_f32_16x16x32_bf16 v[56:59], v[160:163], v[176:179], v[56:59]
	v_mfma_f32_16x16x32_bf16 v[52:55], v[168:171], v[176:179], v[52:55]
	v_mfma_f32_16x16x32_bf16 v[40:43], v[160:163], v[184:187], v[40:43]
	v_mfma_f32_16x16x32_bf16 v[36:39], v[168:171], v[184:187], v[36:39]
	v_mfma_f32_16x16x32_bf16 v[22:25], v[160:163], v[196:199], v[22:25]
	v_mfma_f32_16x16x32_bf16 v[18:21], v[168:171], v[196:199], v[18:21]
	v_mfma_f32_16x16x32_bf16 v[6:9], v[160:163], v[200:203], v[6:9]
	v_mfma_f32_16x16x32_bf16 v[2:5], v[168:171], v[200:203], v[2:5]
	v_mfma_f32_16x16x32_bf16 v[56:59], v[164:167], v[188:191], v[56:59]
	v_mfma_f32_16x16x32_bf16 v[52:55], v[172:175], v[188:191], v[52:55]
	v_mfma_f32_16x16x32_bf16 v[40:43], v[164:167], v[192:195], v[40:43]
	v_mfma_f32_16x16x32_bf16 v[36:39], v[172:175], v[192:195], v[36:39]
	v_mfma_f32_16x16x32_bf16 v[22:25], v[164:167], v[204:207], v[22:25]
	v_mfma_f32_16x16x32_bf16 v[18:21], v[172:175], v[204:207], v[18:21]
	v_mfma_f32_16x16x32_bf16 v[6:9], v[164:167], v[208:211], v[6:9]
	v_mfma_f32_16x16x32_bf16 v[2:5], v[172:175], v[208:211], v[2:5]
	s_barrier
	s_add_i32 s31, 0, 0x18000
	ds_read_b128 v[144:147], v1 offset:32768
	ds_read_b128 v[148:151], v141 offset:32768
	s_add_i32 s47, 0, 0x1c000
	ds_read_b128 v[152:155], v1 offset:34816
	ds_read_b128 v[156:159], v141 offset:34816
	ds_read_b128 v[160:163], v1 offset:49152
	ds_read_b128 v[164:167], v141 offset:49152
	ds_read_b128 v[168:171], v1 offset:51200
	ds_read_b128 v[172:175], v141 offset:51200
	s_mov_b64 s[100:101], s[48:49]
	s_add_u32 s48, s48, 0x80000
	s_addc_u32 s49, s49, 0
	s_mov_b32 m0, s54
	ds_read_b128 v[176:179], v142 offset:32768
	ds_read_b128 v[184:187], v142 offset:34816
	ds_read_b128 v[188:191], v143 offset:32768
	ds_read_b128 v[192:195], v143 offset:34816
	ds_read_b128 v[196:199], v142 offset:36864
	ds_read_b128 v[200:203], v142 offset:38912
	ds_read_b128 v[204:207], v143 offset:36864
	global_load_lds_dwordx4 v138, s[48:49]
	s_mov_b32 m0, s55
	ds_read_b128 v[208:211], v143 offset:38912
	global_load_lds_dwordx4 v134, s[48:49]
	s_waitcnt vmcnt(8)
	s_waitcnt lgkmcnt(0)
	s_barrier
	v_mfma_f32_16x16x32_bf16 v[128:131], v[144:147], v[176:179], v[128:131]
	v_mfma_f32_16x16x32_bf16 v[124:127], v[152:155], v[176:179], v[124:127]
	v_mfma_f32_16x16x32_bf16 v[112:115], v[144:147], v[184:187], v[112:115]
	v_mfma_f32_16x16x32_bf16 v[108:111], v[152:155], v[184:187], v[108:111]
	v_mfma_f32_16x16x32_bf16 v[96:99], v[144:147], v[196:199], v[96:99]
	v_mfma_f32_16x16x32_bf16 v[92:95], v[152:155], v[196:199], v[92:95]
	v_mfma_f32_16x16x32_bf16 v[80:83], v[144:147], v[200:203], v[80:83]
	v_mfma_f32_16x16x32_bf16 v[76:79], v[152:155], v[200:203], v[76:79]
	v_mfma_f32_16x16x32_bf16 v[128:131], v[148:151], v[188:191], v[128:131]
	v_mfma_f32_16x16x32_bf16 v[124:127], v[156:159], v[188:191], v[124:127]
	v_mfma_f32_16x16x32_bf16 v[112:115], v[148:151], v[192:195], v[112:115]
	v_mfma_f32_16x16x32_bf16 v[108:111], v[156:159], v[192:195], v[108:111]
	v_mfma_f32_16x16x32_bf16 v[96:99], v[148:151], v[204:207], v[96:99]
	v_mfma_f32_16x16x32_bf16 v[92:95], v[156:159], v[204:207], v[92:95]
	v_mfma_f32_16x16x32_bf16 v[80:83], v[148:151], v[208:211], v[80:83]
	v_mfma_f32_16x16x32_bf16 v[76:79], v[156:159], v[208:211], v[76:79]
	v_mfma_f32_16x16x32_bf16 v[120:123], v[160:163], v[176:179], v[120:123]
	v_mfma_f32_16x16x32_bf16 v[116:119], v[168:171], v[176:179], v[116:119]
	v_mfma_f32_16x16x32_bf16 v[104:107], v[160:163], v[184:187], v[104:107]
	v_mfma_f32_16x16x32_bf16 v[100:103], v[168:171], v[184:187], v[100:103]
	v_mfma_f32_16x16x32_bf16 v[88:91], v[160:163], v[196:199], v[88:91]
	v_mfma_f32_16x16x32_bf16 v[84:87], v[168:171], v[196:199], v[84:87]
	v_mfma_f32_16x16x32_bf16 v[72:75], v[160:163], v[200:203], v[72:75]
	v_mfma_f32_16x16x32_bf16 v[68:71], v[168:171], v[200:203], v[68:71]
	v_mfma_f32_16x16x32_bf16 v[120:123], v[164:167], v[188:191], v[120:123]
	v_mfma_f32_16x16x32_bf16 v[116:119], v[172:175], v[188:191], v[116:119]
	v_mfma_f32_16x16x32_bf16 v[104:107], v[164:167], v[192:195], v[104:107]
	v_mfma_f32_16x16x32_bf16 v[100:103], v[172:175], v[192:195], v[100:103]
	v_mfma_f32_16x16x32_bf16 v[88:91], v[164:167], v[204:207], v[88:91]
	v_mfma_f32_16x16x32_bf16 v[84:87], v[172:175], v[204:207], v[84:87]
	v_mfma_f32_16x16x32_bf16 v[72:75], v[164:167], v[208:211], v[72:75]
	v_mfma_f32_16x16x32_bf16 v[68:71], v[172:175], v[208:211], v[68:71]
	s_barrier
	s_add_i32 s31, s31, s33
	s_add_i32 m0, s31, 0xffffff80
	ds_read_b128 v[176:179], v142 offset:49152
	ds_read_b128 v[184:187], v142 offset:51200
	ds_read_b128 v[188:191], v143 offset:49152
	ds_read_b128 v[192:195], v143 offset:51200
	global_load_lds_dwordx4 v136, s[44:45] offset:128
	s_add_i32 m0, s31, 0x1f80
	s_mov_b64 s[98:99], s[44:45]
	s_add_u32 s44, s44, 0x80080
	s_addc_u32 s45, s45, 0
	s_add_i32 s31, s47, s33
	global_load_lds_dwordx4 v132, s[98:99] offset:128
	s_mov_b32 m0, s31
	ds_read_b128 v[196:199], v142 offset:53248
	global_load_lds_dwordx4 v136, s[44:45]
	s_add_i32 m0, s31, 0x2000
	ds_read_b128 v[200:203], v142 offset:55296
	global_load_lds_dwordx4 v132, s[44:45]
	s_add_i32 m0, s56, 0xffffff80
	ds_read_b128 v[204:207], v143 offset:53248
	global_load_lds_dwordx4 v138, s[100:101] offset:128
	s_add_i32 m0, s57, 0xffffff80
	ds_read_b128 v[208:211], v143 offset:55296
	global_load_lds_dwordx4 v134, s[100:101] offset:128
	s_waitcnt vmcnt(8)
	s_waitcnt lgkmcnt(0)
	s_barrier
	v_mfma_f32_16x16x32_bf16 v[64:67], v[144:147], v[176:179], v[64:67]
	v_mfma_f32_16x16x32_bf16 v[60:63], v[152:155], v[176:179], v[60:63]
	v_mfma_f32_16x16x32_bf16 v[48:51], v[144:147], v[184:187], v[48:51]
	v_mfma_f32_16x16x32_bf16 v[44:47], v[152:155], v[184:187], v[44:47]
	v_mfma_f32_16x16x32_bf16 v[30:33], v[144:147], v[196:199], v[30:33]
	v_mfma_f32_16x16x32_bf16 v[26:29], v[152:155], v[196:199], v[26:29]
	v_mfma_f32_16x16x32_bf16 v[14:17], v[144:147], v[200:203], v[14:17]
	v_mfma_f32_16x16x32_bf16 v[10:13], v[152:155], v[200:203], v[10:13]
	v_mfma_f32_16x16x32_bf16 v[64:67], v[148:151], v[188:191], v[64:67]
	v_mfma_f32_16x16x32_bf16 v[60:63], v[156:159], v[188:191], v[60:63]
	v_mfma_f32_16x16x32_bf16 v[48:51], v[148:151], v[192:195], v[48:51]
	v_mfma_f32_16x16x32_bf16 v[44:47], v[156:159], v[192:195], v[44:47]
	v_mfma_f32_16x16x32_bf16 v[30:33], v[148:151], v[204:207], v[30:33]
	v_mfma_f32_16x16x32_bf16 v[26:29], v[156:159], v[204:207], v[26:29]
	v_mfma_f32_16x16x32_bf16 v[14:17], v[148:151], v[208:211], v[14:17]
	v_mfma_f32_16x16x32_bf16 v[10:13], v[156:159], v[208:211], v[10:13]
	v_mfma_f32_16x16x32_bf16 v[56:59], v[160:163], v[176:179], v[56:59]
	v_mfma_f32_16x16x32_bf16 v[52:55], v[168:171], v[176:179], v[52:55]
	v_mfma_f32_16x16x32_bf16 v[40:43], v[160:163], v[184:187], v[40:43]
	v_mfma_f32_16x16x32_bf16 v[36:39], v[168:171], v[184:187], v[36:39]
	v_mfma_f32_16x16x32_bf16 v[22:25], v[160:163], v[196:199], v[22:25]
	v_mfma_f32_16x16x32_bf16 v[18:21], v[168:171], v[196:199], v[18:21]
	v_mfma_f32_16x16x32_bf16 v[6:9], v[160:163], v[200:203], v[6:9]
	v_mfma_f32_16x16x32_bf16 v[2:5], v[168:171], v[200:203], v[2:5]
	v_mfma_f32_16x16x32_bf16 v[56:59], v[164:167], v[188:191], v[56:59]
	v_mfma_f32_16x16x32_bf16 v[52:55], v[172:175], v[188:191], v[52:55]
	v_mfma_f32_16x16x32_bf16 v[40:43], v[164:167], v[192:195], v[40:43]
	v_mfma_f32_16x16x32_bf16 v[36:39], v[172:175], v[192:195], v[36:39]
	v_mfma_f32_16x16x32_bf16 v[22:25], v[164:167], v[204:207], v[22:25]
	v_mfma_f32_16x16x32_bf16 v[18:21], v[172:175], v[204:207], v[18:21]
	v_mfma_f32_16x16x32_bf16 v[6:9], v[164:167], v[208:211], v[6:9]
	v_mfma_f32_16x16x32_bf16 v[2:5], v[172:175], v[208:211], v[2:5]
	s_barrier
	s_add_i32 s30, s30, 2
	s_add_u32 s42, s42, 0x100
	s_addc_u32 s43, s43, 0
	s_add_u32 s23, s23, 0x100
	s_addc_u32 s25, s25, 0
	s_cmp_gt_u32 s30, 29
	s_cbranch_scc0 .LBB0_162

.LBB0_907:
	s_and_b32 s9, 1, s12
	s_cmp_gt_i32 s12, 1
	s_cselect_b32 s24, 10, 12
	s_cmp_eq_u32 s9, 1
	s_cselect_b64 s[18:19], -1, 0
	s_and_b64 s[20:21], s[18:19], exec
	s_cselect_b32 s9, s24, 32
	s_add_i32 s20, s9, -2
	s_add_u32 s22, s22, 0x80080
	s_addc_u32 s23, s23, 0
	s_add_u32 s21, s28, 0x100
	s_addc_u32 s24, s29, 0
	s_mov_b32 s25, 0
	s_waitcnt vmcnt(0)
	v_readlane_b32 s43, v255, 20
	v_readlane_b32 s45, v255, 21
	v_readlane_b32 s66, v255, 22
	v_readlane_b32 s67, v255, 23
	s_mov_b64 s[68:69], 0x80
	s_add_i32 s30, s25, 2
	s_add_u32 s28, s22, 0xfff80080
	s_addc_u32 s29, s23, -1
	s_add_i32 s31, 0, 0x10000
	s_cmp_eq_u32 s20, s25
	s_cselect_b32 s41, s47, s29
	s_cselect_b32 s40, s46, s28
	s_cselect_b32 s29, s49, s24
	s_cselect_b32 s28, s48, s21
	s_add_i32 s25, 0, 0x14000
	ds_read_b128 v[132:135], v1
	ds_read_b128 v[136:139], v204
	ds_read_b128 v[140:143], v1 offset:2048
	ds_read_b128 v[144:147], v204 offset:2048
	ds_read_b128 v[148:151], v1 offset:16384
	ds_read_b128 v[152:155], v204 offset:16384
	ds_read_b128 v[156:159], v1 offset:18432
	ds_read_b128 v[160:163], v204 offset:18432
	s_add_i32 m0, s50, 0xc000
	ds_read_b128 v[164:167], v205
	ds_read_b128 v[168:171], v205 offset:2048
	ds_read_b128 v[172:175], v206
	ds_read_b128 v[176:179], v206 offset:2048
	ds_read_b128 v[190:193], v205 offset:4096
	ds_read_b128 v[194:197], v205 offset:6144
	ds_read_b128 v[198:201], v206 offset:4096
	global_load_lds_dwordx4 v188, s[22:23]
	s_add_i32 m0, s50, 0xe000
	ds_read_b128 v[232:235], v206 offset:6144
	global_load_lds_dwordx4 v186, s[22:23]
	s_waitcnt vmcnt(8)
	s_waitcnt lgkmcnt(0)
	s_barrier
	v_mfma_f32_16x16x32_bf16 v[68:71], v[132:135], v[164:167], 0
	v_mfma_f32_16x16x32_bf16 v[72:75], v[140:143], v[164:167], 0
	v_mfma_f32_16x16x32_bf16 v[84:87], v[132:135], v[168:171], 0
	v_mfma_f32_16x16x32_bf16 v[88:91], v[140:143], v[168:171], 0
	v_mfma_f32_16x16x32_bf16 v[100:103], v[132:135], v[190:193], 0
	v_mfma_f32_16x16x32_bf16 v[104:107], v[140:143], v[190:193], 0
	v_mfma_f32_16x16x32_bf16 v[116:119], v[132:135], v[194:197], 0
	v_mfma_f32_16x16x32_bf16 v[120:123], v[140:143], v[194:197], 0
	v_mfma_f32_16x16x32_bf16 v[68:71], v[136:139], v[172:175], v[68:71]
	v_mfma_f32_16x16x32_bf16 v[72:75], v[144:147], v[172:175], v[72:75]
	v_mfma_f32_16x16x32_bf16 v[84:87], v[136:139], v[176:179], v[84:87]
	v_mfma_f32_16x16x32_bf16 v[88:91], v[144:147], v[176:179], v[88:91]
	v_mfma_f32_16x16x32_bf16 v[100:103], v[136:139], v[198:201], v[100:103]
	v_mfma_f32_16x16x32_bf16 v[104:107], v[144:147], v[198:201], v[104:107]
	v_mfma_f32_16x16x32_bf16 v[116:119], v[136:139], v[232:235], v[116:119]
	v_mfma_f32_16x16x32_bf16 v[120:123], v[144:147], v[232:235], v[120:123]
	v_mfma_f32_16x16x32_bf16 v[76:79], v[148:151], v[164:167], 0
	v_mfma_f32_16x16x32_bf16 v[80:83], v[156:159], v[164:167], 0
	v_mfma_f32_16x16x32_bf16 v[92:95], v[148:151], v[168:171], 0
	v_mfma_f32_16x16x32_bf16 v[96:99], v[156:159], v[168:171], 0
	v_mfma_f32_16x16x32_bf16 v[108:111], v[148:151], v[190:193], 0
	v_mfma_f32_16x16x32_bf16 v[112:115], v[156:159], v[190:193], 0
	v_mfma_f32_16x16x32_bf16 v[124:127], v[148:151], v[194:197], 0
	v_mfma_f32_16x16x32_bf16 v[128:131], v[156:159], v[194:197], 0
	v_mfma_f32_16x16x32_bf16 v[76:79], v[152:155], v[172:175], v[76:79]
	v_mfma_f32_16x16x32_bf16 v[80:83], v[160:163], v[172:175], v[80:83]
	v_mfma_f32_16x16x32_bf16 v[92:95], v[152:155], v[176:179], v[92:95]
	v_mfma_f32_16x16x32_bf16 v[96:99], v[160:163], v[176:179], v[96:99]
	v_mfma_f32_16x16x32_bf16 v[108:111], v[152:155], v[198:201], v[108:111]
	v_mfma_f32_16x16x32_bf16 v[112:115], v[160:163], v[198:201], v[112:115]
	v_mfma_f32_16x16x32_bf16 v[124:127], v[152:155], v[232:235], v[124:127]
	v_mfma_f32_16x16x32_bf16 v[128:131], v[160:163], v[232:235], v[128:131]
	s_barrier
	s_add_i32 s31, s31, s33
	s_mov_b32 m0, s31
	ds_read_b128 v[164:167], v205 offset:16384
	ds_read_b128 v[168:171], v205 offset:18432
	ds_read_b128 v[172:175], v206 offset:16384
	ds_read_b128 v[176:179], v206 offset:18432
	global_load_lds_dwordx4 v34, s[28:29]
	s_add_i32 m0, s31, 0x2000
	s_add_u32 s34, s28, 0x80000
	s_addc_u32 s35, s29, 0
	s_add_i32 s25, s25, s33
	global_load_lds_dwordx4 v184, s[28:29]
	s_mov_b32 m0, s25
	ds_read_b128 v[190:193], v205 offset:20480
	global_load_lds_dwordx4 v34, s[34:35]
	s_add_i32 m0, s25, 0x2000
	ds_read_b128 v[194:197], v205 offset:22528
	global_load_lds_dwordx4 v184, s[34:35]
	s_mov_b32 m0, s50
	ds_read_b128 v[198:201], v206 offset:20480
	global_load_lds_dwordx4 v188, s[40:41]
	s_mov_b32 m0, s51
	ds_read_b128 v[232:235], v206 offset:22528
	global_load_lds_dwordx4 v186, s[40:41]
	s_waitcnt vmcnt(8)
	s_waitcnt lgkmcnt(0)
	s_barrier
	v_mfma_f32_16x16x32_bf16 v[2:5], v[132:135], v[164:167], 0
	v_mfma_f32_16x16x32_bf16 v[6:9], v[140:143], v[164:167], 0
	v_mfma_f32_16x16x32_bf16 v[18:21], v[132:135], v[168:171], 0
	v_mfma_f32_16x16x32_bf16 v[22:25], v[140:143], v[168:171], 0
	v_mfma_f32_16x16x32_bf16 v[36:39], v[132:135], v[190:193], 0
	v_mfma_f32_16x16x32_bf16 v[40:43], v[140:143], v[190:193], 0
	v_mfma_f32_16x16x32_bf16 v[52:55], v[132:135], v[194:197], 0
	v_mfma_f32_16x16x32_bf16 v[56:59], v[140:143], v[194:197], 0
	v_mfma_f32_16x16x32_bf16 v[2:5], v[136:139], v[172:175], v[2:5]
	v_mfma_f32_16x16x32_bf16 v[6:9], v[144:147], v[172:175], v[6:9]
	v_mfma_f32_16x16x32_bf16 v[18:21], v[136:139], v[176:179], v[18:21]
	v_mfma_f32_16x16x32_bf16 v[22:25], v[144:147], v[176:179], v[22:25]
	v_mfma_f32_16x16x32_bf16 v[36:39], v[136:139], v[198:201], v[36:39]
	v_mfma_f32_16x16x32_bf16 v[40:43], v[144:147], v[198:201], v[40:43]
	v_mfma_f32_16x16x32_bf16 v[52:55], v[136:139], v[232:235], v[52:55]
	v_mfma_f32_16x16x32_bf16 v[56:59], v[144:147], v[232:235], v[56:59]
	v_mfma_f32_16x16x32_bf16 v[10:13], v[148:151], v[164:167], 0
	v_mfma_f32_16x16x32_bf16 v[14:17], v[156:159], v[164:167], 0
	v_mfma_f32_16x16x32_bf16 v[26:29], v[148:151], v[168:171], 0
	v_mfma_f32_16x16x32_bf16 v[30:33], v[156:159], v[168:171], 0
	v_mfma_f32_16x16x32_bf16 v[44:47], v[148:151], v[190:193], 0
	v_mfma_f32_16x16x32_bf16 v[48:51], v[156:159], v[190:193], 0
	v_mfma_f32_16x16x32_bf16 v[60:63], v[148:151], v[194:197], 0
	v_mfma_f32_16x16x32_bf16 v[64:67], v[156:159], v[194:197], 0
	v_mfma_f32_16x16x32_bf16 v[10:13], v[152:155], v[172:175], v[10:13]
	v_mfma_f32_16x16x32_bf16 v[14:17], v[160:163], v[172:175], v[14:17]
	v_mfma_f32_16x16x32_bf16 v[26:29], v[152:155], v[176:179], v[26:29]
	v_mfma_f32_16x16x32_bf16 v[30:33], v[160:163], v[176:179], v[30:33]
	v_mfma_f32_16x16x32_bf16 v[44:47], v[152:155], v[198:201], v[44:47]
	v_mfma_f32_16x16x32_bf16 v[48:51], v[160:163], v[198:201], v[48:51]
	v_mfma_f32_16x16x32_bf16 v[60:63], v[152:155], v[232:235], v[60:63]
	v_mfma_f32_16x16x32_bf16 v[64:67], v[160:163], v[232:235], v[64:67]
	s_barrier
	s_add_i32 s25, 0, 0x18000
	s_add_i32 s31, 0, 0x1c000
	ds_read_b128 v[132:135], v1 offset:32768
	ds_read_b128 v[136:139], v204 offset:32768
	ds_read_b128 v[140:143], v1 offset:34816
	ds_read_b128 v[144:147], v204 offset:34816
	ds_read_b128 v[148:151], v1 offset:49152
	ds_read_b128 v[152:155], v204 offset:49152
	ds_read_b128 v[156:159], v1 offset:51200
	ds_read_b128 v[160:163], v204 offset:51200
	s_add_u32 s34, s40, 0x80000
	s_addc_u32 s35, s41, 0
	s_mov_b32 m0, s52
	ds_read_b128 v[164:167], v205 offset:32768
	ds_read_b128 v[168:171], v205 offset:34816
	ds_read_b128 v[172:175], v206 offset:32768
	ds_read_b128 v[176:179], v206 offset:34816
	ds_read_b128 v[190:193], v205 offset:36864
	ds_read_b128 v[194:197], v205 offset:38912
	ds_read_b128 v[198:201], v206 offset:36864
	global_load_lds_dwordx4 v188, s[34:35]
	s_mov_b32 m0, s53
	ds_read_b128 v[232:235], v206 offset:38912
	global_load_lds_dwordx4 v186, s[34:35]
	s_waitcnt vmcnt(8)
	s_waitcnt lgkmcnt(0)
	s_barrier
	v_mfma_f32_16x16x32_bf16 v[68:71], v[132:135], v[164:167], v[68:71]
	v_mfma_f32_16x16x32_bf16 v[72:75], v[140:143], v[164:167], v[72:75]
	v_mfma_f32_16x16x32_bf16 v[84:87], v[132:135], v[168:171], v[84:87]
	v_mfma_f32_16x16x32_bf16 v[88:91], v[140:143], v[168:171], v[88:91]
	v_mfma_f32_16x16x32_bf16 v[100:103], v[132:135], v[190:193], v[100:103]
	v_mfma_f32_16x16x32_bf16 v[104:107], v[140:143], v[190:193], v[104:107]
	v_mfma_f32_16x16x32_bf16 v[116:119], v[132:135], v[194:197], v[116:119]
	v_mfma_f32_16x16x32_bf16 v[120:123], v[140:143], v[194:197], v[120:123]
	v_mfma_f32_16x16x32_bf16 v[68:71], v[136:139], v[172:175], v[68:71]
	v_mfma_f32_16x16x32_bf16 v[72:75], v[144:147], v[172:175], v[72:75]
	v_mfma_f32_16x16x32_bf16 v[84:87], v[136:139], v[176:179], v[84:87]
	v_mfma_f32_16x16x32_bf16 v[88:91], v[144:147], v[176:179], v[88:91]
	v_mfma_f32_16x16x32_bf16 v[100:103], v[136:139], v[198:201], v[100:103]
	v_mfma_f32_16x16x32_bf16 v[104:107], v[144:147], v[198:201], v[104:107]
	v_mfma_f32_16x16x32_bf16 v[116:119], v[136:139], v[232:235], v[116:119]
	v_mfma_f32_16x16x32_bf16 v[120:123], v[144:147], v[232:235], v[120:123]
	v_mfma_f32_16x16x32_bf16 v[76:79], v[148:151], v[164:167], v[76:79]
	v_mfma_f32_16x16x32_bf16 v[80:83], v[156:159], v[164:167], v[80:83]
	v_mfma_f32_16x16x32_bf16 v[92:95], v[148:151], v[168:171], v[92:95]
	v_mfma_f32_16x16x32_bf16 v[96:99], v[156:159], v[168:171], v[96:99]
	v_mfma_f32_16x16x32_bf16 v[108:111], v[148:151], v[190:193], v[108:111]
	v_mfma_f32_16x16x32_bf16 v[112:115], v[156:159], v[190:193], v[112:115]
	v_mfma_f32_16x16x32_bf16 v[124:127], v[148:151], v[194:197], v[124:127]
	v_mfma_f32_16x16x32_bf16 v[128:131], v[156:159], v[194:197], v[128:131]
	v_mfma_f32_16x16x32_bf16 v[76:79], v[152:155], v[172:175], v[76:79]
	v_mfma_f32_16x16x32_bf16 v[80:83], v[160:163], v[172:175], v[80:83]
	v_mfma_f32_16x16x32_bf16 v[92:95], v[152:155], v[176:179], v[92:95]
	v_mfma_f32_16x16x32_bf16 v[96:99], v[160:163], v[176:179], v[96:99]
	v_mfma_f32_16x16x32_bf16 v[108:111], v[152:155], v[198:201], v[108:111]
	v_mfma_f32_16x16x32_bf16 v[112:115], v[160:163], v[198:201], v[112:115]
	v_mfma_f32_16x16x32_bf16 v[124:127], v[152:155], v[232:235], v[124:127]
	v_mfma_f32_16x16x32_bf16 v[128:131], v[160:163], v[232:235], v[128:131]
	s_barrier
	s_add_i32 s25, s25, s33
	s_add_i32 m0, s25, 0xffffff80
	ds_read_b128 v[164:167], v205 offset:49152
	ds_read_b128 v[168:171], v205 offset:51200
	ds_read_b128 v[172:175], v206 offset:49152
	ds_read_b128 v[176:179], v206 offset:51200
	global_load_lds_dwordx4 v34, s[28:29] offset:128
	s_add_i32 m0, s25, 0x1f80
	s_mov_b64 s[98:99], s[28:29]
	s_add_u32 s28, s28, 0x80080
	s_addc_u32 s29, s29, 0
	s_add_i32 s25, s31, s33
	global_load_lds_dwordx4 v184, s[98:99] offset:128
	s_mov_b32 m0, s25
	ds_read_b128 v[190:193], v205 offset:53248
	global_load_lds_dwordx4 v34, s[28:29]
	s_add_i32 m0, s25, 0x2000
	ds_read_b128 v[194:197], v205 offset:55296
	global_load_lds_dwordx4 v184, s[28:29]
	s_add_i32 m0, s54, 0xffffff80
	ds_read_b128 v[198:201], v206 offset:53248
	global_load_lds_dwordx4 v188, s[40:41] offset:128
	s_add_i32 m0, s55, 0xffffff80
	ds_read_b128 v[232:235], v206 offset:55296
	global_load_lds_dwordx4 v186, s[40:41] offset:128
	s_waitcnt vmcnt(8)
	s_waitcnt lgkmcnt(0)
	s_barrier
	v_mfma_f32_16x16x32_bf16 v[2:5], v[132:135], v[164:167], v[2:5]
	v_mfma_f32_16x16x32_bf16 v[6:9], v[140:143], v[164:167], v[6:9]
	v_mfma_f32_16x16x32_bf16 v[18:21], v[132:135], v[168:171], v[18:21]
	v_mfma_f32_16x16x32_bf16 v[22:25], v[140:143], v[168:171], v[22:25]
	v_mfma_f32_16x16x32_bf16 v[36:39], v[132:135], v[190:193], v[36:39]
	v_mfma_f32_16x16x32_bf16 v[40:43], v[140:143], v[190:193], v[40:43]
	v_mfma_f32_16x16x32_bf16 v[52:55], v[132:135], v[194:197], v[52:55]
	v_mfma_f32_16x16x32_bf16 v[56:59], v[140:143], v[194:197], v[56:59]
	v_mfma_f32_16x16x32_bf16 v[2:5], v[136:139], v[172:175], v[2:5]
	v_mfma_f32_16x16x32_bf16 v[6:9], v[144:147], v[172:175], v[6:9]
	v_mfma_f32_16x16x32_bf16 v[18:21], v[136:139], v[176:179], v[18:21]
	v_mfma_f32_16x16x32_bf16 v[22:25], v[144:147], v[176:179], v[22:25]
	v_mfma_f32_16x16x32_bf16 v[36:39], v[136:139], v[198:201], v[36:39]
	v_mfma_f32_16x16x32_bf16 v[40:43], v[144:147], v[198:201], v[40:43]
	v_mfma_f32_16x16x32_bf16 v[52:55], v[136:139], v[232:235], v[52:55]
	v_mfma_f32_16x16x32_bf16 v[56:59], v[144:147], v[232:235], v[56:59]
	v_mfma_f32_16x16x32_bf16 v[10:13], v[148:151], v[164:167], v[10:13]
	v_mfma_f32_16x16x32_bf16 v[14:17], v[156:159], v[164:167], v[14:17]
	v_mfma_f32_16x16x32_bf16 v[26:29], v[148:151], v[168:171], v[26:29]
	v_mfma_f32_16x16x32_bf16 v[30:33], v[156:159], v[168:171], v[30:33]
	v_mfma_f32_16x16x32_bf16 v[44:47], v[148:151], v[190:193], v[44:47]
	v_mfma_f32_16x16x32_bf16 v[48:51], v[156:159], v[190:193], v[48:51]
	v_mfma_f32_16x16x32_bf16 v[60:63], v[148:151], v[194:197], v[60:63]
	v_mfma_f32_16x16x32_bf16 v[64:67], v[156:159], v[194:197], v[64:67]
	v_mfma_f32_16x16x32_bf16 v[10:13], v[152:155], v[172:175], v[10:13]
	v_mfma_f32_16x16x32_bf16 v[14:17], v[160:163], v[172:175], v[14:17]
	v_mfma_f32_16x16x32_bf16 v[26:29], v[152:155], v[176:179], v[26:29]
	v_mfma_f32_16x16x32_bf16 v[30:33], v[160:163], v[176:179], v[30:33]
	v_mfma_f32_16x16x32_bf16 v[44:47], v[152:155], v[198:201], v[44:47]
	v_mfma_f32_16x16x32_bf16 v[48:51], v[160:163], v[198:201], v[48:51]
	v_mfma_f32_16x16x32_bf16 v[60:63], v[152:155], v[232:235], v[60:63]
	v_mfma_f32_16x16x32_bf16 v[64:67], v[160:163], v[232:235], v[64:67]
	s_barrier
	s_add_u32 s22, s22, 0x100
	s_addc_u32 s23, s23, 0
	s_add_u32 s21, s21, 0x100
	s_addc_u32 s24, s24, 0
	s_cmp_ge_u32 s30, s9
	s_mov_b32 s25, s30
	s_cbranch_scc1 .Lpeel_done_P3
.LBB0_908:
	s_add_i32 s30, s25, 2
	s_add_u32 s28, s22, 0xfff80080
	s_addc_u32 s29, s23, -1
	s_add_i32 s31, 0, 0x10000
	s_cmp_eq_u32 s20, s25
	s_cselect_b32 s41, s47, s29
	s_cselect_b32 s40, s46, s28
	s_cselect_b32 s29, s49, s24
	s_cselect_b32 s28, s48, s21
	s_add_i32 s25, 0, 0x14000
	ds_read_b128 v[132:135], v1
	ds_read_b128 v[136:139], v204
	ds_read_b128 v[140:143], v1 offset:2048
	ds_read_b128 v[144:147], v204 offset:2048
	ds_read_b128 v[148:151], v1 offset:16384
	ds_read_b128 v[152:155], v204 offset:16384
	ds_read_b128 v[156:159], v1 offset:18432
	ds_read_b128 v[160:163], v204 offset:18432
	s_add_i32 m0, s50, 0xc000
	ds_read_b128 v[164:167], v205
	ds_read_b128 v[168:171], v205 offset:2048
	ds_read_b128 v[172:175], v206
	ds_read_b128 v[176:179], v206 offset:2048
	ds_read_b128 v[190:193], v205 offset:4096
	ds_read_b128 v[194:197], v205 offset:6144
	ds_read_b128 v[198:201], v206 offset:4096
	global_load_lds_dwordx4 v188, s[22:23]
	s_add_i32 m0, s50, 0xe000
	ds_read_b128 v[232:235], v206 offset:6144
	global_load_lds_dwordx4 v186, s[22:23]
	s_waitcnt vmcnt(8)
	s_waitcnt lgkmcnt(0)
	s_barrier
	v_mfma_f32_16x16x32_bf16 v[68:71], v[132:135], v[164:167], v[68:71]
	v_mfma_f32_16x16x32_bf16 v[72:75], v[140:143], v[164:167], v[72:75]
	v_mfma_f32_16x16x32_bf16 v[84:87], v[132:135], v[168:171], v[84:87]
	v_mfma_f32_16x16x32_bf16 v[88:91], v[140:143], v[168:171], v[88:91]
	v_mfma_f32_16x16x32_bf16 v[100:103], v[132:135], v[190:193], v[100:103]
	v_mfma_f32_16x16x32_bf16 v[104:107], v[140:143], v[190:193], v[104:107]
	v_mfma_f32_16x16x32_bf16 v[116:119], v[132:135], v[194:197], v[116:119]
	v_mfma_f32_16x16x32_bf16 v[120:123], v[140:143], v[194:197], v[120:123]
	v_mfma_f32_16x16x32_bf16 v[68:71], v[136:139], v[172:175], v[68:71]
	v_mfma_f32_16x16x32_bf16 v[72:75], v[144:147], v[172:175], v[72:75]
	v_mfma_f32_16x16x32_bf16 v[84:87], v[136:139], v[176:179], v[84:87]
	v_mfma_f32_16x16x32_bf16 v[88:91], v[144:147], v[176:179], v[88:91]
	v_mfma_f32_16x16x32_bf16 v[100:103], v[136:139], v[198:201], v[100:103]
	v_mfma_f32_16x16x32_bf16 v[104:107], v[144:147], v[198:201], v[104:107]
	v_mfma_f32_16x16x32_bf16 v[116:119], v[136:139], v[232:235], v[116:119]
	v_mfma_f32_16x16x32_bf16 v[120:123], v[144:147], v[232:235], v[120:123]
	v_mfma_f32_16x16x32_bf16 v[76:79], v[148:151], v[164:167], v[76:79]
	v_mfma_f32_16x16x32_bf16 v[80:83], v[156:159], v[164:167], v[80:83]
	v_mfma_f32_16x16x32_bf16 v[92:95], v[148:151], v[168:171], v[92:95]
	v_mfma_f32_16x16x32_bf16 v[96:99], v[156:159], v[168:171], v[96:99]
	v_mfma_f32_16x16x32_bf16 v[108:111], v[148:151], v[190:193], v[108:111]
	v_mfma_f32_16x16x32_bf16 v[112:115], v[156:159], v[190:193], v[112:115]
	v_mfma_f32_16x16x32_bf16 v[124:127], v[148:151], v[194:197], v[124:127]
	v_mfma_f32_16x16x32_bf16 v[128:131], v[156:159], v[194:197], v[128:131]
	v_mfma_f32_16x16x32_bf16 v[76:79], v[152:155], v[172:175], v[76:79]
	v_mfma_f32_16x16x32_bf16 v[80:83], v[160:163], v[172:175], v[80:83]
	v_mfma_f32_16x16x32_bf16 v[92:95], v[152:155], v[176:179], v[92:95]
	v_mfma_f32_16x16x32_bf16 v[96:99], v[160:163], v[176:179], v[96:99]
	v_mfma_f32_16x16x32_bf16 v[108:111], v[152:155], v[198:201], v[108:111]
	v_mfma_f32_16x16x32_bf16 v[112:115], v[160:163], v[198:201], v[112:115]
	v_mfma_f32_16x16x32_bf16 v[124:127], v[152:155], v[232:235], v[124:127]
	v_mfma_f32_16x16x32_bf16 v[128:131], v[160:163], v[232:235], v[128:131]
	s_barrier
	s_add_i32 s31, s31, s33
	s_mov_b32 m0, s31
	ds_read_b128 v[164:167], v205 offset:16384
	ds_read_b128 v[168:171], v205 offset:18432
	ds_read_b128 v[172:175], v206 offset:16384
	ds_read_b128 v[176:179], v206 offset:18432
	global_load_lds_dwordx4 v34, s[28:29]
	s_add_i32 m0, s31, 0x2000
	s_add_u32 s34, s28, 0x80000
	s_addc_u32 s35, s29, 0
	s_add_i32 s25, s25, s33
	global_load_lds_dwordx4 v184, s[28:29]
	s_mov_b32 m0, s25
	ds_read_b128 v[190:193], v205 offset:20480
	global_load_lds_dwordx4 v34, s[34:35]
	s_add_i32 m0, s25, 0x2000
	ds_read_b128 v[194:197], v205 offset:22528
	global_load_lds_dwordx4 v184, s[34:35]
	s_mov_b32 m0, s50
	ds_read_b128 v[198:201], v206 offset:20480
	global_load_lds_dwordx4 v188, s[40:41]
	s_mov_b32 m0, s51
	ds_read_b128 v[232:235], v206 offset:22528
	global_load_lds_dwordx4 v186, s[40:41]
	s_waitcnt vmcnt(8)
	s_waitcnt lgkmcnt(0)
	s_barrier
	v_mfma_f32_16x16x32_bf16 v[2:5], v[132:135], v[164:167], v[2:5]
	v_mfma_f32_16x16x32_bf16 v[6:9], v[140:143], v[164:167], v[6:9]
	v_mfma_f32_16x16x32_bf16 v[18:21], v[132:135], v[168:171], v[18:21]
	v_mfma_f32_16x16x32_bf16 v[22:25], v[140:143], v[168:171], v[22:25]
	v_mfma_f32_16x16x32_bf16 v[36:39], v[132:135], v[190:193], v[36:39]
	v_mfma_f32_16x16x32_bf16 v[40:43], v[140:143], v[190:193], v[40:43]
	v_mfma_f32_16x16x32_bf16 v[52:55], v[132:135], v[194:197], v[52:55]
	v_mfma_f32_16x16x32_bf16 v[56:59], v[140:143], v[194:197], v[56:59]
	v_mfma_f32_16x16x32_bf16 v[2:5], v[136:139], v[172:175], v[2:5]
	v_mfma_f32_16x16x32_bf16 v[6:9], v[144:147], v[172:175], v[6:9]
	v_mfma_f32_16x16x32_bf16 v[18:21], v[136:139], v[176:179], v[18:21]
	v_mfma_f32_16x16x32_bf16 v[22:25], v[144:147], v[176:179], v[22:25]
	v_mfma_f32_16x16x32_bf16 v[36:39], v[136:139], v[198:201], v[36:39]
	v_mfma_f32_16x16x32_bf16 v[40:43], v[144:147], v[198:201], v[40:43]
	v_mfma_f32_16x16x32_bf16 v[52:55], v[136:139], v[232:235], v[52:55]
	v_mfma_f32_16x16x32_bf16 v[56:59], v[144:147], v[232:235], v[56:59]
	v_mfma_f32_16x16x32_bf16 v[10:13], v[148:151], v[164:167], v[10:13]
	v_mfma_f32_16x16x32_bf16 v[14:17], v[156:159], v[164:167], v[14:17]
	v_mfma_f32_16x16x32_bf16 v[26:29], v[148:151], v[168:171], v[26:29]
	v_mfma_f32_16x16x32_bf16 v[30:33], v[156:159], v[168:171], v[30:33]
	v_mfma_f32_16x16x32_bf16 v[44:47], v[148:151], v[190:193], v[44:47]
	v_mfma_f32_16x16x32_bf16 v[48:51], v[156:159], v[190:193], v[48:51]
	v_mfma_f32_16x16x32_bf16 v[60:63], v[148:151], v[194:197], v[60:63]
	v_mfma_f32_16x16x32_bf16 v[64:67], v[156:159], v[194:197], v[64:67]
	v_mfma_f32_16x16x32_bf16 v[10:13], v[152:155], v[172:175], v[10:13]
	v_mfma_f32_16x16x32_bf16 v[14:17], v[160:163], v[172:175], v[14:17]
	v_mfma_f32_16x16x32_bf16 v[26:29], v[152:155], v[176:179], v[26:29]
	v_mfma_f32_16x16x32_bf16 v[30:33], v[160:163], v[176:179], v[30:33]
	v_mfma_f32_16x16x32_bf16 v[44:47], v[152:155], v[198:201], v[44:47]
	v_mfma_f32_16x16x32_bf16 v[48:51], v[160:163], v[198:201], v[48:51]
	v_mfma_f32_16x16x32_bf16 v[60:63], v[152:155], v[232:235], v[60:63]
	v_mfma_f32_16x16x32_bf16 v[64:67], v[160:163], v[232:235], v[64:67]
	s_barrier
	s_add_i32 s25, 0, 0x18000
	s_add_i32 s31, 0, 0x1c000
	ds_read_b128 v[132:135], v1 offset:32768
	ds_read_b128 v[136:139], v204 offset:32768
	ds_read_b128 v[140:143], v1 offset:34816
	ds_read_b128 v[144:147], v204 offset:34816
	ds_read_b128 v[148:151], v1 offset:49152
	ds_read_b128 v[152:155], v204 offset:49152
	ds_read_b128 v[156:159], v1 offset:51200
	ds_read_b128 v[160:163], v204 offset:51200
	s_add_u32 s34, s40, 0x80000
	s_addc_u32 s35, s41, 0
	s_mov_b32 m0, s52
	ds_read_b128 v[164:167], v205 offset:32768
	ds_read_b128 v[168:171], v205 offset:34816
	ds_read_b128 v[172:175], v206 offset:32768
	ds_read_b128 v[176:179], v206 offset:34816
	ds_read_b128 v[190:193], v205 offset:36864
	ds_read_b128 v[194:197], v205 offset:38912
	ds_read_b128 v[198:201], v206 offset:36864
	global_load_lds_dwordx4 v188, s[34:35]
	s_mov_b32 m0, s53
	ds_read_b128 v[232:235], v206 offset:38912
	global_load_lds_dwordx4 v186, s[34:35]
	s_waitcnt vmcnt(8)
	s_waitcnt lgkmcnt(0)
	s_barrier
	v_mfma_f32_16x16x32_bf16 v[68:71], v[132:135], v[164:167], v[68:71]
	v_mfma_f32_16x16x32_bf16 v[72:75], v[140:143], v[164:167], v[72:75]
	v_mfma_f32_16x16x32_bf16 v[84:87], v[132:135], v[168:171], v[84:87]
	v_mfma_f32_16x16x32_bf16 v[88:91], v[140:143], v[168:171], v[88:91]
	v_mfma_f32_16x16x32_bf16 v[100:103], v[132:135], v[190:193], v[100:103]
	v_mfma_f32_16x16x32_bf16 v[104:107], v[140:143], v[190:193], v[104:107]
	v_mfma_f32_16x16x32_bf16 v[116:119], v[132:135], v[194:197], v[116:119]
	v_mfma_f32_16x16x32_bf16 v[120:123], v[140:143], v[194:197], v[120:123]
	v_mfma_f32_16x16x32_bf16 v[68:71], v[136:139], v[172:175], v[68:71]
	v_mfma_f32_16x16x32_bf16 v[72:75], v[144:147], v[172:175], v[72:75]
	v_mfma_f32_16x16x32_bf16 v[84:87], v[136:139], v[176:179], v[84:87]
	v_mfma_f32_16x16x32_bf16 v[88:91], v[144:147], v[176:179], v[88:91]
	v_mfma_f32_16x16x32_bf16 v[100:103], v[136:139], v[198:201], v[100:103]
	v_mfma_f32_16x16x32_bf16 v[104:107], v[144:147], v[198:201], v[104:107]
	v_mfma_f32_16x16x32_bf16 v[116:119], v[136:139], v[232:235], v[116:119]
	v_mfma_f32_16x16x32_bf16 v[120:123], v[144:147], v[232:235], v[120:123]
	v_mfma_f32_16x16x32_bf16 v[76:79], v[148:151], v[164:167], v[76:79]
	v_mfma_f32_16x16x32_bf16 v[80:83], v[156:159], v[164:167], v[80:83]
	v_mfma_f32_16x16x32_bf16 v[92:95], v[148:151], v[168:171], v[92:95]
	v_mfma_f32_16x16x32_bf16 v[96:99], v[156:159], v[168:171], v[96:99]
	v_mfma_f32_16x16x32_bf16 v[108:111], v[148:151], v[190:193], v[108:111]
	v_mfma_f32_16x16x32_bf16 v[112:115], v[156:159], v[190:193], v[112:115]
	v_mfma_f32_16x16x32_bf16 v[124:127], v[148:151], v[194:197], v[124:127]
	v_mfma_f32_16x16x32_bf16 v[128:131], v[156:159], v[194:197], v[128:131]
	v_mfma_f32_16x16x32_bf16 v[76:79], v[152:155], v[172:175], v[76:79]
	v_mfma_f32_16x16x32_bf16 v[80:83], v[160:163], v[172:175], v[80:83]
	v_mfma_f32_16x16x32_bf16 v[92:95], v[152:155], v[176:179], v[92:95]
	v_mfma_f32_16x16x32_bf16 v[96:99], v[160:163], v[176:179], v[96:99]
	v_mfma_f32_16x16x32_bf16 v[108:111], v[152:155], v[198:201], v[108:111]
	v_mfma_f32_16x16x32_bf16 v[112:115], v[160:163], v[198:201], v[112:115]
	v_mfma_f32_16x16x32_bf16 v[124:127], v[152:155], v[232:235], v[124:127]
	v_mfma_f32_16x16x32_bf16 v[128:131], v[160:163], v[232:235], v[128:131]
	s_barrier
	s_add_i32 s25, s25, s33
	s_add_i32 m0, s25, 0xffffff80
	ds_read_b128 v[164:167], v205 offset:49152
	ds_read_b128 v[168:171], v205 offset:51200
	ds_read_b128 v[172:175], v206 offset:49152
	ds_read_b128 v[176:179], v206 offset:51200
	global_load_lds_dwordx4 v34, s[28:29] offset:128
	s_add_i32 m0, s25, 0x1f80
	s_mov_b64 s[98:99], s[28:29]
	s_add_u32 s28, s28, 0x80080
	s_addc_u32 s29, s29, 0
	s_add_i32 s25, s31, s33
	global_load_lds_dwordx4 v184, s[98:99] offset:128
	s_mov_b32 m0, s25
	ds_read_b128 v[190:193], v205 offset:53248
	global_load_lds_dwordx4 v34, s[28:29]
	s_add_i32 m0, s25, 0x2000
	ds_read_b128 v[194:197], v205 offset:55296
	global_load_lds_dwordx4 v184, s[28:29]
	s_add_i32 m0, s54, 0xffffff80
	ds_read_b128 v[198:201], v206 offset:53248
	global_load_lds_dwordx4 v188, s[40:41] offset:128
	s_add_i32 m0, s55, 0xffffff80
	ds_read_b128 v[232:235], v206 offset:55296
	global_load_lds_dwordx4 v186, s[40:41] offset:128
	s_waitcnt vmcnt(8)
	s_waitcnt lgkmcnt(0)
	s_barrier
	v_mfma_f32_16x16x32_bf16 v[2:5], v[132:135], v[164:167], v[2:5]
	v_mfma_f32_16x16x32_bf16 v[6:9], v[140:143], v[164:167], v[6:9]
	v_mfma_f32_16x16x32_bf16 v[18:21], v[132:135], v[168:171], v[18:21]
	v_mfma_f32_16x16x32_bf16 v[22:25], v[140:143], v[168:171], v[22:25]
	v_mfma_f32_16x16x32_bf16 v[36:39], v[132:135], v[190:193], v[36:39]
	v_mfma_f32_16x16x32_bf16 v[40:43], v[140:143], v[190:193], v[40:43]
	v_mfma_f32_16x16x32_bf16 v[52:55], v[132:135], v[194:197], v[52:55]
	v_mfma_f32_16x16x32_bf16 v[56:59], v[140:143], v[194:197], v[56:59]
	v_mfma_f32_16x16x32_bf16 v[2:5], v[136:139], v[172:175], v[2:5]
	v_mfma_f32_16x16x32_bf16 v[6:9], v[144:147], v[172:175], v[6:9]
	v_mfma_f32_16x16x32_bf16 v[18:21], v[136:139], v[176:179], v[18:21]
	v_mfma_f32_16x16x32_bf16 v[22:25], v[144:147], v[176:179], v[22:25]
	v_mfma_f32_16x16x32_bf16 v[36:39], v[136:139], v[198:201], v[36:39]
	v_mfma_f32_16x16x32_bf16 v[40:43], v[144:147], v[198:201], v[40:43]
	v_mfma_f32_16x16x32_bf16 v[52:55], v[136:139], v[232:235], v[52:55]
	v_mfma_f32_16x16x32_bf16 v[56:59], v[144:147], v[232:235], v[56:59]
	v_mfma_f32_16x16x32_bf16 v[10:13], v[148:151], v[164:167], v[10:13]
	v_mfma_f32_16x16x32_bf16 v[14:17], v[156:159], v[164:167], v[14:17]
	v_mfma_f32_16x16x32_bf16 v[26:29], v[148:151], v[168:171], v[26:29]
	v_mfma_f32_16x16x32_bf16 v[30:33], v[156:159], v[168:171], v[30:33]
	v_mfma_f32_16x16x32_bf16 v[44:47], v[148:151], v[190:193], v[44:47]
	v_mfma_f32_16x16x32_bf16 v[48:51], v[156:159], v[190:193], v[48:51]
	v_mfma_f32_16x16x32_bf16 v[60:63], v[148:151], v[194:197], v[60:63]
	v_mfma_f32_16x16x32_bf16 v[64:67], v[156:159], v[194:197], v[64:67]
	v_mfma_f32_16x16x32_bf16 v[10:13], v[152:155], v[172:175], v[10:13]
	v_mfma_f32_16x16x32_bf16 v[14:17], v[160:163], v[172:175], v[14:17]
	v_mfma_f32_16x16x32_bf16 v[26:29], v[152:155], v[176:179], v[26:29]
	v_mfma_f32_16x16x32_bf16 v[30:33], v[160:163], v[176:179], v[30:33]
	v_mfma_f32_16x16x32_bf16 v[44:47], v[152:155], v[198:201], v[44:47]
	v_mfma_f32_16x16x32_bf16 v[48:51], v[160:163], v[198:201], v[48:51]
	v_mfma_f32_16x16x32_bf16 v[60:63], v[152:155], v[232:235], v[60:63]
	v_mfma_f32_16x16x32_bf16 v[64:67], v[160:163], v[232:235], v[64:67]
	s_barrier
	s_add_u32 s22, s22, 0x100
	s_addc_u32 s23, s23, 0
	s_add_u32 s21, s21, 0x100
	s_addc_u32 s24, s24, 0
	s_cmp_ge_u32 s30, s9
	s_mov_b32 s25, s30
	s_cbranch_scc0 .LBB0_908

.LBB0_1022:
	s_ashr_i32 s23, s22, 31
	s_lshl_b64 s[12:13], s[22:23], 20
	v_readlane_b32 s20, v254, 52
	v_readlane_b32 s21, v254, 53
	s_add_u32 s40, s20, s12
	s_addc_u32 s41, s21, s13
	s_and_b64 s[12:13], s[38:39], exec
	s_cselect_b32 s12, s41, s9
	s_cselect_b32 s13, s40, s8
	s_ashr_i32 s19, s18, 31
	s_lshl_b64 s[20:21], s[18:19], 20
	v_readlane_b32 s24, v254, 48
	v_readlane_b32 s25, v254, 49
	s_add_u32 s42, s24, s20
	s_addc_u32 s43, s25, s21
	s_and_b64 s[20:21], s[38:39], exec
	s_cselect_b32 s19, s43, s29
	s_cselect_b32 s20, s42, s28
	s_add_u32 s8, s8, 0x80080
	s_addc_u32 s9, s9, 0
	s_add_u32 s21, s28, 0x100
	s_addc_u32 s23, s29, 0
	s_mov_b32 s24, -2
	v_readlane_b32 s35, v255, 20
	v_readlane_b32 s57, v255, 21
	v_readlane_b32 s58, v255, 22
	v_readlane_b32 s59, v255, 23
	s_mov_b64 s[60:61], 0x80
	s_add_u32 s25, s8, 0xfff80080
	s_addc_u32 s28, s9, -1
	s_add_i32 s30, 0, 0x10000
	s_cmp_eq_u32 s24, 28
	s_cselect_b32 s45, s12, s28
	s_cselect_b32 s44, s13, s25
	s_cselect_b32 s29, s19, s23
	s_cselect_b32 s28, s20, s21
	s_add_i32 s25, 0, 0x14000
	ds_read_b128 v[138:141], v1
	ds_read_b128 v[142:145], v150
	ds_read_b128 v[146:149], v1 offset:2048
	ds_read_b128 v[154:157], v150 offset:2048
	ds_read_b128 v[158:161], v1 offset:16384
	ds_read_b128 v[162:165], v150 offset:16384
	ds_read_b128 v[166:169], v1 offset:18432
	ds_read_b128 v[170:173], v150 offset:18432
	s_add_i32 m0, s46, 0xc000
	ds_read_b128 v[174:177], v151
	ds_read_b128 v[184:187], v151 offset:2048
	ds_read_b128 v[188:191], v152
	ds_read_b128 v[192:195], v152 offset:2048
	ds_read_b128 v[196:199], v151 offset:4096
	ds_read_b128 v[200:203], v151 offset:6144
	ds_read_b128 v[204:207], v152 offset:4096
	global_load_lds_dwordx4 v136, s[8:9]
	s_add_i32 m0, s46, 0xe000
	ds_read_b128 v[208:211], v152 offset:6144
	global_load_lds_dwordx4 v134, s[8:9]
	s_waitcnt vmcnt(8)
	s_waitcnt lgkmcnt(0)
	s_barrier
	v_mfma_f32_16x16x32_bf16 v[128:131], v[138:141], v[174:177], 0
	v_mfma_f32_16x16x32_bf16 v[124:127], v[146:149], v[174:177], 0
	v_mfma_f32_16x16x32_bf16 v[112:115], v[138:141], v[184:187], 0
	v_mfma_f32_16x16x32_bf16 v[108:111], v[146:149], v[184:187], 0
	v_mfma_f32_16x16x32_bf16 v[96:99], v[138:141], v[196:199], 0
	v_mfma_f32_16x16x32_bf16 v[92:95], v[146:149], v[196:199], 0
	v_mfma_f32_16x16x32_bf16 v[80:83], v[138:141], v[200:203], 0
	v_mfma_f32_16x16x32_bf16 v[76:79], v[146:149], v[200:203], 0
	v_mfma_f32_16x16x32_bf16 v[128:131], v[142:145], v[188:191], v[128:131]
	v_mfma_f32_16x16x32_bf16 v[124:127], v[154:157], v[188:191], v[124:127]
	v_mfma_f32_16x16x32_bf16 v[112:115], v[142:145], v[192:195], v[112:115]
	v_mfma_f32_16x16x32_bf16 v[108:111], v[154:157], v[192:195], v[108:111]
	v_mfma_f32_16x16x32_bf16 v[96:99], v[142:145], v[204:207], v[96:99]
	v_mfma_f32_16x16x32_bf16 v[92:95], v[154:157], v[204:207], v[92:95]
	v_mfma_f32_16x16x32_bf16 v[80:83], v[142:145], v[208:211], v[80:83]
	v_mfma_f32_16x16x32_bf16 v[76:79], v[154:157], v[208:211], v[76:79]
	v_mfma_f32_16x16x32_bf16 v[120:123], v[158:161], v[174:177], 0
	v_mfma_f32_16x16x32_bf16 v[116:119], v[166:169], v[174:177], 0
	v_mfma_f32_16x16x32_bf16 v[104:107], v[158:161], v[184:187], 0
	v_mfma_f32_16x16x32_bf16 v[100:103], v[166:169], v[184:187], 0
	v_mfma_f32_16x16x32_bf16 v[88:91], v[158:161], v[196:199], 0
	v_mfma_f32_16x16x32_bf16 v[84:87], v[166:169], v[196:199], 0
	v_mfma_f32_16x16x32_bf16 v[72:75], v[158:161], v[200:203], 0
	v_mfma_f32_16x16x32_bf16 v[68:71], v[166:169], v[200:203], 0
	v_mfma_f32_16x16x32_bf16 v[120:123], v[162:165], v[188:191], v[120:123]
	v_mfma_f32_16x16x32_bf16 v[116:119], v[170:173], v[188:191], v[116:119]
	v_mfma_f32_16x16x32_bf16 v[104:107], v[162:165], v[192:195], v[104:107]
	v_mfma_f32_16x16x32_bf16 v[100:103], v[170:173], v[192:195], v[100:103]
	v_mfma_f32_16x16x32_bf16 v[88:91], v[162:165], v[204:207], v[88:91]
	v_mfma_f32_16x16x32_bf16 v[84:87], v[170:173], v[204:207], v[84:87]
	v_mfma_f32_16x16x32_bf16 v[72:75], v[162:165], v[208:211], v[72:75]
	v_mfma_f32_16x16x32_bf16 v[68:71], v[170:173], v[208:211], v[68:71]
	s_barrier
	s_add_i32 s30, s30, s33
	s_mov_b32 m0, s30
	ds_read_b128 v[174:177], v151 offset:16384
	ds_read_b128 v[184:187], v151 offset:18432
	ds_read_b128 v[188:191], v152 offset:16384
	ds_read_b128 v[192:195], v152 offset:18432
	global_load_lds_dwordx4 v34, s[28:29]
	s_add_i32 m0, s30, 0x2000
	s_add_u32 s30, s28, 0x80000
	s_addc_u32 s31, s29, 0
	s_add_i32 s25, s25, s33
	global_load_lds_dwordx4 v132, s[28:29]
	s_mov_b32 m0, s25
	ds_read_b128 v[196:199], v151 offset:20480
	global_load_lds_dwordx4 v34, s[30:31]
	s_add_i32 m0, s25, 0x2000
	ds_read_b128 v[200:203], v151 offset:22528
	global_load_lds_dwordx4 v132, s[30:31]
	s_mov_b32 m0, s46
	ds_read_b128 v[204:207], v152 offset:20480
	global_load_lds_dwordx4 v136, s[44:45]
	s_mov_b32 m0, s47
	ds_read_b128 v[208:211], v152 offset:22528
	global_load_lds_dwordx4 v134, s[44:45]
	s_waitcnt vmcnt(8)
	s_waitcnt lgkmcnt(0)
	s_barrier
	v_mfma_f32_16x16x32_bf16 v[64:67], v[138:141], v[174:177], 0
	v_mfma_f32_16x16x32_bf16 v[60:63], v[146:149], v[174:177], 0
	v_mfma_f32_16x16x32_bf16 v[48:51], v[138:141], v[184:187], 0
	v_mfma_f32_16x16x32_bf16 v[44:47], v[146:149], v[184:187], 0
	v_mfma_f32_16x16x32_bf16 v[30:33], v[138:141], v[196:199], 0
	v_mfma_f32_16x16x32_bf16 v[26:29], v[146:149], v[196:199], 0
	v_mfma_f32_16x16x32_bf16 v[14:17], v[138:141], v[200:203], 0
	v_mfma_f32_16x16x32_bf16 v[10:13], v[146:149], v[200:203], 0
	v_mfma_f32_16x16x32_bf16 v[64:67], v[142:145], v[188:191], v[64:67]
	v_mfma_f32_16x16x32_bf16 v[60:63], v[154:157], v[188:191], v[60:63]
	v_mfma_f32_16x16x32_bf16 v[48:51], v[142:145], v[192:195], v[48:51]
	v_mfma_f32_16x16x32_bf16 v[44:47], v[154:157], v[192:195], v[44:47]
	v_mfma_f32_16x16x32_bf16 v[30:33], v[142:145], v[204:207], v[30:33]
	v_mfma_f32_16x16x32_bf16 v[26:29], v[154:157], v[204:207], v[26:29]
	v_mfma_f32_16x16x32_bf16 v[14:17], v[142:145], v[208:211], v[14:17]
	v_mfma_f32_16x16x32_bf16 v[10:13], v[154:157], v[208:211], v[10:13]
	v_mfma_f32_16x16x32_bf16 v[56:59], v[158:161], v[174:177], 0
	v_mfma_f32_16x16x32_bf16 v[52:55], v[166:169], v[174:177], 0
	v_mfma_f32_16x16x32_bf16 v[40:43], v[158:161], v[184:187], 0
	v_mfma_f32_16x16x32_bf16 v[36:39], v[166:169], v[184:187], 0
	v_mfma_f32_16x16x32_bf16 v[22:25], v[158:161], v[196:199], 0
	v_mfma_f32_16x16x32_bf16 v[18:21], v[166:169], v[196:199], 0
	v_mfma_f32_16x16x32_bf16 v[6:9], v[158:161], v[200:203], 0
	v_mfma_f32_16x16x32_bf16 v[2:5], v[166:169], v[200:203], 0
	v_mfma_f32_16x16x32_bf16 v[56:59], v[162:165], v[188:191], v[56:59]
	v_mfma_f32_16x16x32_bf16 v[52:55], v[170:173], v[188:191], v[52:55]
	v_mfma_f32_16x16x32_bf16 v[40:43], v[162:165], v[192:195], v[40:43]
	v_mfma_f32_16x16x32_bf16 v[36:39], v[170:173], v[192:195], v[36:39]
	v_mfma_f32_16x16x32_bf16 v[22:25], v[162:165], v[204:207], v[22:25]
	v_mfma_f32_16x16x32_bf16 v[18:21], v[170:173], v[204:207], v[18:21]
	v_mfma_f32_16x16x32_bf16 v[6:9], v[162:165], v[208:211], v[6:9]
	v_mfma_f32_16x16x32_bf16 v[2:5], v[170:173], v[208:211], v[2:5]
	s_barrier
	s_add_i32 s25, 0, 0x18000
	s_add_i32 s34, 0, 0x1c000
	ds_read_b128 v[138:141], v1 offset:32768
	ds_read_b128 v[142:145], v150 offset:32768
	ds_read_b128 v[146:149], v1 offset:34816
	ds_read_b128 v[154:157], v150 offset:34816
	ds_read_b128 v[158:161], v1 offset:49152
	ds_read_b128 v[162:165], v150 offset:49152
	ds_read_b128 v[166:169], v1 offset:51200
	ds_read_b128 v[170:173], v150 offset:51200
	s_add_u32 s30, s44, 0x80000
	s_addc_u32 s31, s45, 0
	s_mov_b32 m0, s48
	ds_read_b128 v[174:177], v151 offset:32768
	ds_read_b128 v[184:187], v151 offset:34816
	ds_read_b128 v[188:191], v152 offset:32768
	ds_read_b128 v[192:195], v152 offset:34816
	ds_read_b128 v[196:199], v151 offset:36864
	ds_read_b128 v[200:203], v151 offset:38912
	ds_read_b128 v[204:207], v152 offset:36864
	global_load_lds_dwordx4 v136, s[30:31]
	s_mov_b32 m0, s49
	ds_read_b128 v[208:211], v152 offset:38912
	global_load_lds_dwordx4 v134, s[30:31]
	s_waitcnt vmcnt(8)
	s_waitcnt lgkmcnt(0)
	s_barrier
	v_mfma_f32_16x16x32_bf16 v[128:131], v[138:141], v[174:177], v[128:131]
	v_mfma_f32_16x16x32_bf16 v[124:127], v[146:149], v[174:177], v[124:127]
	v_mfma_f32_16x16x32_bf16 v[112:115], v[138:141], v[184:187], v[112:115]
	v_mfma_f32_16x16x32_bf16 v[108:111], v[146:149], v[184:187], v[108:111]
	v_mfma_f32_16x16x32_bf16 v[96:99], v[138:141], v[196:199], v[96:99]
	v_mfma_f32_16x16x32_bf16 v[92:95], v[146:149], v[196:199], v[92:95]
	v_mfma_f32_16x16x32_bf16 v[80:83], v[138:141], v[200:203], v[80:83]
	v_mfma_f32_16x16x32_bf16 v[76:79], v[146:149], v[200:203], v[76:79]
	v_mfma_f32_16x16x32_bf16 v[128:131], v[142:145], v[188:191], v[128:131]
	v_mfma_f32_16x16x32_bf16 v[124:127], v[154:157], v[188:191], v[124:127]
	v_mfma_f32_16x16x32_bf16 v[112:115], v[142:145], v[192:195], v[112:115]
	v_mfma_f32_16x16x32_bf16 v[108:111], v[154:157], v[192:195], v[108:111]
	v_mfma_f32_16x16x32_bf16 v[96:99], v[142:145], v[204:207], v[96:99]
	v_mfma_f32_16x16x32_bf16 v[92:95], v[154:157], v[204:207], v[92:95]
	v_mfma_f32_16x16x32_bf16 v[80:83], v[142:145], v[208:211], v[80:83]
	v_mfma_f32_16x16x32_bf16 v[76:79], v[154:157], v[208:211], v[76:79]
	v_mfma_f32_16x16x32_bf16 v[120:123], v[158:161], v[174:177], v[120:123]
	v_mfma_f32_16x16x32_bf16 v[116:119], v[166:169], v[174:177], v[116:119]
	v_mfma_f32_16x16x32_bf16 v[104:107], v[158:161], v[184:187], v[104:107]
	v_mfma_f32_16x16x32_bf16 v[100:103], v[166:169], v[184:187], v[100:103]
	v_mfma_f32_16x16x32_bf16 v[88:91], v[158:161], v[196:199], v[88:91]
	v_mfma_f32_16x16x32_bf16 v[84:87], v[166:169], v[196:199], v[84:87]
	v_mfma_f32_16x16x32_bf16 v[72:75], v[158:161], v[200:203], v[72:75]
	v_mfma_f32_16x16x32_bf16 v[68:71], v[166:169], v[200:203], v[68:71]
	v_mfma_f32_16x16x32_bf16 v[120:123], v[162:165], v[188:191], v[120:123]
	v_mfma_f32_16x16x32_bf16 v[116:119], v[170:173], v[188:191], v[116:119]
	v_mfma_f32_16x16x32_bf16 v[104:107], v[162:165], v[192:195], v[104:107]
	v_mfma_f32_16x16x32_bf16 v[100:103], v[170:173], v[192:195], v[100:103]
	v_mfma_f32_16x16x32_bf16 v[88:91], v[162:165], v[204:207], v[88:91]
	v_mfma_f32_16x16x32_bf16 v[84:87], v[170:173], v[204:207], v[84:87]
	v_mfma_f32_16x16x32_bf16 v[72:75], v[162:165], v[208:211], v[72:75]
	v_mfma_f32_16x16x32_bf16 v[68:71], v[170:173], v[208:211], v[68:71]
	s_barrier
	s_add_i32 s25, s25, s33
	s_add_i32 m0, s25, 0xffffff80
	ds_read_b128 v[174:177], v151 offset:49152
	ds_read_b128 v[184:187], v151 offset:51200
	ds_read_b128 v[188:191], v152 offset:49152
	ds_read_b128 v[192:195], v152 offset:51200
	global_load_lds_dwordx4 v34, s[28:29] offset:128
	s_add_i32 m0, s25, 0x1f80
	s_mov_b64 s[98:99], s[28:29]
	s_add_u32 s28, s28, 0x80080
	s_addc_u32 s29, s29, 0
	s_add_i32 s25, s34, s33
	global_load_lds_dwordx4 v132, s[98:99] offset:128
	s_mov_b32 m0, s25
	ds_read_b128 v[196:199], v151 offset:53248
	global_load_lds_dwordx4 v34, s[28:29]
	s_add_i32 m0, s25, 0x2000
	ds_read_b128 v[200:203], v151 offset:55296
	global_load_lds_dwordx4 v132, s[28:29]
	s_add_i32 m0, s52, 0xffffff80
	ds_read_b128 v[204:207], v152 offset:53248
	global_load_lds_dwordx4 v136, s[44:45] offset:128
	s_add_i32 m0, s53, 0xffffff80
	ds_read_b128 v[208:211], v152 offset:55296
	global_load_lds_dwordx4 v134, s[44:45] offset:128
	s_waitcnt vmcnt(8)
	s_waitcnt lgkmcnt(0)
	s_barrier
	v_mfma_f32_16x16x32_bf16 v[64:67], v[138:141], v[174:177], v[64:67]
	v_mfma_f32_16x16x32_bf16 v[60:63], v[146:149], v[174:177], v[60:63]
	v_mfma_f32_16x16x32_bf16 v[48:51], v[138:141], v[184:187], v[48:51]
	v_mfma_f32_16x16x32_bf16 v[44:47], v[146:149], v[184:187], v[44:47]
	v_mfma_f32_16x16x32_bf16 v[30:33], v[138:141], v[196:199], v[30:33]
	v_mfma_f32_16x16x32_bf16 v[26:29], v[146:149], v[196:199], v[26:29]
	v_mfma_f32_16x16x32_bf16 v[14:17], v[138:141], v[200:203], v[14:17]
	v_mfma_f32_16x16x32_bf16 v[10:13], v[146:149], v[200:203], v[10:13]
	v_mfma_f32_16x16x32_bf16 v[64:67], v[142:145], v[188:191], v[64:67]
	v_mfma_f32_16x16x32_bf16 v[60:63], v[154:157], v[188:191], v[60:63]
	v_mfma_f32_16x16x32_bf16 v[48:51], v[142:145], v[192:195], v[48:51]
	v_mfma_f32_16x16x32_bf16 v[44:47], v[154:157], v[192:195], v[44:47]
	v_mfma_f32_16x16x32_bf16 v[30:33], v[142:145], v[204:207], v[30:33]
	v_mfma_f32_16x16x32_bf16 v[26:29], v[154:157], v[204:207], v[26:29]
	v_mfma_f32_16x16x32_bf16 v[14:17], v[142:145], v[208:211], v[14:17]
	v_mfma_f32_16x16x32_bf16 v[10:13], v[154:157], v[208:211], v[10:13]
	v_mfma_f32_16x16x32_bf16 v[56:59], v[158:161], v[174:177], v[56:59]
	v_mfma_f32_16x16x32_bf16 v[52:55], v[166:169], v[174:177], v[52:55]
	v_mfma_f32_16x16x32_bf16 v[40:43], v[158:161], v[184:187], v[40:43]
	v_mfma_f32_16x16x32_bf16 v[36:39], v[166:169], v[184:187], v[36:39]
	v_mfma_f32_16x16x32_bf16 v[22:25], v[158:161], v[196:199], v[22:25]
	v_mfma_f32_16x16x32_bf16 v[18:21], v[166:169], v[196:199], v[18:21]
	v_mfma_f32_16x16x32_bf16 v[6:9], v[158:161], v[200:203], v[6:9]
	v_mfma_f32_16x16x32_bf16 v[2:5], v[166:169], v[200:203], v[2:5]
	v_mfma_f32_16x16x32_bf16 v[56:59], v[162:165], v[188:191], v[56:59]
	v_mfma_f32_16x16x32_bf16 v[52:55], v[170:173], v[188:191], v[52:55]
	v_mfma_f32_16x16x32_bf16 v[40:43], v[162:165], v[192:195], v[40:43]
	v_mfma_f32_16x16x32_bf16 v[36:39], v[170:173], v[192:195], v[36:39]
	v_mfma_f32_16x16x32_bf16 v[22:25], v[162:165], v[204:207], v[22:25]
	v_mfma_f32_16x16x32_bf16 v[18:21], v[170:173], v[204:207], v[18:21]
	v_mfma_f32_16x16x32_bf16 v[6:9], v[162:165], v[208:211], v[6:9]
	v_mfma_f32_16x16x32_bf16 v[2:5], v[170:173], v[208:211], v[2:5]
	s_barrier
	s_add_i32 s24, s24, 2
	s_add_u32 s8, s8, 0x100
	s_addc_u32 s9, s9, 0
	s_add_u32 s21, s21, 0x100
	s_addc_u32 s23, s23, 0
	s_cmp_gt_u32 s24, 29
	s_cbranch_scc1 .Lpeel_done_P4
.LBB0_1023:
	s_add_u32 s25, s8, 0xfff80080
	s_addc_u32 s28, s9, -1
	s_add_i32 s30, 0, 0x10000
	s_cmp_eq_u32 s24, 28
	s_cselect_b32 s45, s12, s28
	s_cselect_b32 s44, s13, s25
	s_cselect_b32 s29, s19, s23
	s_cselect_b32 s28, s20, s21
	s_add_i32 s25, 0, 0x14000
	ds_read_b128 v[138:141], v1
	ds_read_b128 v[142:145], v150
	ds_read_b128 v[146:149], v1 offset:2048
	ds_read_b128 v[154:157], v150 offset:2048
	ds_read_b128 v[158:161], v1 offset:16384
	ds_read_b128 v[162:165], v150 offset:16384
	ds_read_b128 v[166:169], v1 offset:18432
	ds_read_b128 v[170:173], v150 offset:18432
	s_add_i32 m0, s46, 0xc000
	ds_read_b128 v[174:177], v151
	ds_read_b128 v[184:187], v151 offset:2048
	ds_read_b128 v[188:191], v152
	ds_read_b128 v[192:195], v152 offset:2048
	ds_read_b128 v[196:199], v151 offset:4096
	ds_read_b128 v[200:203], v151 offset:6144
	ds_read_b128 v[204:207], v152 offset:4096
	global_load_lds_dwordx4 v136, s[8:9]
	s_add_i32 m0, s46, 0xe000
	ds_read_b128 v[208:211], v152 offset:6144
	global_load_lds_dwordx4 v134, s[8:9]
	s_waitcnt vmcnt(8)
	s_waitcnt lgkmcnt(0)
	s_barrier
	v_mfma_f32_16x16x32_bf16 v[128:131], v[138:141], v[174:177], v[128:131]
	v_mfma_f32_16x16x32_bf16 v[124:127], v[146:149], v[174:177], v[124:127]
	v_mfma_f32_16x16x32_bf16 v[112:115], v[138:141], v[184:187], v[112:115]
	v_mfma_f32_16x16x32_bf16 v[108:111], v[146:149], v[184:187], v[108:111]
	v_mfma_f32_16x16x32_bf16 v[96:99], v[138:141], v[196:199], v[96:99]
	v_mfma_f32_16x16x32_bf16 v[92:95], v[146:149], v[196:199], v[92:95]
	v_mfma_f32_16x16x32_bf16 v[80:83], v[138:141], v[200:203], v[80:83]
	v_mfma_f32_16x16x32_bf16 v[76:79], v[146:149], v[200:203], v[76:79]
	v_mfma_f32_16x16x32_bf16 v[128:131], v[142:145], v[188:191], v[128:131]
	v_mfma_f32_16x16x32_bf16 v[124:127], v[154:157], v[188:191], v[124:127]
	v_mfma_f32_16x16x32_bf16 v[112:115], v[142:145], v[192:195], v[112:115]
	v_mfma_f32_16x16x32_bf16 v[108:111], v[154:157], v[192:195], v[108:111]
	v_mfma_f32_16x16x32_bf16 v[96:99], v[142:145], v[204:207], v[96:99]
	v_mfma_f32_16x16x32_bf16 v[92:95], v[154:157], v[204:207], v[92:95]
	v_mfma_f32_16x16x32_bf16 v[80:83], v[142:145], v[208:211], v[80:83]
	v_mfma_f32_16x16x32_bf16 v[76:79], v[154:157], v[208:211], v[76:79]
	v_mfma_f32_16x16x32_bf16 v[120:123], v[158:161], v[174:177], v[120:123]
	v_mfma_f32_16x16x32_bf16 v[116:119], v[166:169], v[174:177], v[116:119]
	v_mfma_f32_16x16x32_bf16 v[104:107], v[158:161], v[184:187], v[104:107]
	v_mfma_f32_16x16x32_bf16 v[100:103], v[166:169], v[184:187], v[100:103]
	v_mfma_f32_16x16x32_bf16 v[88:91], v[158:161], v[196:199], v[88:91]
	v_mfma_f32_16x16x32_bf16 v[84:87], v[166:169], v[196:199], v[84:87]
	v_mfma_f32_16x16x32_bf16 v[72:75], v[158:161], v[200:203], v[72:75]
	v_mfma_f32_16x16x32_bf16 v[68:71], v[166:169], v[200:203], v[68:71]
	v_mfma_f32_16x16x32_bf16 v[120:123], v[162:165], v[188:191], v[120:123]
	v_mfma_f32_16x16x32_bf16 v[116:119], v[170:173], v[188:191], v[116:119]
	v_mfma_f32_16x16x32_bf16 v[104:107], v[162:165], v[192:195], v[104:107]
	v_mfma_f32_16x16x32_bf16 v[100:103], v[170:173], v[192:195], v[100:103]
	v_mfma_f32_16x16x32_bf16 v[88:91], v[162:165], v[204:207], v[88:91]
	v_mfma_f32_16x16x32_bf16 v[84:87], v[170:173], v[204:207], v[84:87]
	v_mfma_f32_16x16x32_bf16 v[72:75], v[162:165], v[208:211], v[72:75]
	v_mfma_f32_16x16x32_bf16 v[68:71], v[170:173], v[208:211], v[68:71]
	s_barrier
	s_add_i32 s30, s30, s33
	s_mov_b32 m0, s30
	ds_read_b128 v[174:177], v151 offset:16384
	ds_read_b128 v[184:187], v151 offset:18432
	ds_read_b128 v[188:191], v152 offset:16384
	ds_read_b128 v[192:195], v152 offset:18432
	global_load_lds_dwordx4 v34, s[28:29]
	s_add_i32 m0, s30, 0x2000
	s_add_u32 s30, s28, 0x80000
	s_addc_u32 s31, s29, 0
	s_add_i32 s25, s25, s33
	global_load_lds_dwordx4 v132, s[28:29]
	s_mov_b32 m0, s25
	ds_read_b128 v[196:199], v151 offset:20480
	global_load_lds_dwordx4 v34, s[30:31]
	s_add_i32 m0, s25, 0x2000
	ds_read_b128 v[200:203], v151 offset:22528
	global_load_lds_dwordx4 v132, s[30:31]
	s_mov_b32 m0, s46
	ds_read_b128 v[204:207], v152 offset:20480
	global_load_lds_dwordx4 v136, s[44:45]
	s_mov_b32 m0, s47
	ds_read_b128 v[208:211], v152 offset:22528
	global_load_lds_dwordx4 v134, s[44:45]
	s_waitcnt vmcnt(8)
	s_waitcnt lgkmcnt(0)
	s_barrier
	v_mfma_f32_16x16x32_bf16 v[64:67], v[138:141], v[174:177], v[64:67]
	v_mfma_f32_16x16x32_bf16 v[60:63], v[146:149], v[174:177], v[60:63]
	v_mfma_f32_16x16x32_bf16 v[48:51], v[138:141], v[184:187], v[48:51]
	v_mfma_f32_16x16x32_bf16 v[44:47], v[146:149], v[184:187], v[44:47]
	v_mfma_f32_16x16x32_bf16 v[30:33], v[138:141], v[196:199], v[30:33]
	v_mfma_f32_16x16x32_bf16 v[26:29], v[146:149], v[196:199], v[26:29]
	v_mfma_f32_16x16x32_bf16 v[14:17], v[138:141], v[200:203], v[14:17]
	v_mfma_f32_16x16x32_bf16 v[10:13], v[146:149], v[200:203], v[10:13]
	v_mfma_f32_16x16x32_bf16 v[64:67], v[142:145], v[188:191], v[64:67]
	v_mfma_f32_16x16x32_bf16 v[60:63], v[154:157], v[188:191], v[60:63]
	v_mfma_f32_16x16x32_bf16 v[48:51], v[142:145], v[192:195], v[48:51]
	v_mfma_f32_16x16x32_bf16 v[44:47], v[154:157], v[192:195], v[44:47]
	v_mfma_f32_16x16x32_bf16 v[30:33], v[142:145], v[204:207], v[30:33]
	v_mfma_f32_16x16x32_bf16 v[26:29], v[154:157], v[204:207], v[26:29]
	v_mfma_f32_16x16x32_bf16 v[14:17], v[142:145], v[208:211], v[14:17]
	v_mfma_f32_16x16x32_bf16 v[10:13], v[154:157], v[208:211], v[10:13]
	v_mfma_f32_16x16x32_bf16 v[56:59], v[158:161], v[174:177], v[56:59]
	v_mfma_f32_16x16x32_bf16 v[52:55], v[166:169], v[174:177], v[52:55]
	v_mfma_f32_16x16x32_bf16 v[40:43], v[158:161], v[184:187], v[40:43]
	v_mfma_f32_16x16x32_bf16 v[36:39], v[166:169], v[184:187], v[36:39]
	v_mfma_f32_16x16x32_bf16 v[22:25], v[158:161], v[196:199], v[22:25]
	v_mfma_f32_16x16x32_bf16 v[18:21], v[166:169], v[196:199], v[18:21]
	v_mfma_f32_16x16x32_bf16 v[6:9], v[158:161], v[200:203], v[6:9]
	v_mfma_f32_16x16x32_bf16 v[2:5], v[166:169], v[200:203], v[2:5]
	v_mfma_f32_16x16x32_bf16 v[56:59], v[162:165], v[188:191], v[56:59]
	v_mfma_f32_16x16x32_bf16 v[52:55], v[170:173], v[188:191], v[52:55]
	v_mfma_f32_16x16x32_bf16 v[40:43], v[162:165], v[192:195], v[40:43]
	v_mfma_f32_16x16x32_bf16 v[36:39], v[170:173], v[192:195], v[36:39]
	v_mfma_f32_16x16x32_bf16 v[22:25], v[162:165], v[204:207], v[22:25]
	v_mfma_f32_16x16x32_bf16 v[18:21], v[170:173], v[204:207], v[18:21]
	v_mfma_f32_16x16x32_bf16 v[6:9], v[162:165], v[208:211], v[6:9]
	v_mfma_f32_16x16x32_bf16 v[2:5], v[170:173], v[208:211], v[2:5]
	s_barrier
	s_add_i32 s25, 0, 0x18000
	s_add_i32 s34, 0, 0x1c000
	ds_read_b128 v[138:141], v1 offset:32768
	ds_read_b128 v[142:145], v150 offset:32768
	ds_read_b128 v[146:149], v1 offset:34816
	ds_read_b128 v[154:157], v150 offset:34816
	ds_read_b128 v[158:161], v1 offset:49152
	ds_read_b128 v[162:165], v150 offset:49152
	ds_read_b128 v[166:169], v1 offset:51200
	ds_read_b128 v[170:173], v150 offset:51200
	s_add_u32 s30, s44, 0x80000
	s_addc_u32 s31, s45, 0
	s_mov_b32 m0, s48
	ds_read_b128 v[174:177], v151 offset:32768
	ds_read_b128 v[184:187], v151 offset:34816
	ds_read_b128 v[188:191], v152 offset:32768
	ds_read_b128 v[192:195], v152 offset:34816
	ds_read_b128 v[196:199], v151 offset:36864
	ds_read_b128 v[200:203], v151 offset:38912
	ds_read_b128 v[204:207], v152 offset:36864
	global_load_lds_dwordx4 v136, s[30:31]
	s_mov_b32 m0, s49
	ds_read_b128 v[208:211], v152 offset:38912
	global_load_lds_dwordx4 v134, s[30:31]
	s_waitcnt vmcnt(8)
	s_waitcnt lgkmcnt(0)
	s_barrier
	v_mfma_f32_16x16x32_bf16 v[128:131], v[138:141], v[174:177], v[128:131]
	v_mfma_f32_16x16x32_bf16 v[124:127], v[146:149], v[174:177], v[124:127]
	v_mfma_f32_16x16x32_bf16 v[112:115], v[138:141], v[184:187], v[112:115]
	v_mfma_f32_16x16x32_bf16 v[108:111], v[146:149], v[184:187], v[108:111]
	v_mfma_f32_16x16x32_bf16 v[96:99], v[138:141], v[196:199], v[96:99]
	v_mfma_f32_16x16x32_bf16 v[92:95], v[146:149], v[196:199], v[92:95]
	v_mfma_f32_16x16x32_bf16 v[80:83], v[138:141], v[200:203], v[80:83]
	v_mfma_f32_16x16x32_bf16 v[76:79], v[146:149], v[200:203], v[76:79]
	v_mfma_f32_16x16x32_bf16 v[128:131], v[142:145], v[188:191], v[128:131]
	v_mfma_f32_16x16x32_bf16 v[124:127], v[154:157], v[188:191], v[124:127]
	v_mfma_f32_16x16x32_bf16 v[112:115], v[142:145], v[192:195], v[112:115]
	v_mfma_f32_16x16x32_bf16 v[108:111], v[154:157], v[192:195], v[108:111]
	v_mfma_f32_16x16x32_bf16 v[96:99], v[142:145], v[204:207], v[96:99]
	v_mfma_f32_16x16x32_bf16 v[92:95], v[154:157], v[204:207], v[92:95]
	v_mfma_f32_16x16x32_bf16 v[80:83], v[142:145], v[208:211], v[80:83]
	v_mfma_f32_16x16x32_bf16 v[76:79], v[154:157], v[208:211], v[76:79]
	v_mfma_f32_16x16x32_bf16 v[120:123], v[158:161], v[174:177], v[120:123]
	v_mfma_f32_16x16x32_bf16 v[116:119], v[166:169], v[174:177], v[116:119]
	v_mfma_f32_16x16x32_bf16 v[104:107], v[158:161], v[184:187], v[104:107]
	v_mfma_f32_16x16x32_bf16 v[100:103], v[166:169], v[184:187], v[100:103]
	v_mfma_f32_16x16x32_bf16 v[88:91], v[158:161], v[196:199], v[88:91]
	v_mfma_f32_16x16x32_bf16 v[84:87], v[166:169], v[196:199], v[84:87]
	v_mfma_f32_16x16x32_bf16 v[72:75], v[158:161], v[200:203], v[72:75]
	v_mfma_f32_16x16x32_bf16 v[68:71], v[166:169], v[200:203], v[68:71]
	v_mfma_f32_16x16x32_bf16 v[120:123], v[162:165], v[188:191], v[120:123]
	v_mfma_f32_16x16x32_bf16 v[116:119], v[170:173], v[188:191], v[116:119]
	v_mfma_f32_16x16x32_bf16 v[104:107], v[162:165], v[192:195], v[104:107]
	v_mfma_f32_16x16x32_bf16 v[100:103], v[170:173], v[192:195], v[100:103]
	v_mfma_f32_16x16x32_bf16 v[88:91], v[162:165], v[204:207], v[88:91]
	v_mfma_f32_16x16x32_bf16 v[84:87], v[170:173], v[204:207], v[84:87]
	v_mfma_f32_16x16x32_bf16 v[72:75], v[162:165], v[208:211], v[72:75]
	v_mfma_f32_16x16x32_bf16 v[68:71], v[170:173], v[208:211], v[68:71]
	s_barrier
	s_add_i32 s25, s25, s33
	s_add_i32 m0, s25, 0xffffff80
	ds_read_b128 v[174:177], v151 offset:49152
	ds_read_b128 v[184:187], v151 offset:51200
	ds_read_b128 v[188:191], v152 offset:49152
	ds_read_b128 v[192:195], v152 offset:51200
	global_load_lds_dwordx4 v34, s[28:29] offset:128
	s_add_i32 m0, s25, 0x1f80
	s_mov_b64 s[98:99], s[28:29]
	s_add_u32 s28, s28, 0x80080
	s_addc_u32 s29, s29, 0
	s_add_i32 s25, s34, s33
	global_load_lds_dwordx4 v132, s[98:99] offset:128
	s_mov_b32 m0, s25
	ds_read_b128 v[196:199], v151 offset:53248
	global_load_lds_dwordx4 v34, s[28:29]
	s_add_i32 m0, s25, 0x2000
	ds_read_b128 v[200:203], v151 offset:55296
	global_load_lds_dwordx4 v132, s[28:29]
	s_add_i32 m0, s52, 0xffffff80
	ds_read_b128 v[204:207], v152 offset:53248
	global_load_lds_dwordx4 v136, s[44:45] offset:128
	s_add_i32 m0, s53, 0xffffff80
	ds_read_b128 v[208:211], v152 offset:55296
	global_load_lds_dwordx4 v134, s[44:45] offset:128
	s_waitcnt vmcnt(8)
	s_waitcnt lgkmcnt(0)
	s_barrier
	v_mfma_f32_16x16x32_bf16 v[64:67], v[138:141], v[174:177], v[64:67]
	v_mfma_f32_16x16x32_bf16 v[60:63], v[146:149], v[174:177], v[60:63]
	v_mfma_f32_16x16x32_bf16 v[48:51], v[138:141], v[184:187], v[48:51]
	v_mfma_f32_16x16x32_bf16 v[44:47], v[146:149], v[184:187], v[44:47]
	v_mfma_f32_16x16x32_bf16 v[30:33], v[138:141], v[196:199], v[30:33]
	v_mfma_f32_16x16x32_bf16 v[26:29], v[146:149], v[196:199], v[26:29]
	v_mfma_f32_16x16x32_bf16 v[14:17], v[138:141], v[200:203], v[14:17]
	v_mfma_f32_16x16x32_bf16 v[10:13], v[146:149], v[200:203], v[10:13]
	v_mfma_f32_16x16x32_bf16 v[64:67], v[142:145], v[188:191], v[64:67]
	v_mfma_f32_16x16x32_bf16 v[60:63], v[154:157], v[188:191], v[60:63]
	v_mfma_f32_16x16x32_bf16 v[48:51], v[142:145], v[192:195], v[48:51]
	v_mfma_f32_16x16x32_bf16 v[44:47], v[154:157], v[192:195], v[44:47]
	v_mfma_f32_16x16x32_bf16 v[30:33], v[142:145], v[204:207], v[30:33]
	v_mfma_f32_16x16x32_bf16 v[26:29], v[154:157], v[204:207], v[26:29]
	v_mfma_f32_16x16x32_bf16 v[14:17], v[142:145], v[208:211], v[14:17]
	v_mfma_f32_16x16x32_bf16 v[10:13], v[154:157], v[208:211], v[10:13]
	v_mfma_f32_16x16x32_bf16 v[56:59], v[158:161], v[174:177], v[56:59]
	v_mfma_f32_16x16x32_bf16 v[52:55], v[166:169], v[174:177], v[52:55]
	v_mfma_f32_16x16x32_bf16 v[40:43], v[158:161], v[184:187], v[40:43]
	v_mfma_f32_16x16x32_bf16 v[36:39], v[166:169], v[184:187], v[36:39]
	v_mfma_f32_16x16x32_bf16 v[22:25], v[158:161], v[196:199], v[22:25]
	v_mfma_f32_16x16x32_bf16 v[18:21], v[166:169], v[196:199], v[18:21]
	v_mfma_f32_16x16x32_bf16 v[6:9], v[158:161], v[200:203], v[6:9]
	v_mfma_f32_16x16x32_bf16 v[2:5], v[166:169], v[200:203], v[2:5]
	v_mfma_f32_16x16x32_bf16 v[56:59], v[162:165], v[188:191], v[56:59]
	v_mfma_f32_16x16x32_bf16 v[52:55], v[170:173], v[188:191], v[52:55]
	v_mfma_f32_16x16x32_bf16 v[40:43], v[162:165], v[192:195], v[40:43]
	v_mfma_f32_16x16x32_bf16 v[36:39], v[170:173], v[192:195], v[36:39]
	v_mfma_f32_16x16x32_bf16 v[22:25], v[162:165], v[204:207], v[22:25]
	v_mfma_f32_16x16x32_bf16 v[18:21], v[170:173], v[204:207], v[18:21]
	v_mfma_f32_16x16x32_bf16 v[6:9], v[162:165], v[208:211], v[6:9]
	v_mfma_f32_16x16x32_bf16 v[2:5], v[170:173], v[208:211], v[2:5]
	s_barrier
	s_add_i32 s24, s24, 2
	s_add_u32 s8, s8, 0x100
	s_addc_u32 s9, s9, 0
	s_add_u32 s21, s21, 0x100
	s_addc_u32 s23, s23, 0
	s_cmp_gt_u32 s24, 29
	s_cbranch_scc0 .LBB0_1023

.LBB0_1113:
	s_ashr_i32 s19, s18, 31
	s_lshl_b64 s[20:21], s[18:19], 20
	v_readlane_b32 s22, v254, 38
	v_readlane_b32 s23, v254, 39
	s_add_u32 s22, s22, s20
	s_addc_u32 s23, s23, s21
	s_and_b64 s[20:21], s[38:39], exec
	s_cselect_b32 s13, s23, s9
	s_cselect_b32 s19, s22, s8
	s_ashr_i32 s11, s10, 31
	s_lshl_b64 s[20:21], s[10:11], 20
	v_readlane_b32 s30, v254, 8
	v_readlane_b32 s31, v254, 9
	s_add_u32 s40, s30, s20
	s_addc_u32 s41, s31, s21
	v_mov_b32_e32 v2, v0
	s_and_b64 s[20:21], s[38:39], exec
	s_cselect_b32 s20, s41, s29
	s_cselect_b32 s21, s40, s28
	s_lshl_b32 s11, s24, 8
	v_and_or_b32 v2, v2, 63, s50
	v_or_b32_e32 v2, s11, v2
	v_ashrrev_i32_e32 v3, 31, v2
	v_readlane_b32 s24, v252, 61
	v_lshlrev_b64 v[2:3], 5, v[2:3]
	v_readlane_b32 s25, v252, 62
	s_add_u32 s8, s8, 0x80080
	s_addc_u32 s9, s9, 0
	v_lshl_add_u64 v[2:3], s[24:25], 0, v[2:3]
	global_load_dwordx4 v[116:119], v[2:3], off offset:16
	global_load_dwordx4 v[120:123], v[2:3], off
	s_add_u32 s24, s28, 0x100
	s_addc_u32 s25, s29, 0
	s_mov_b32 s30, -2
	v_readlane_b32 s57, v255, 20
	v_readlane_b32 s58, v255, 21
	v_readlane_b32 s59, v255, 22
	v_readlane_b32 s60, v255, 23
	s_mov_b64 s[62:63], 0x80
	s_add_u32 s28, s8, 0xfff80080
	s_addc_u32 s29, s9, -1
	s_add_i32 s31, 0, 0x10000
	s_cmp_eq_u32 s30, 28
	s_cselect_b32 s43, s13, s29
	s_cselect_b32 s42, s19, s28
	ds_read_b128 v[150:153], v1
	ds_read_b128 v[154:157], v146
	s_cselect_b32 s29, s20, s25
	s_cselect_b32 s28, s21, s24
	s_add_i32 s56, 0, 0x14000
	ds_read_b128 v[158:161], v1 offset:2048
	ds_read_b128 v[162:165], v146 offset:2048
	ds_read_b128 v[166:169], v1 offset:16384
	ds_read_b128 v[170:173], v146 offset:16384
	ds_read_b128 v[174:177], v1 offset:18432
	ds_read_b128 v[184:187], v146 offset:18432
	s_add_i32 m0, s34, 0xc000
	ds_read_b128 v[188:191], v147
	ds_read_b128 v[192:195], v147 offset:2048
	ds_read_b128 v[196:199], v148
	ds_read_b128 v[200:203], v148 offset:2048
	ds_read_b128 v[204:207], v147 offset:4096
	ds_read_b128 v[208:211], v147 offset:6144
	ds_read_b128 v[224:227], v148 offset:4096
	global_load_lds_dwordx4 v144, s[8:9]
	s_add_i32 m0, s34, 0xe000
	ds_read_b128 v[228:231], v148 offset:6144
	global_load_lds_dwordx4 v142, s[8:9]
	s_waitcnt vmcnt(8)
	s_waitcnt lgkmcnt(0)
	s_barrier
	v_mfma_f32_16x16x32_bf16 v[132:135], v[150:153], v[188:191], 0
	v_mfma_f32_16x16x32_bf16 v[124:127], v[158:161], v[188:191], 0
	v_mfma_f32_16x16x32_bf16 v[108:111], v[150:153], v[192:195], 0
	v_mfma_f32_16x16x32_bf16 v[100:103], v[158:161], v[192:195], 0
	v_mfma_f32_16x16x32_bf16 v[92:95], v[150:153], v[204:207], 0
	v_mfma_f32_16x16x32_bf16 v[84:87], v[158:161], v[204:207], 0
	v_mfma_f32_16x16x32_bf16 v[76:79], v[150:153], v[208:211], 0
	v_mfma_f32_16x16x32_bf16 v[68:71], v[158:161], v[208:211], 0
	v_mfma_f32_16x16x32_bf16 v[132:135], v[154:157], v[196:199], v[132:135]
	v_mfma_f32_16x16x32_bf16 v[124:127], v[162:165], v[196:199], v[124:127]
	v_mfma_f32_16x16x32_bf16 v[108:111], v[154:157], v[200:203], v[108:111]
	v_mfma_f32_16x16x32_bf16 v[100:103], v[162:165], v[200:203], v[100:103]
	v_mfma_f32_16x16x32_bf16 v[92:95], v[154:157], v[224:227], v[92:95]
	v_mfma_f32_16x16x32_bf16 v[84:87], v[162:165], v[224:227], v[84:87]
	v_mfma_f32_16x16x32_bf16 v[76:79], v[154:157], v[228:231], v[76:79]
	v_mfma_f32_16x16x32_bf16 v[68:71], v[162:165], v[228:231], v[68:71]
	v_mfma_f32_16x16x32_bf16 v[136:139], v[166:169], v[188:191], 0
	v_mfma_f32_16x16x32_bf16 v[128:131], v[174:177], v[188:191], 0
	v_mfma_f32_16x16x32_bf16 v[112:115], v[166:169], v[192:195], 0
	v_mfma_f32_16x16x32_bf16 v[104:107], v[174:177], v[192:195], 0
	v_mfma_f32_16x16x32_bf16 v[96:99], v[166:169], v[204:207], 0
	v_mfma_f32_16x16x32_bf16 v[88:91], v[174:177], v[204:207], 0
	v_mfma_f32_16x16x32_bf16 v[80:83], v[166:169], v[208:211], 0
	v_mfma_f32_16x16x32_bf16 v[72:75], v[174:177], v[208:211], 0
	v_mfma_f32_16x16x32_bf16 v[136:139], v[170:173], v[196:199], v[136:139]
	v_mfma_f32_16x16x32_bf16 v[128:131], v[184:187], v[196:199], v[128:131]
	v_mfma_f32_16x16x32_bf16 v[112:115], v[170:173], v[200:203], v[112:115]
	v_mfma_f32_16x16x32_bf16 v[104:107], v[184:187], v[200:203], v[104:107]
	v_mfma_f32_16x16x32_bf16 v[96:99], v[170:173], v[224:227], v[96:99]
	v_mfma_f32_16x16x32_bf16 v[88:91], v[184:187], v[224:227], v[88:91]
	v_mfma_f32_16x16x32_bf16 v[80:83], v[170:173], v[228:231], v[80:83]
	v_mfma_f32_16x16x32_bf16 v[72:75], v[184:187], v[228:231], v[72:75]
	s_barrier
	s_add_i32 s31, s31, s33
	s_mov_b32 m0, s31
	ds_read_b128 v[188:191], v147 offset:16384
	ds_read_b128 v[192:195], v147 offset:18432
	ds_read_b128 v[196:199], v148 offset:16384
	ds_read_b128 v[200:203], v148 offset:18432
	global_load_lds_dwordx4 v34, s[28:29]
	s_add_i32 m0, s31, 0x2000
	s_add_u32 s54, s28, 0x80000
	s_addc_u32 s55, s29, 0
	s_add_i32 s31, s56, s33
	global_load_lds_dwordx4 v140, s[28:29]
	s_mov_b32 m0, s31
	ds_read_b128 v[204:207], v147 offset:20480
	global_load_lds_dwordx4 v34, s[54:55]
	s_add_i32 m0, s31, 0x2000
	ds_read_b128 v[208:211], v147 offset:22528
	global_load_lds_dwordx4 v140, s[54:55]
	s_mov_b32 m0, s34
	ds_read_b128 v[224:227], v148 offset:20480
	global_load_lds_dwordx4 v144, s[42:43]
	s_mov_b32 m0, s35
	ds_read_b128 v[228:231], v148 offset:22528
	global_load_lds_dwordx4 v142, s[42:43]
	s_waitcnt vmcnt(8)
	s_waitcnt lgkmcnt(0)
	s_barrier
	v_mfma_f32_16x16x32_bf16 v[60:63], v[150:153], v[188:191], 0
	v_mfma_f32_16x16x32_bf16 v[52:55], v[158:161], v[188:191], 0
	v_mfma_f32_16x16x32_bf16 v[44:47], v[150:153], v[192:195], 0
	v_mfma_f32_16x16x32_bf16 v[36:39], v[158:161], v[192:195], 0
	v_mfma_f32_16x16x32_bf16 v[26:29], v[150:153], v[204:207], 0
	v_mfma_f32_16x16x32_bf16 v[18:21], v[158:161], v[204:207], 0
	v_mfma_f32_16x16x32_bf16 v[10:13], v[150:153], v[208:211], 0
	v_mfma_f32_16x16x32_bf16 v[6:9], v[158:161], v[208:211], 0
	v_mfma_f32_16x16x32_bf16 v[60:63], v[154:157], v[196:199], v[60:63]
	v_mfma_f32_16x16x32_bf16 v[52:55], v[162:165], v[196:199], v[52:55]
	v_mfma_f32_16x16x32_bf16 v[44:47], v[154:157], v[200:203], v[44:47]
	v_mfma_f32_16x16x32_bf16 v[36:39], v[162:165], v[200:203], v[36:39]
	v_mfma_f32_16x16x32_bf16 v[26:29], v[154:157], v[224:227], v[26:29]
	v_mfma_f32_16x16x32_bf16 v[18:21], v[162:165], v[224:227], v[18:21]
	v_mfma_f32_16x16x32_bf16 v[10:13], v[154:157], v[228:231], v[10:13]
	v_mfma_f32_16x16x32_bf16 v[6:9], v[162:165], v[228:231], v[6:9]
	v_mfma_f32_16x16x32_bf16 v[64:67], v[166:169], v[188:191], 0
	v_mfma_f32_16x16x32_bf16 v[56:59], v[174:177], v[188:191], 0
	v_mfma_f32_16x16x32_bf16 v[48:51], v[166:169], v[192:195], 0
	v_mfma_f32_16x16x32_bf16 v[40:43], v[174:177], v[192:195], 0
	v_mfma_f32_16x16x32_bf16 v[30:33], v[166:169], v[204:207], 0
	v_mfma_f32_16x16x32_bf16 v[22:25], v[174:177], v[204:207], 0
	v_mfma_f32_16x16x32_bf16 v[14:17], v[166:169], v[208:211], 0
	v_mfma_f32_16x16x32_bf16 v[2:5], v[174:177], v[208:211], 0
	v_mfma_f32_16x16x32_bf16 v[64:67], v[170:173], v[196:199], v[64:67]
	v_mfma_f32_16x16x32_bf16 v[56:59], v[184:187], v[196:199], v[56:59]
	v_mfma_f32_16x16x32_bf16 v[48:51], v[170:173], v[200:203], v[48:51]
	v_mfma_f32_16x16x32_bf16 v[40:43], v[184:187], v[200:203], v[40:43]
	v_mfma_f32_16x16x32_bf16 v[30:33], v[170:173], v[224:227], v[30:33]
	v_mfma_f32_16x16x32_bf16 v[22:25], v[184:187], v[224:227], v[22:25]
	v_mfma_f32_16x16x32_bf16 v[14:17], v[170:173], v[228:231], v[14:17]
	v_mfma_f32_16x16x32_bf16 v[2:5], v[184:187], v[228:231], v[2:5]
	s_barrier
	s_add_i32 s31, 0, 0x18000
	ds_read_b128 v[150:153], v1 offset:32768
	ds_read_b128 v[154:157], v146 offset:32768
	s_add_i32 s54, 0, 0x1c000
	ds_read_b128 v[158:161], v1 offset:34816
	ds_read_b128 v[162:165], v146 offset:34816
	ds_read_b128 v[166:169], v1 offset:49152
	ds_read_b128 v[170:173], v146 offset:49152
	ds_read_b128 v[174:177], v1 offset:51200
	ds_read_b128 v[184:187], v146 offset:51200
	s_mov_b64 s[100:101], s[42:43]
	s_add_u32 s42, s42, 0x80000
	s_addc_u32 s43, s43, 0
	s_mov_b32 m0, s44
	ds_read_b128 v[188:191], v147 offset:32768
	ds_read_b128 v[192:195], v147 offset:34816
	ds_read_b128 v[196:199], v148 offset:32768
	ds_read_b128 v[200:203], v148 offset:34816
	ds_read_b128 v[204:207], v147 offset:36864
	ds_read_b128 v[208:211], v147 offset:38912
	ds_read_b128 v[224:227], v148 offset:36864
	global_load_lds_dwordx4 v144, s[42:43]
	s_mov_b32 m0, s45
	ds_read_b128 v[228:231], v148 offset:38912
	global_load_lds_dwordx4 v142, s[42:43]
	s_waitcnt vmcnt(8)
	s_waitcnt lgkmcnt(0)
	s_barrier
	v_mfma_f32_16x16x32_bf16 v[132:135], v[150:153], v[188:191], v[132:135]
	v_mfma_f32_16x16x32_bf16 v[124:127], v[158:161], v[188:191], v[124:127]
	v_mfma_f32_16x16x32_bf16 v[108:111], v[150:153], v[192:195], v[108:111]
	v_mfma_f32_16x16x32_bf16 v[100:103], v[158:161], v[192:195], v[100:103]
	v_mfma_f32_16x16x32_bf16 v[92:95], v[150:153], v[204:207], v[92:95]
	v_mfma_f32_16x16x32_bf16 v[84:87], v[158:161], v[204:207], v[84:87]
	v_mfma_f32_16x16x32_bf16 v[76:79], v[150:153], v[208:211], v[76:79]
	v_mfma_f32_16x16x32_bf16 v[68:71], v[158:161], v[208:211], v[68:71]
	v_mfma_f32_16x16x32_bf16 v[132:135], v[154:157], v[196:199], v[132:135]
	v_mfma_f32_16x16x32_bf16 v[124:127], v[162:165], v[196:199], v[124:127]
	v_mfma_f32_16x16x32_bf16 v[108:111], v[154:157], v[200:203], v[108:111]
	v_mfma_f32_16x16x32_bf16 v[100:103], v[162:165], v[200:203], v[100:103]
	v_mfma_f32_16x16x32_bf16 v[92:95], v[154:157], v[224:227], v[92:95]
	v_mfma_f32_16x16x32_bf16 v[84:87], v[162:165], v[224:227], v[84:87]
	v_mfma_f32_16x16x32_bf16 v[76:79], v[154:157], v[228:231], v[76:79]
	v_mfma_f32_16x16x32_bf16 v[68:71], v[162:165], v[228:231], v[68:71]
	v_mfma_f32_16x16x32_bf16 v[136:139], v[166:169], v[188:191], v[136:139]
	v_mfma_f32_16x16x32_bf16 v[128:131], v[174:177], v[188:191], v[128:131]
	v_mfma_f32_16x16x32_bf16 v[112:115], v[166:169], v[192:195], v[112:115]
	v_mfma_f32_16x16x32_bf16 v[104:107], v[174:177], v[192:195], v[104:107]
	v_mfma_f32_16x16x32_bf16 v[96:99], v[166:169], v[204:207], v[96:99]
	v_mfma_f32_16x16x32_bf16 v[88:91], v[174:177], v[204:207], v[88:91]
	v_mfma_f32_16x16x32_bf16 v[80:83], v[166:169], v[208:211], v[80:83]
	v_mfma_f32_16x16x32_bf16 v[72:75], v[174:177], v[208:211], v[72:75]
	v_mfma_f32_16x16x32_bf16 v[136:139], v[170:173], v[196:199], v[136:139]
	v_mfma_f32_16x16x32_bf16 v[128:131], v[184:187], v[196:199], v[128:131]
	v_mfma_f32_16x16x32_bf16 v[112:115], v[170:173], v[200:203], v[112:115]
	v_mfma_f32_16x16x32_bf16 v[104:107], v[184:187], v[200:203], v[104:107]
	v_mfma_f32_16x16x32_bf16 v[96:99], v[170:173], v[224:227], v[96:99]
	v_mfma_f32_16x16x32_bf16 v[88:91], v[184:187], v[224:227], v[88:91]
	v_mfma_f32_16x16x32_bf16 v[80:83], v[170:173], v[228:231], v[80:83]
	v_mfma_f32_16x16x32_bf16 v[72:75], v[184:187], v[228:231], v[72:75]
	s_barrier
	s_add_i32 s31, s31, s33
	s_add_i32 m0, s31, 0xffffff80
	ds_read_b128 v[188:191], v147 offset:49152
	ds_read_b128 v[192:195], v147 offset:51200
	ds_read_b128 v[196:199], v148 offset:49152
	ds_read_b128 v[200:203], v148 offset:51200
	global_load_lds_dwordx4 v34, s[28:29] offset:128
	s_add_i32 m0, s31, 0x1f80
	s_mov_b64 s[98:99], s[28:29]
	s_add_u32 s28, s28, 0x80080
	s_addc_u32 s29, s29, 0
	s_add_i32 s31, s54, s33
	global_load_lds_dwordx4 v140, s[98:99] offset:128
	s_mov_b32 m0, s31
	ds_read_b128 v[204:207], v147 offset:53248
	global_load_lds_dwordx4 v34, s[28:29]
	s_add_i32 m0, s31, 0x2000
	ds_read_b128 v[208:211], v147 offset:55296
	global_load_lds_dwordx4 v140, s[28:29]
	s_add_i32 m0, s48, 0xffffff80
	ds_read_b128 v[224:227], v148 offset:53248
	global_load_lds_dwordx4 v144, s[100:101] offset:128
	s_add_i32 m0, s49, 0xffffff80
	ds_read_b128 v[228:231], v148 offset:55296
	global_load_lds_dwordx4 v142, s[100:101] offset:128
	s_waitcnt vmcnt(8)
	s_waitcnt lgkmcnt(0)
	s_barrier
	v_mfma_f32_16x16x32_bf16 v[60:63], v[150:153], v[188:191], v[60:63]
	v_mfma_f32_16x16x32_bf16 v[52:55], v[158:161], v[188:191], v[52:55]
	v_mfma_f32_16x16x32_bf16 v[44:47], v[150:153], v[192:195], v[44:47]
	v_mfma_f32_16x16x32_bf16 v[36:39], v[158:161], v[192:195], v[36:39]
	v_mfma_f32_16x16x32_bf16 v[26:29], v[150:153], v[204:207], v[26:29]
	v_mfma_f32_16x16x32_bf16 v[18:21], v[158:161], v[204:207], v[18:21]
	v_mfma_f32_16x16x32_bf16 v[10:13], v[150:153], v[208:211], v[10:13]
	v_mfma_f32_16x16x32_bf16 v[6:9], v[158:161], v[208:211], v[6:9]
	v_mfma_f32_16x16x32_bf16 v[60:63], v[154:157], v[196:199], v[60:63]
	v_mfma_f32_16x16x32_bf16 v[52:55], v[162:165], v[196:199], v[52:55]
	v_mfma_f32_16x16x32_bf16 v[44:47], v[154:157], v[200:203], v[44:47]
	v_mfma_f32_16x16x32_bf16 v[36:39], v[162:165], v[200:203], v[36:39]
	v_mfma_f32_16x16x32_bf16 v[26:29], v[154:157], v[224:227], v[26:29]
	v_mfma_f32_16x16x32_bf16 v[18:21], v[162:165], v[224:227], v[18:21]
	v_mfma_f32_16x16x32_bf16 v[10:13], v[154:157], v[228:231], v[10:13]
	v_mfma_f32_16x16x32_bf16 v[6:9], v[162:165], v[228:231], v[6:9]
	v_mfma_f32_16x16x32_bf16 v[64:67], v[166:169], v[188:191], v[64:67]
	v_mfma_f32_16x16x32_bf16 v[56:59], v[174:177], v[188:191], v[56:59]
	v_mfma_f32_16x16x32_bf16 v[48:51], v[166:169], v[192:195], v[48:51]
	v_mfma_f32_16x16x32_bf16 v[40:43], v[174:177], v[192:195], v[40:43]
	v_mfma_f32_16x16x32_bf16 v[30:33], v[166:169], v[204:207], v[30:33]
	v_mfma_f32_16x16x32_bf16 v[22:25], v[174:177], v[204:207], v[22:25]
	v_mfma_f32_16x16x32_bf16 v[14:17], v[166:169], v[208:211], v[14:17]
	v_mfma_f32_16x16x32_bf16 v[2:5], v[174:177], v[208:211], v[2:5]
	v_mfma_f32_16x16x32_bf16 v[64:67], v[170:173], v[196:199], v[64:67]
	v_mfma_f32_16x16x32_bf16 v[56:59], v[184:187], v[196:199], v[56:59]
	v_mfma_f32_16x16x32_bf16 v[48:51], v[170:173], v[200:203], v[48:51]
	v_mfma_f32_16x16x32_bf16 v[40:43], v[184:187], v[200:203], v[40:43]
	v_mfma_f32_16x16x32_bf16 v[30:33], v[170:173], v[224:227], v[30:33]
	v_mfma_f32_16x16x32_bf16 v[22:25], v[184:187], v[224:227], v[22:25]
	v_mfma_f32_16x16x32_bf16 v[14:17], v[170:173], v[228:231], v[14:17]
	v_mfma_f32_16x16x32_bf16 v[2:5], v[184:187], v[228:231], v[2:5]
	s_barrier
	s_add_i32 s30, s30, 2
	s_add_u32 s8, s8, 0x100
	s_addc_u32 s9, s9, 0
	s_add_u32 s24, s24, 0x100
	s_addc_u32 s25, s25, 0
	s_cmp_gt_u32 s30, 29
	s_cbranch_scc1 .Lpeel_done_P6
.LBB0_1114:
	s_add_u32 s28, s8, 0xfff80080
	s_addc_u32 s29, s9, -1
	s_add_i32 s31, 0, 0x10000
	s_cmp_eq_u32 s30, 28
	s_cselect_b32 s43, s13, s29
	s_cselect_b32 s42, s19, s28
	ds_read_b128 v[150:153], v1
	ds_read_b128 v[154:157], v146
	s_cselect_b32 s29, s20, s25
	s_cselect_b32 s28, s21, s24
	s_add_i32 s56, 0, 0x14000
	ds_read_b128 v[158:161], v1 offset:2048
	ds_read_b128 v[162:165], v146 offset:2048
	ds_read_b128 v[166:169], v1 offset:16384
	ds_read_b128 v[170:173], v146 offset:16384
	ds_read_b128 v[174:177], v1 offset:18432
	ds_read_b128 v[184:187], v146 offset:18432
	s_add_i32 m0, s34, 0xc000
	ds_read_b128 v[188:191], v147
	ds_read_b128 v[192:195], v147 offset:2048
	ds_read_b128 v[196:199], v148
	ds_read_b128 v[200:203], v148 offset:2048
	ds_read_b128 v[204:207], v147 offset:4096
	ds_read_b128 v[208:211], v147 offset:6144
	ds_read_b128 v[224:227], v148 offset:4096
	global_load_lds_dwordx4 v144, s[8:9]
	s_add_i32 m0, s34, 0xe000
	ds_read_b128 v[228:231], v148 offset:6144
	global_load_lds_dwordx4 v142, s[8:9]
	s_waitcnt vmcnt(8)
	s_waitcnt lgkmcnt(0)
	s_barrier
	v_mfma_f32_16x16x32_bf16 v[132:135], v[150:153], v[188:191], v[132:135]
	v_mfma_f32_16x16x32_bf16 v[124:127], v[158:161], v[188:191], v[124:127]
	v_mfma_f32_16x16x32_bf16 v[108:111], v[150:153], v[192:195], v[108:111]
	v_mfma_f32_16x16x32_bf16 v[100:103], v[158:161], v[192:195], v[100:103]
	v_mfma_f32_16x16x32_bf16 v[92:95], v[150:153], v[204:207], v[92:95]
	v_mfma_f32_16x16x32_bf16 v[84:87], v[158:161], v[204:207], v[84:87]
	v_mfma_f32_16x16x32_bf16 v[76:79], v[150:153], v[208:211], v[76:79]
	v_mfma_f32_16x16x32_bf16 v[68:71], v[158:161], v[208:211], v[68:71]
	v_mfma_f32_16x16x32_bf16 v[132:135], v[154:157], v[196:199], v[132:135]
	v_mfma_f32_16x16x32_bf16 v[124:127], v[162:165], v[196:199], v[124:127]
	v_mfma_f32_16x16x32_bf16 v[108:111], v[154:157], v[200:203], v[108:111]
	v_mfma_f32_16x16x32_bf16 v[100:103], v[162:165], v[200:203], v[100:103]
	v_mfma_f32_16x16x32_bf16 v[92:95], v[154:157], v[224:227], v[92:95]
	v_mfma_f32_16x16x32_bf16 v[84:87], v[162:165], v[224:227], v[84:87]
	v_mfma_f32_16x16x32_bf16 v[76:79], v[154:157], v[228:231], v[76:79]
	v_mfma_f32_16x16x32_bf16 v[68:71], v[162:165], v[228:231], v[68:71]
	v_mfma_f32_16x16x32_bf16 v[136:139], v[166:169], v[188:191], v[136:139]
	v_mfma_f32_16x16x32_bf16 v[128:131], v[174:177], v[188:191], v[128:131]
	v_mfma_f32_16x16x32_bf16 v[112:115], v[166:169], v[192:195], v[112:115]
	v_mfma_f32_16x16x32_bf16 v[104:107], v[174:177], v[192:195], v[104:107]
	v_mfma_f32_16x16x32_bf16 v[96:99], v[166:169], v[204:207], v[96:99]
	v_mfma_f32_16x16x32_bf16 v[88:91], v[174:177], v[204:207], v[88:91]
	v_mfma_f32_16x16x32_bf16 v[80:83], v[166:169], v[208:211], v[80:83]
	v_mfma_f32_16x16x32_bf16 v[72:75], v[174:177], v[208:211], v[72:75]
	v_mfma_f32_16x16x32_bf16 v[136:139], v[170:173], v[196:199], v[136:139]
	v_mfma_f32_16x16x32_bf16 v[128:131], v[184:187], v[196:199], v[128:131]
	v_mfma_f32_16x16x32_bf16 v[112:115], v[170:173], v[200:203], v[112:115]
	v_mfma_f32_16x16x32_bf16 v[104:107], v[184:187], v[200:203], v[104:107]
	v_mfma_f32_16x16x32_bf16 v[96:99], v[170:173], v[224:227], v[96:99]
	v_mfma_f32_16x16x32_bf16 v[88:91], v[184:187], v[224:227], v[88:91]
	v_mfma_f32_16x16x32_bf16 v[80:83], v[170:173], v[228:231], v[80:83]
	v_mfma_f32_16x16x32_bf16 v[72:75], v[184:187], v[228:231], v[72:75]
	s_barrier
	s_add_i32 s31, s31, s33
	s_mov_b32 m0, s31
	ds_read_b128 v[188:191], v147 offset:16384
	ds_read_b128 v[192:195], v147 offset:18432
	ds_read_b128 v[196:199], v148 offset:16384
	ds_read_b128 v[200:203], v148 offset:18432
	global_load_lds_dwordx4 v34, s[28:29]
	s_add_i32 m0, s31, 0x2000
	s_add_u32 s54, s28, 0x80000
	s_addc_u32 s55, s29, 0
	s_add_i32 s31, s56, s33
	global_load_lds_dwordx4 v140, s[28:29]
	s_mov_b32 m0, s31
	ds_read_b128 v[204:207], v147 offset:20480
	global_load_lds_dwordx4 v34, s[54:55]
	s_add_i32 m0, s31, 0x2000
	ds_read_b128 v[208:211], v147 offset:22528
	global_load_lds_dwordx4 v140, s[54:55]
	s_mov_b32 m0, s34
	ds_read_b128 v[224:227], v148 offset:20480
	global_load_lds_dwordx4 v144, s[42:43]
	s_mov_b32 m0, s35
	ds_read_b128 v[228:231], v148 offset:22528
	global_load_lds_dwordx4 v142, s[42:43]
	s_waitcnt vmcnt(8)
	s_waitcnt lgkmcnt(0)
	s_barrier
	v_mfma_f32_16x16x32_bf16 v[60:63], v[150:153], v[188:191], v[60:63]
	v_mfma_f32_16x16x32_bf16 v[52:55], v[158:161], v[188:191], v[52:55]
	v_mfma_f32_16x16x32_bf16 v[44:47], v[150:153], v[192:195], v[44:47]
	v_mfma_f32_16x16x32_bf16 v[36:39], v[158:161], v[192:195], v[36:39]
	v_mfma_f32_16x16x32_bf16 v[26:29], v[150:153], v[204:207], v[26:29]
	v_mfma_f32_16x16x32_bf16 v[18:21], v[158:161], v[204:207], v[18:21]
	v_mfma_f32_16x16x32_bf16 v[10:13], v[150:153], v[208:211], v[10:13]
	v_mfma_f32_16x16x32_bf16 v[6:9], v[158:161], v[208:211], v[6:9]
	v_mfma_f32_16x16x32_bf16 v[60:63], v[154:157], v[196:199], v[60:63]
	v_mfma_f32_16x16x32_bf16 v[52:55], v[162:165], v[196:199], v[52:55]
	v_mfma_f32_16x16x32_bf16 v[44:47], v[154:157], v[200:203], v[44:47]
	v_mfma_f32_16x16x32_bf16 v[36:39], v[162:165], v[200:203], v[36:39]
	v_mfma_f32_16x16x32_bf16 v[26:29], v[154:157], v[224:227], v[26:29]
	v_mfma_f32_16x16x32_bf16 v[18:21], v[162:165], v[224:227], v[18:21]
	v_mfma_f32_16x16x32_bf16 v[10:13], v[154:157], v[228:231], v[10:13]
	v_mfma_f32_16x16x32_bf16 v[6:9], v[162:165], v[228:231], v[6:9]
	v_mfma_f32_16x16x32_bf16 v[64:67], v[166:169], v[188:191], v[64:67]
	v_mfma_f32_16x16x32_bf16 v[56:59], v[174:177], v[188:191], v[56:59]
	v_mfma_f32_16x16x32_bf16 v[48:51], v[166:169], v[192:195], v[48:51]
	v_mfma_f32_16x16x32_bf16 v[40:43], v[174:177], v[192:195], v[40:43]
	v_mfma_f32_16x16x32_bf16 v[30:33], v[166:169], v[204:207], v[30:33]
	v_mfma_f32_16x16x32_bf16 v[22:25], v[174:177], v[204:207], v[22:25]
	v_mfma_f32_16x16x32_bf16 v[14:17], v[166:169], v[208:211], v[14:17]
	v_mfma_f32_16x16x32_bf16 v[2:5], v[174:177], v[208:211], v[2:5]
	v_mfma_f32_16x16x32_bf16 v[64:67], v[170:173], v[196:199], v[64:67]
	v_mfma_f32_16x16x32_bf16 v[56:59], v[184:187], v[196:199], v[56:59]
	v_mfma_f32_16x16x32_bf16 v[48:51], v[170:173], v[200:203], v[48:51]
	v_mfma_f32_16x16x32_bf16 v[40:43], v[184:187], v[200:203], v[40:43]
	v_mfma_f32_16x16x32_bf16 v[30:33], v[170:173], v[224:227], v[30:33]
	v_mfma_f32_16x16x32_bf16 v[22:25], v[184:187], v[224:227], v[22:25]
	v_mfma_f32_16x16x32_bf16 v[14:17], v[170:173], v[228:231], v[14:17]
	v_mfma_f32_16x16x32_bf16 v[2:5], v[184:187], v[228:231], v[2:5]
	s_barrier
	s_add_i32 s31, 0, 0x18000
	ds_read_b128 v[150:153], v1 offset:32768
	ds_read_b128 v[154:157], v146 offset:32768
	s_add_i32 s54, 0, 0x1c000
	ds_read_b128 v[158:161], v1 offset:34816
	ds_read_b128 v[162:165], v146 offset:34816
	ds_read_b128 v[166:169], v1 offset:49152
	ds_read_b128 v[170:173], v146 offset:49152
	ds_read_b128 v[174:177], v1 offset:51200
	ds_read_b128 v[184:187], v146 offset:51200
	s_mov_b64 s[100:101], s[42:43]
	s_add_u32 s42, s42, 0x80000
	s_addc_u32 s43, s43, 0
	s_mov_b32 m0, s44
	ds_read_b128 v[188:191], v147 offset:32768
	ds_read_b128 v[192:195], v147 offset:34816
	ds_read_b128 v[196:199], v148 offset:32768
	ds_read_b128 v[200:203], v148 offset:34816
	ds_read_b128 v[204:207], v147 offset:36864
	ds_read_b128 v[208:211], v147 offset:38912
	ds_read_b128 v[224:227], v148 offset:36864
	global_load_lds_dwordx4 v144, s[42:43]
	s_mov_b32 m0, s45
	ds_read_b128 v[228:231], v148 offset:38912
	global_load_lds_dwordx4 v142, s[42:43]
	s_waitcnt vmcnt(8)
	s_waitcnt lgkmcnt(0)
	s_barrier
	v_mfma_f32_16x16x32_bf16 v[132:135], v[150:153], v[188:191], v[132:135]
	v_mfma_f32_16x16x32_bf16 v[124:127], v[158:161], v[188:191], v[124:127]
	v_mfma_f32_16x16x32_bf16 v[108:111], v[150:153], v[192:195], v[108:111]
	v_mfma_f32_16x16x32_bf16 v[100:103], v[158:161], v[192:195], v[100:103]
	v_mfma_f32_16x16x32_bf16 v[92:95], v[150:153], v[204:207], v[92:95]
	v_mfma_f32_16x16x32_bf16 v[84:87], v[158:161], v[204:207], v[84:87]
	v_mfma_f32_16x16x32_bf16 v[76:79], v[150:153], v[208:211], v[76:79]
	v_mfma_f32_16x16x32_bf16 v[68:71], v[158:161], v[208:211], v[68:71]
	v_mfma_f32_16x16x32_bf16 v[132:135], v[154:157], v[196:199], v[132:135]
	v_mfma_f32_16x16x32_bf16 v[124:127], v[162:165], v[196:199], v[124:127]
	v_mfma_f32_16x16x32_bf16 v[108:111], v[154:157], v[200:203], v[108:111]
	v_mfma_f32_16x16x32_bf16 v[100:103], v[162:165], v[200:203], v[100:103]
	v_mfma_f32_16x16x32_bf16 v[92:95], v[154:157], v[224:227], v[92:95]
	v_mfma_f32_16x16x32_bf16 v[84:87], v[162:165], v[224:227], v[84:87]
	v_mfma_f32_16x16x32_bf16 v[76:79], v[154:157], v[228:231], v[76:79]
	v_mfma_f32_16x16x32_bf16 v[68:71], v[162:165], v[228:231], v[68:71]
	v_mfma_f32_16x16x32_bf16 v[136:139], v[166:169], v[188:191], v[136:139]
	v_mfma_f32_16x16x32_bf16 v[128:131], v[174:177], v[188:191], v[128:131]
	v_mfma_f32_16x16x32_bf16 v[112:115], v[166:169], v[192:195], v[112:115]
	v_mfma_f32_16x16x32_bf16 v[104:107], v[174:177], v[192:195], v[104:107]
	v_mfma_f32_16x16x32_bf16 v[96:99], v[166:169], v[204:207], v[96:99]
	v_mfma_f32_16x16x32_bf16 v[88:91], v[174:177], v[204:207], v[88:91]
	v_mfma_f32_16x16x32_bf16 v[80:83], v[166:169], v[208:211], v[80:83]
	v_mfma_f32_16x16x32_bf16 v[72:75], v[174:177], v[208:211], v[72:75]
	v_mfma_f32_16x16x32_bf16 v[136:139], v[170:173], v[196:199], v[136:139]
	v_mfma_f32_16x16x32_bf16 v[128:131], v[184:187], v[196:199], v[128:131]
	v_mfma_f32_16x16x32_bf16 v[112:115], v[170:173], v[200:203], v[112:115]
	v_mfma_f32_16x16x32_bf16 v[104:107], v[184:187], v[200:203], v[104:107]
	v_mfma_f32_16x16x32_bf16 v[96:99], v[170:173], v[224:227], v[96:99]
	v_mfma_f32_16x16x32_bf16 v[88:91], v[184:187], v[224:227], v[88:91]
	v_mfma_f32_16x16x32_bf16 v[80:83], v[170:173], v[228:231], v[80:83]
	v_mfma_f32_16x16x32_bf16 v[72:75], v[184:187], v[228:231], v[72:75]
	s_barrier
	s_add_i32 s31, s31, s33
	s_add_i32 m0, s31, 0xffffff80
	ds_read_b128 v[188:191], v147 offset:49152
	ds_read_b128 v[192:195], v147 offset:51200
	ds_read_b128 v[196:199], v148 offset:49152
	ds_read_b128 v[200:203], v148 offset:51200
	global_load_lds_dwordx4 v34, s[28:29] offset:128
	s_add_i32 m0, s31, 0x1f80
	s_mov_b64 s[98:99], s[28:29]
	s_add_u32 s28, s28, 0x80080
	s_addc_u32 s29, s29, 0
	s_add_i32 s31, s54, s33
	global_load_lds_dwordx4 v140, s[98:99] offset:128
	s_mov_b32 m0, s31
	ds_read_b128 v[204:207], v147 offset:53248
	global_load_lds_dwordx4 v34, s[28:29]
	s_add_i32 m0, s31, 0x2000
	ds_read_b128 v[208:211], v147 offset:55296
	global_load_lds_dwordx4 v140, s[28:29]
	s_add_i32 m0, s48, 0xffffff80
	ds_read_b128 v[224:227], v148 offset:53248
	global_load_lds_dwordx4 v144, s[100:101] offset:128
	s_add_i32 m0, s49, 0xffffff80
	ds_read_b128 v[228:231], v148 offset:55296
	global_load_lds_dwordx4 v142, s[100:101] offset:128
	s_waitcnt vmcnt(8)
	s_waitcnt lgkmcnt(0)
	s_barrier
	v_mfma_f32_16x16x32_bf16 v[60:63], v[150:153], v[188:191], v[60:63]
	v_mfma_f32_16x16x32_bf16 v[52:55], v[158:161], v[188:191], v[52:55]
	v_mfma_f32_16x16x32_bf16 v[44:47], v[150:153], v[192:195], v[44:47]
	v_mfma_f32_16x16x32_bf16 v[36:39], v[158:161], v[192:195], v[36:39]
	v_mfma_f32_16x16x32_bf16 v[26:29], v[150:153], v[204:207], v[26:29]
	v_mfma_f32_16x16x32_bf16 v[18:21], v[158:161], v[204:207], v[18:21]
	v_mfma_f32_16x16x32_bf16 v[10:13], v[150:153], v[208:211], v[10:13]
	v_mfma_f32_16x16x32_bf16 v[6:9], v[158:161], v[208:211], v[6:9]
	v_mfma_f32_16x16x32_bf16 v[60:63], v[154:157], v[196:199], v[60:63]
	v_mfma_f32_16x16x32_bf16 v[52:55], v[162:165], v[196:199], v[52:55]
	v_mfma_f32_16x16x32_bf16 v[44:47], v[154:157], v[200:203], v[44:47]
	v_mfma_f32_16x16x32_bf16 v[36:39], v[162:165], v[200:203], v[36:39]
	v_mfma_f32_16x16x32_bf16 v[26:29], v[154:157], v[224:227], v[26:29]
	v_mfma_f32_16x16x32_bf16 v[18:21], v[162:165], v[224:227], v[18:21]
	v_mfma_f32_16x16x32_bf16 v[10:13], v[154:157], v[228:231], v[10:13]
	v_mfma_f32_16x16x32_bf16 v[6:9], v[162:165], v[228:231], v[6:9]
	v_mfma_f32_16x16x32_bf16 v[64:67], v[166:169], v[188:191], v[64:67]
	v_mfma_f32_16x16x32_bf16 v[56:59], v[174:177], v[188:191], v[56:59]
	v_mfma_f32_16x16x32_bf16 v[48:51], v[166:169], v[192:195], v[48:51]
	v_mfma_f32_16x16x32_bf16 v[40:43], v[174:177], v[192:195], v[40:43]
	v_mfma_f32_16x16x32_bf16 v[30:33], v[166:169], v[204:207], v[30:33]
	v_mfma_f32_16x16x32_bf16 v[22:25], v[174:177], v[204:207], v[22:25]
	v_mfma_f32_16x16x32_bf16 v[14:17], v[166:169], v[208:211], v[14:17]
	v_mfma_f32_16x16x32_bf16 v[2:5], v[174:177], v[208:211], v[2:5]
	v_mfma_f32_16x16x32_bf16 v[64:67], v[170:173], v[196:199], v[64:67]
	v_mfma_f32_16x16x32_bf16 v[56:59], v[184:187], v[196:199], v[56:59]
	v_mfma_f32_16x16x32_bf16 v[48:51], v[170:173], v[200:203], v[48:51]
	v_mfma_f32_16x16x32_bf16 v[40:43], v[184:187], v[200:203], v[40:43]
	v_mfma_f32_16x16x32_bf16 v[30:33], v[170:173], v[224:227], v[30:33]
	v_mfma_f32_16x16x32_bf16 v[22:25], v[184:187], v[224:227], v[22:25]
	v_mfma_f32_16x16x32_bf16 v[14:17], v[170:173], v[228:231], v[14:17]
	v_mfma_f32_16x16x32_bf16 v[2:5], v[184:187], v[228:231], v[2:5]
	s_barrier
	s_add_i32 s30, s30, 2
	s_add_u32 s8, s8, 0x100
	s_addc_u32 s9, s9, 0
	s_add_u32 s24, s24, 0x100
	s_addc_u32 s25, s25, 0
	s_cmp_gt_u32 s30, 29
	s_cbranch_scc0 .LBB0_1114

.LBB0_1194:
	s_add_u32 s8, s8, 0x160080
	s_addc_u32 s9, s9, 0
	s_add_u32 s20, s18, 0x100
	s_addc_u32 s21, s19, 0
	s_mov_b32 s24, -2
	v_readlane_b32 s35, v255, 20
	v_readlane_b32 s40, v255, 21
	v_readlane_b32 s41, v255, 22
	v_readlane_b32 s57, v255, 23
	s_mov_b64 s[58:59], 0x80
	s_add_u32 s18, s8, 0xffea0080
	s_addc_u32 s19, s9, -1
	s_add_i32 s25, 0, 0x10000
	s_cmpk_eq_i32 s24, 0x54
	s_cselect_b32 s23, s45, s19
	s_cselect_b32 s22, s44, s18
	s_cselect_b32 s19, s47, s21
	s_cselect_b32 s18, s46, s20
	s_add_i32 s34, 0, 0x14000
	ds_read_b128 v[138:141], v1
	ds_read_b128 v[142:145], v160
	ds_read_b128 v[146:149], v1 offset:2048
	ds_read_b128 v[150:153], v160 offset:2048
	ds_read_b128 v[154:157], v1 offset:16384
	ds_read_b128 v[164:167], v160 offset:16384
	ds_read_b128 v[168:171], v1 offset:18432
	ds_read_b128 v[172:175], v160 offset:18432
	s_add_i32 m0, s29, 0xc000
	ds_read_b128 v[176:179], v161
	ds_read_b128 v[184:187], v161 offset:2048
	ds_read_b128 v[188:191], v162
	ds_read_b128 v[192:195], v162 offset:2048
	ds_read_b128 v[196:199], v161 offset:4096
	ds_read_b128 v[200:203], v161 offset:6144
	ds_read_b128 v[204:207], v162 offset:4096
	global_load_lds_dwordx4 v136, s[8:9]
	s_add_i32 m0, s29, 0xe000
	ds_read_b128 v[208:211], v162 offset:6144
	global_load_lds_dwordx4 v134, s[8:9]
	s_waitcnt vmcnt(8)
	s_waitcnt lgkmcnt(0)
	s_barrier
	v_mfma_f32_16x16x32_bf16 v[128:131], v[138:141], v[176:179], 0
	v_mfma_f32_16x16x32_bf16 v[124:127], v[146:149], v[176:179], 0
	v_mfma_f32_16x16x32_bf16 v[112:115], v[138:141], v[184:187], 0
	v_mfma_f32_16x16x32_bf16 v[108:111], v[146:149], v[184:187], 0
	v_mfma_f32_16x16x32_bf16 v[96:99], v[138:141], v[196:199], 0
	v_mfma_f32_16x16x32_bf16 v[92:95], v[146:149], v[196:199], 0
	v_mfma_f32_16x16x32_bf16 v[80:83], v[138:141], v[200:203], 0
	v_mfma_f32_16x16x32_bf16 v[76:79], v[146:149], v[200:203], 0
	v_mfma_f32_16x16x32_bf16 v[128:131], v[142:145], v[188:191], v[128:131]
	v_mfma_f32_16x16x32_bf16 v[124:127], v[150:153], v[188:191], v[124:127]
	v_mfma_f32_16x16x32_bf16 v[112:115], v[142:145], v[192:195], v[112:115]
	v_mfma_f32_16x16x32_bf16 v[108:111], v[150:153], v[192:195], v[108:111]
	v_mfma_f32_16x16x32_bf16 v[96:99], v[142:145], v[204:207], v[96:99]
	v_mfma_f32_16x16x32_bf16 v[92:95], v[150:153], v[204:207], v[92:95]
	v_mfma_f32_16x16x32_bf16 v[80:83], v[142:145], v[208:211], v[80:83]
	v_mfma_f32_16x16x32_bf16 v[76:79], v[150:153], v[208:211], v[76:79]
	v_mfma_f32_16x16x32_bf16 v[120:123], v[154:157], v[176:179], 0
	v_mfma_f32_16x16x32_bf16 v[116:119], v[168:171], v[176:179], 0
	v_mfma_f32_16x16x32_bf16 v[104:107], v[154:157], v[184:187], 0
	v_mfma_f32_16x16x32_bf16 v[100:103], v[168:171], v[184:187], 0
	v_mfma_f32_16x16x32_bf16 v[88:91], v[154:157], v[196:199], 0
	v_mfma_f32_16x16x32_bf16 v[84:87], v[168:171], v[196:199], 0
	v_mfma_f32_16x16x32_bf16 v[72:75], v[154:157], v[200:203], 0
	v_mfma_f32_16x16x32_bf16 v[68:71], v[168:171], v[200:203], 0
	v_mfma_f32_16x16x32_bf16 v[120:123], v[164:167], v[188:191], v[120:123]
	v_mfma_f32_16x16x32_bf16 v[116:119], v[172:175], v[188:191], v[116:119]
	v_mfma_f32_16x16x32_bf16 v[104:107], v[164:167], v[192:195], v[104:107]
	v_mfma_f32_16x16x32_bf16 v[100:103], v[172:175], v[192:195], v[100:103]
	v_mfma_f32_16x16x32_bf16 v[88:91], v[164:167], v[204:207], v[88:91]
	v_mfma_f32_16x16x32_bf16 v[84:87], v[172:175], v[204:207], v[84:87]
	v_mfma_f32_16x16x32_bf16 v[72:75], v[164:167], v[208:211], v[72:75]
	v_mfma_f32_16x16x32_bf16 v[68:71], v[172:175], v[208:211], v[68:71]
	s_barrier
	s_add_i32 s25, s25, s28
	s_mov_b32 m0, s25
	ds_read_b128 v[176:179], v161 offset:16384
	ds_read_b128 v[184:187], v161 offset:18432
	ds_read_b128 v[188:191], v162 offset:16384
	ds_read_b128 v[192:195], v162 offset:18432
	global_load_lds_dwordx4 v34, s[18:19]
	s_add_i32 m0, s25, 0x2000
	s_add_u32 s30, s18, 0x160000
	s_addc_u32 s31, s19, 0
	s_add_i32 s25, s34, s28
	global_load_lds_dwordx4 v132, s[18:19]
	s_mov_b32 m0, s25
	ds_read_b128 v[196:199], v161 offset:20480
	global_load_lds_dwordx4 v34, s[30:31]
	s_add_i32 m0, s25, 0x2000
	ds_read_b128 v[200:203], v161 offset:22528
	global_load_lds_dwordx4 v132, s[30:31]
	s_mov_b32 m0, s29
	ds_read_b128 v[204:207], v162 offset:20480
	global_load_lds_dwordx4 v136, s[22:23]
	s_mov_b32 m0, s33
	ds_read_b128 v[208:211], v162 offset:22528
	global_load_lds_dwordx4 v134, s[22:23]
	s_waitcnt vmcnt(8)
	s_waitcnt lgkmcnt(0)
	s_barrier
	v_mfma_f32_16x16x32_bf16 v[64:67], v[138:141], v[176:179], 0
	v_mfma_f32_16x16x32_bf16 v[60:63], v[146:149], v[176:179], 0
	v_mfma_f32_16x16x32_bf16 v[48:51], v[138:141], v[184:187], 0
	v_mfma_f32_16x16x32_bf16 v[44:47], v[146:149], v[184:187], 0
	v_mfma_f32_16x16x32_bf16 v[30:33], v[138:141], v[196:199], 0
	v_mfma_f32_16x16x32_bf16 v[26:29], v[146:149], v[196:199], 0
	v_mfma_f32_16x16x32_bf16 v[14:17], v[138:141], v[200:203], 0
	v_mfma_f32_16x16x32_bf16 v[10:13], v[146:149], v[200:203], 0
	v_mfma_f32_16x16x32_bf16 v[64:67], v[142:145], v[188:191], v[64:67]
	v_mfma_f32_16x16x32_bf16 v[60:63], v[150:153], v[188:191], v[60:63]
	v_mfma_f32_16x16x32_bf16 v[48:51], v[142:145], v[192:195], v[48:51]
	v_mfma_f32_16x16x32_bf16 v[44:47], v[150:153], v[192:195], v[44:47]
	v_mfma_f32_16x16x32_bf16 v[30:33], v[142:145], v[204:207], v[30:33]
	v_mfma_f32_16x16x32_bf16 v[26:29], v[150:153], v[204:207], v[26:29]
	v_mfma_f32_16x16x32_bf16 v[14:17], v[142:145], v[208:211], v[14:17]
	v_mfma_f32_16x16x32_bf16 v[10:13], v[150:153], v[208:211], v[10:13]
	v_mfma_f32_16x16x32_bf16 v[56:59], v[154:157], v[176:179], 0
	v_mfma_f32_16x16x32_bf16 v[52:55], v[168:171], v[176:179], 0
	v_mfma_f32_16x16x32_bf16 v[40:43], v[154:157], v[184:187], 0
	v_mfma_f32_16x16x32_bf16 v[36:39], v[168:171], v[184:187], 0
	v_mfma_f32_16x16x32_bf16 v[22:25], v[154:157], v[196:199], 0
	v_mfma_f32_16x16x32_bf16 v[18:21], v[168:171], v[196:199], 0
	v_mfma_f32_16x16x32_bf16 v[6:9], v[154:157], v[200:203], 0
	v_mfma_f32_16x16x32_bf16 v[2:5], v[168:171], v[200:203], 0
	v_mfma_f32_16x16x32_bf16 v[56:59], v[164:167], v[188:191], v[56:59]
	v_mfma_f32_16x16x32_bf16 v[52:55], v[172:175], v[188:191], v[52:55]
	v_mfma_f32_16x16x32_bf16 v[40:43], v[164:167], v[192:195], v[40:43]
	v_mfma_f32_16x16x32_bf16 v[36:39], v[172:175], v[192:195], v[36:39]
	v_mfma_f32_16x16x32_bf16 v[22:25], v[164:167], v[204:207], v[22:25]
	v_mfma_f32_16x16x32_bf16 v[18:21], v[172:175], v[204:207], v[18:21]
	v_mfma_f32_16x16x32_bf16 v[6:9], v[164:167], v[208:211], v[6:9]
	v_mfma_f32_16x16x32_bf16 v[2:5], v[172:175], v[208:211], v[2:5]
	s_barrier
	s_add_i32 s25, 0, 0x18000
	s_add_i32 s30, 0, 0x1c000
	ds_read_b128 v[138:141], v1 offset:32768
	ds_read_b128 v[142:145], v160 offset:32768
	ds_read_b128 v[146:149], v1 offset:34816
	ds_read_b128 v[150:153], v160 offset:34816
	ds_read_b128 v[154:157], v1 offset:49152
	ds_read_b128 v[164:167], v160 offset:49152
	ds_read_b128 v[168:171], v1 offset:51200
	ds_read_b128 v[172:175], v160 offset:51200
	s_mov_b64 s[100:101], s[22:23]
	s_add_u32 s22, s22, 0x160000
	s_addc_u32 s23, s23, 0
	s_mov_b32 m0, s48
	ds_read_b128 v[176:179], v161 offset:32768
	ds_read_b128 v[184:187], v161 offset:34816
	ds_read_b128 v[188:191], v162 offset:32768
	ds_read_b128 v[192:195], v162 offset:34816
	ds_read_b128 v[196:199], v161 offset:36864
	ds_read_b128 v[200:203], v161 offset:38912
	ds_read_b128 v[204:207], v162 offset:36864
	global_load_lds_dwordx4 v136, s[22:23]
	s_mov_b32 m0, s49
	ds_read_b128 v[208:211], v162 offset:38912
	global_load_lds_dwordx4 v134, s[22:23]
	s_waitcnt vmcnt(8)
	s_waitcnt lgkmcnt(0)
	s_barrier
	v_mfma_f32_16x16x32_bf16 v[128:131], v[138:141], v[176:179], v[128:131]
	v_mfma_f32_16x16x32_bf16 v[124:127], v[146:149], v[176:179], v[124:127]
	v_mfma_f32_16x16x32_bf16 v[112:115], v[138:141], v[184:187], v[112:115]
	v_mfma_f32_16x16x32_bf16 v[108:111], v[146:149], v[184:187], v[108:111]
	v_mfma_f32_16x16x32_bf16 v[96:99], v[138:141], v[196:199], v[96:99]
	v_mfma_f32_16x16x32_bf16 v[92:95], v[146:149], v[196:199], v[92:95]
	v_mfma_f32_16x16x32_bf16 v[80:83], v[138:141], v[200:203], v[80:83]
	v_mfma_f32_16x16x32_bf16 v[76:79], v[146:149], v[200:203], v[76:79]
	v_mfma_f32_16x16x32_bf16 v[128:131], v[142:145], v[188:191], v[128:131]
	v_mfma_f32_16x16x32_bf16 v[124:127], v[150:153], v[188:191], v[124:127]
	v_mfma_f32_16x16x32_bf16 v[112:115], v[142:145], v[192:195], v[112:115]
	v_mfma_f32_16x16x32_bf16 v[108:111], v[150:153], v[192:195], v[108:111]
	v_mfma_f32_16x16x32_bf16 v[96:99], v[142:145], v[204:207], v[96:99]
	v_mfma_f32_16x16x32_bf16 v[92:95], v[150:153], v[204:207], v[92:95]
	v_mfma_f32_16x16x32_bf16 v[80:83], v[142:145], v[208:211], v[80:83]
	v_mfma_f32_16x16x32_bf16 v[76:79], v[150:153], v[208:211], v[76:79]
	v_mfma_f32_16x16x32_bf16 v[120:123], v[154:157], v[176:179], v[120:123]
	v_mfma_f32_16x16x32_bf16 v[116:119], v[168:171], v[176:179], v[116:119]
	v_mfma_f32_16x16x32_bf16 v[104:107], v[154:157], v[184:187], v[104:107]
	v_mfma_f32_16x16x32_bf16 v[100:103], v[168:171], v[184:187], v[100:103]
	v_mfma_f32_16x16x32_bf16 v[88:91], v[154:157], v[196:199], v[88:91]
	v_mfma_f32_16x16x32_bf16 v[84:87], v[168:171], v[196:199], v[84:87]
	v_mfma_f32_16x16x32_bf16 v[72:75], v[154:157], v[200:203], v[72:75]
	v_mfma_f32_16x16x32_bf16 v[68:71], v[168:171], v[200:203], v[68:71]
	v_mfma_f32_16x16x32_bf16 v[120:123], v[164:167], v[188:191], v[120:123]
	v_mfma_f32_16x16x32_bf16 v[116:119], v[172:175], v[188:191], v[116:119]
	v_mfma_f32_16x16x32_bf16 v[104:107], v[164:167], v[192:195], v[104:107]
	v_mfma_f32_16x16x32_bf16 v[100:103], v[172:175], v[192:195], v[100:103]
	v_mfma_f32_16x16x32_bf16 v[88:91], v[164:167], v[204:207], v[88:91]
	v_mfma_f32_16x16x32_bf16 v[84:87], v[172:175], v[204:207], v[84:87]
	v_mfma_f32_16x16x32_bf16 v[72:75], v[164:167], v[208:211], v[72:75]
	v_mfma_f32_16x16x32_bf16 v[68:71], v[172:175], v[208:211], v[68:71]
	s_barrier
	s_add_i32 s22, s25, s28
	s_add_i32 m0, s22, 0xffffff80
	ds_read_b128 v[176:179], v161 offset:49152
	ds_read_b128 v[184:187], v161 offset:51200
	ds_read_b128 v[188:191], v162 offset:49152
	ds_read_b128 v[192:195], v162 offset:51200
	global_load_lds_dwordx4 v34, s[18:19] offset:128
	s_add_i32 m0, s22, 0x1f80
	s_mov_b64 s[98:99], s[18:19]
	s_add_u32 s18, s18, 0x160080
	s_addc_u32 s19, s19, 0
	s_add_i32 s22, s30, s28
	global_load_lds_dwordx4 v132, s[98:99] offset:128
	s_mov_b32 m0, s22
	ds_read_b128 v[196:199], v161 offset:53248
	global_load_lds_dwordx4 v34, s[18:19]
	s_add_i32 m0, s22, 0x2000
	ds_read_b128 v[200:203], v161 offset:55296
	global_load_lds_dwordx4 v132, s[18:19]
	s_add_i32 m0, s53, 0xffffff80
	ds_read_b128 v[204:207], v162 offset:53248
	global_load_lds_dwordx4 v136, s[100:101] offset:128
	s_add_i32 m0, s54, 0xffffff80
	ds_read_b128 v[208:211], v162 offset:55296
	global_load_lds_dwordx4 v134, s[100:101] offset:128
	s_waitcnt vmcnt(8)
	s_waitcnt lgkmcnt(0)
	s_barrier
	v_mfma_f32_16x16x32_bf16 v[64:67], v[138:141], v[176:179], v[64:67]
	v_mfma_f32_16x16x32_bf16 v[60:63], v[146:149], v[176:179], v[60:63]
	v_mfma_f32_16x16x32_bf16 v[48:51], v[138:141], v[184:187], v[48:51]
	v_mfma_f32_16x16x32_bf16 v[44:47], v[146:149], v[184:187], v[44:47]
	v_mfma_f32_16x16x32_bf16 v[30:33], v[138:141], v[196:199], v[30:33]
	v_mfma_f32_16x16x32_bf16 v[26:29], v[146:149], v[196:199], v[26:29]
	v_mfma_f32_16x16x32_bf16 v[14:17], v[138:141], v[200:203], v[14:17]
	v_mfma_f32_16x16x32_bf16 v[10:13], v[146:149], v[200:203], v[10:13]
	v_mfma_f32_16x16x32_bf16 v[64:67], v[142:145], v[188:191], v[64:67]
	v_mfma_f32_16x16x32_bf16 v[60:63], v[150:153], v[188:191], v[60:63]
	v_mfma_f32_16x16x32_bf16 v[48:51], v[142:145], v[192:195], v[48:51]
	v_mfma_f32_16x16x32_bf16 v[44:47], v[150:153], v[192:195], v[44:47]
	v_mfma_f32_16x16x32_bf16 v[30:33], v[142:145], v[204:207], v[30:33]
	v_mfma_f32_16x16x32_bf16 v[26:29], v[150:153], v[204:207], v[26:29]
	v_mfma_f32_16x16x32_bf16 v[14:17], v[142:145], v[208:211], v[14:17]
	v_mfma_f32_16x16x32_bf16 v[10:13], v[150:153], v[208:211], v[10:13]
	v_mfma_f32_16x16x32_bf16 v[56:59], v[154:157], v[176:179], v[56:59]
	v_mfma_f32_16x16x32_bf16 v[52:55], v[168:171], v[176:179], v[52:55]
	v_mfma_f32_16x16x32_bf16 v[40:43], v[154:157], v[184:187], v[40:43]
	v_mfma_f32_16x16x32_bf16 v[36:39], v[168:171], v[184:187], v[36:39]
	v_mfma_f32_16x16x32_bf16 v[22:25], v[154:157], v[196:199], v[22:25]
	v_mfma_f32_16x16x32_bf16 v[18:21], v[168:171], v[196:199], v[18:21]
	v_mfma_f32_16x16x32_bf16 v[6:9], v[154:157], v[200:203], v[6:9]
	v_mfma_f32_16x16x32_bf16 v[2:5], v[168:171], v[200:203], v[2:5]
	v_mfma_f32_16x16x32_bf16 v[56:59], v[164:167], v[188:191], v[56:59]
	v_mfma_f32_16x16x32_bf16 v[52:55], v[172:175], v[188:191], v[52:55]
	v_mfma_f32_16x16x32_bf16 v[40:43], v[164:167], v[192:195], v[40:43]
	v_mfma_f32_16x16x32_bf16 v[36:39], v[172:175], v[192:195], v[36:39]
	v_mfma_f32_16x16x32_bf16 v[22:25], v[164:167], v[204:207], v[22:25]
	v_mfma_f32_16x16x32_bf16 v[18:21], v[172:175], v[204:207], v[18:21]
	v_mfma_f32_16x16x32_bf16 v[6:9], v[164:167], v[208:211], v[6:9]
	v_mfma_f32_16x16x32_bf16 v[2:5], v[172:175], v[208:211], v[2:5]
	s_barrier
	s_add_i32 s24, s24, 2
	s_add_u32 s8, s8, 0x100
	s_addc_u32 s9, s9, 0
	s_add_u32 s20, s20, 0x100
	s_addc_u32 s21, s21, 0
	s_cmpk_gt_u32 s24, 0x55
	s_cbranch_scc1 .Lpeel_done_P7
.LBB0_1195:
	s_add_u32 s18, s8, 0xffea0080
	s_addc_u32 s19, s9, -1
	s_add_i32 s25, 0, 0x10000
	s_cmpk_eq_i32 s24, 0x54
	s_cselect_b32 s23, s45, s19
	s_cselect_b32 s22, s44, s18
	s_cselect_b32 s19, s47, s21
	s_cselect_b32 s18, s46, s20
	s_add_i32 s34, 0, 0x14000
	ds_read_b128 v[138:141], v1
	ds_read_b128 v[142:145], v160
	ds_read_b128 v[146:149], v1 offset:2048
	ds_read_b128 v[150:153], v160 offset:2048
	ds_read_b128 v[154:157], v1 offset:16384
	ds_read_b128 v[164:167], v160 offset:16384
	ds_read_b128 v[168:171], v1 offset:18432
	ds_read_b128 v[172:175], v160 offset:18432
	s_add_i32 m0, s29, 0xc000
	ds_read_b128 v[176:179], v161
	ds_read_b128 v[184:187], v161 offset:2048
	ds_read_b128 v[188:191], v162
	ds_read_b128 v[192:195], v162 offset:2048
	ds_read_b128 v[196:199], v161 offset:4096
	ds_read_b128 v[200:203], v161 offset:6144
	ds_read_b128 v[204:207], v162 offset:4096
	global_load_lds_dwordx4 v136, s[8:9]
	s_add_i32 m0, s29, 0xe000
	ds_read_b128 v[208:211], v162 offset:6144
	global_load_lds_dwordx4 v134, s[8:9]
	s_waitcnt vmcnt(8)
	s_waitcnt lgkmcnt(0)
	s_barrier
	v_mfma_f32_16x16x32_bf16 v[128:131], v[138:141], v[176:179], v[128:131]
	v_mfma_f32_16x16x32_bf16 v[124:127], v[146:149], v[176:179], v[124:127]
	v_mfma_f32_16x16x32_bf16 v[112:115], v[138:141], v[184:187], v[112:115]
	v_mfma_f32_16x16x32_bf16 v[108:111], v[146:149], v[184:187], v[108:111]
	v_mfma_f32_16x16x32_bf16 v[96:99], v[138:141], v[196:199], v[96:99]
	v_mfma_f32_16x16x32_bf16 v[92:95], v[146:149], v[196:199], v[92:95]
	v_mfma_f32_16x16x32_bf16 v[80:83], v[138:141], v[200:203], v[80:83]
	v_mfma_f32_16x16x32_bf16 v[76:79], v[146:149], v[200:203], v[76:79]
	v_mfma_f32_16x16x32_bf16 v[128:131], v[142:145], v[188:191], v[128:131]
	v_mfma_f32_16x16x32_bf16 v[124:127], v[150:153], v[188:191], v[124:127]
	v_mfma_f32_16x16x32_bf16 v[112:115], v[142:145], v[192:195], v[112:115]
	v_mfma_f32_16x16x32_bf16 v[108:111], v[150:153], v[192:195], v[108:111]
	v_mfma_f32_16x16x32_bf16 v[96:99], v[142:145], v[204:207], v[96:99]
	v_mfma_f32_16x16x32_bf16 v[92:95], v[150:153], v[204:207], v[92:95]
	v_mfma_f32_16x16x32_bf16 v[80:83], v[142:145], v[208:211], v[80:83]
	v_mfma_f32_16x16x32_bf16 v[76:79], v[150:153], v[208:211], v[76:79]
	v_mfma_f32_16x16x32_bf16 v[120:123], v[154:157], v[176:179], v[120:123]
	v_mfma_f32_16x16x32_bf16 v[116:119], v[168:171], v[176:179], v[116:119]
	v_mfma_f32_16x16x32_bf16 v[104:107], v[154:157], v[184:187], v[104:107]
	v_mfma_f32_16x16x32_bf16 v[100:103], v[168:171], v[184:187], v[100:103]
	v_mfma_f32_16x16x32_bf16 v[88:91], v[154:157], v[196:199], v[88:91]
	v_mfma_f32_16x16x32_bf16 v[84:87], v[168:171], v[196:199], v[84:87]
	v_mfma_f32_16x16x32_bf16 v[72:75], v[154:157], v[200:203], v[72:75]
	v_mfma_f32_16x16x32_bf16 v[68:71], v[168:171], v[200:203], v[68:71]
	v_mfma_f32_16x16x32_bf16 v[120:123], v[164:167], v[188:191], v[120:123]
	v_mfma_f32_16x16x32_bf16 v[116:119], v[172:175], v[188:191], v[116:119]
	v_mfma_f32_16x16x32_bf16 v[104:107], v[164:167], v[192:195], v[104:107]
	v_mfma_f32_16x16x32_bf16 v[100:103], v[172:175], v[192:195], v[100:103]
	v_mfma_f32_16x16x32_bf16 v[88:91], v[164:167], v[204:207], v[88:91]
	v_mfma_f32_16x16x32_bf16 v[84:87], v[172:175], v[204:207], v[84:87]
	v_mfma_f32_16x16x32_bf16 v[72:75], v[164:167], v[208:211], v[72:75]
	v_mfma_f32_16x16x32_bf16 v[68:71], v[172:175], v[208:211], v[68:71]
	s_barrier
	s_add_i32 s25, s25, s28
	s_mov_b32 m0, s25
	ds_read_b128 v[176:179], v161 offset:16384
	ds_read_b128 v[184:187], v161 offset:18432
	ds_read_b128 v[188:191], v162 offset:16384
	ds_read_b128 v[192:195], v162 offset:18432
	global_load_lds_dwordx4 v34, s[18:19]
	s_add_i32 m0, s25, 0x2000
	s_add_u32 s30, s18, 0x160000
	s_addc_u32 s31, s19, 0
	s_add_i32 s25, s34, s28
	global_load_lds_dwordx4 v132, s[18:19]
	s_mov_b32 m0, s25
	ds_read_b128 v[196:199], v161 offset:20480
	global_load_lds_dwordx4 v34, s[30:31]
	s_add_i32 m0, s25, 0x2000
	ds_read_b128 v[200:203], v161 offset:22528
	global_load_lds_dwordx4 v132, s[30:31]
	s_mov_b32 m0, s29
	ds_read_b128 v[204:207], v162 offset:20480
	global_load_lds_dwordx4 v136, s[22:23]
	s_mov_b32 m0, s33
	ds_read_b128 v[208:211], v162 offset:22528
	global_load_lds_dwordx4 v134, s[22:23]
	s_waitcnt vmcnt(8)
	s_waitcnt lgkmcnt(0)
	s_barrier
	v_mfma_f32_16x16x32_bf16 v[64:67], v[138:141], v[176:179], v[64:67]
	v_mfma_f32_16x16x32_bf16 v[60:63], v[146:149], v[176:179], v[60:63]
	v_mfma_f32_16x16x32_bf16 v[48:51], v[138:141], v[184:187], v[48:51]
	v_mfma_f32_16x16x32_bf16 v[44:47], v[146:149], v[184:187], v[44:47]
	v_mfma_f32_16x16x32_bf16 v[30:33], v[138:141], v[196:199], v[30:33]
	v_mfma_f32_16x16x32_bf16 v[26:29], v[146:149], v[196:199], v[26:29]
	v_mfma_f32_16x16x32_bf16 v[14:17], v[138:141], v[200:203], v[14:17]
	v_mfma_f32_16x16x32_bf16 v[10:13], v[146:149], v[200:203], v[10:13]
	v_mfma_f32_16x16x32_bf16 v[64:67], v[142:145], v[188:191], v[64:67]
	v_mfma_f32_16x16x32_bf16 v[60:63], v[150:153], v[188:191], v[60:63]
	v_mfma_f32_16x16x32_bf16 v[48:51], v[142:145], v[192:195], v[48:51]
	v_mfma_f32_16x16x32_bf16 v[44:47], v[150:153], v[192:195], v[44:47]
	v_mfma_f32_16x16x32_bf16 v[30:33], v[142:145], v[204:207], v[30:33]
	v_mfma_f32_16x16x32_bf16 v[26:29], v[150:153], v[204:207], v[26:29]
	v_mfma_f32_16x16x32_bf16 v[14:17], v[142:145], v[208:211], v[14:17]
	v_mfma_f32_16x16x32_bf16 v[10:13], v[150:153], v[208:211], v[10:13]
	v_mfma_f32_16x16x32_bf16 v[56:59], v[154:157], v[176:179], v[56:59]
	v_mfma_f32_16x16x32_bf16 v[52:55], v[168:171], v[176:179], v[52:55]
	v_mfma_f32_16x16x32_bf16 v[40:43], v[154:157], v[184:187], v[40:43]
	v_mfma_f32_16x16x32_bf16 v[36:39], v[168:171], v[184:187], v[36:39]
	v_mfma_f32_16x16x32_bf16 v[22:25], v[154:157], v[196:199], v[22:25]
	v_mfma_f32_16x16x32_bf16 v[18:21], v[168:171], v[196:199], v[18:21]
	v_mfma_f32_16x16x32_bf16 v[6:9], v[154:157], v[200:203], v[6:9]
	v_mfma_f32_16x16x32_bf16 v[2:5], v[168:171], v[200:203], v[2:5]
	v_mfma_f32_16x16x32_bf16 v[56:59], v[164:167], v[188:191], v[56:59]
	v_mfma_f32_16x16x32_bf16 v[52:55], v[172:175], v[188:191], v[52:55]
	v_mfma_f32_16x16x32_bf16 v[40:43], v[164:167], v[192:195], v[40:43]
	v_mfma_f32_16x16x32_bf16 v[36:39], v[172:175], v[192:195], v[36:39]
	v_mfma_f32_16x16x32_bf16 v[22:25], v[164:167], v[204:207], v[22:25]
	v_mfma_f32_16x16x32_bf16 v[18:21], v[172:175], v[204:207], v[18:21]
	v_mfma_f32_16x16x32_bf16 v[6:9], v[164:167], v[208:211], v[6:9]
	v_mfma_f32_16x16x32_bf16 v[2:5], v[172:175], v[208:211], v[2:5]
	s_barrier
	s_add_i32 s25, 0, 0x18000
	s_add_i32 s30, 0, 0x1c000
	ds_read_b128 v[138:141], v1 offset:32768
	ds_read_b128 v[142:145], v160 offset:32768
	ds_read_b128 v[146:149], v1 offset:34816
	ds_read_b128 v[150:153], v160 offset:34816
	ds_read_b128 v[154:157], v1 offset:49152
	ds_read_b128 v[164:167], v160 offset:49152
	ds_read_b128 v[168:171], v1 offset:51200
	ds_read_b128 v[172:175], v160 offset:51200
	s_mov_b64 s[100:101], s[22:23]
	s_add_u32 s22, s22, 0x160000
	s_addc_u32 s23, s23, 0
	s_mov_b32 m0, s48
	ds_read_b128 v[176:179], v161 offset:32768
	ds_read_b128 v[184:187], v161 offset:34816
	ds_read_b128 v[188:191], v162 offset:32768
	ds_read_b128 v[192:195], v162 offset:34816
	ds_read_b128 v[196:199], v161 offset:36864
	ds_read_b128 v[200:203], v161 offset:38912
	ds_read_b128 v[204:207], v162 offset:36864
	global_load_lds_dwordx4 v136, s[22:23]
	s_mov_b32 m0, s49
	ds_read_b128 v[208:211], v162 offset:38912
	global_load_lds_dwordx4 v134, s[22:23]
	s_waitcnt vmcnt(8)
	s_waitcnt lgkmcnt(0)
	s_barrier
	v_mfma_f32_16x16x32_bf16 v[128:131], v[138:141], v[176:179], v[128:131]
	v_mfma_f32_16x16x32_bf16 v[124:127], v[146:149], v[176:179], v[124:127]
	v_mfma_f32_16x16x32_bf16 v[112:115], v[138:141], v[184:187], v[112:115]
	v_mfma_f32_16x16x32_bf16 v[108:111], v[146:149], v[184:187], v[108:111]
	v_mfma_f32_16x16x32_bf16 v[96:99], v[138:141], v[196:199], v[96:99]
	v_mfma_f32_16x16x32_bf16 v[92:95], v[146:149], v[196:199], v[92:95]
	v_mfma_f32_16x16x32_bf16 v[80:83], v[138:141], v[200:203], v[80:83]
	v_mfma_f32_16x16x32_bf16 v[76:79], v[146:149], v[200:203], v[76:79]
	v_mfma_f32_16x16x32_bf16 v[128:131], v[142:145], v[188:191], v[128:131]
	v_mfma_f32_16x16x32_bf16 v[124:127], v[150:153], v[188:191], v[124:127]
	v_mfma_f32_16x16x32_bf16 v[112:115], v[142:145], v[192:195], v[112:115]
	v_mfma_f32_16x16x32_bf16 v[108:111], v[150:153], v[192:195], v[108:111]
	v_mfma_f32_16x16x32_bf16 v[96:99], v[142:145], v[204:207], v[96:99]
	v_mfma_f32_16x16x32_bf16 v[92:95], v[150:153], v[204:207], v[92:95]
	v_mfma_f32_16x16x32_bf16 v[80:83], v[142:145], v[208:211], v[80:83]
	v_mfma_f32_16x16x32_bf16 v[76:79], v[150:153], v[208:211], v[76:79]
	v_mfma_f32_16x16x32_bf16 v[120:123], v[154:157], v[176:179], v[120:123]
	v_mfma_f32_16x16x32_bf16 v[116:119], v[168:171], v[176:179], v[116:119]
	v_mfma_f32_16x16x32_bf16 v[104:107], v[154:157], v[184:187], v[104:107]
	v_mfma_f32_16x16x32_bf16 v[100:103], v[168:171], v[184:187], v[100:103]
	v_mfma_f32_16x16x32_bf16 v[88:91], v[154:157], v[196:199], v[88:91]
	v_mfma_f32_16x16x32_bf16 v[84:87], v[168:171], v[196:199], v[84:87]
	v_mfma_f32_16x16x32_bf16 v[72:75], v[154:157], v[200:203], v[72:75]
	v_mfma_f32_16x16x32_bf16 v[68:71], v[168:171], v[200:203], v[68:71]
	v_mfma_f32_16x16x32_bf16 v[120:123], v[164:167], v[188:191], v[120:123]
	v_mfma_f32_16x16x32_bf16 v[116:119], v[172:175], v[188:191], v[116:119]
	v_mfma_f32_16x16x32_bf16 v[104:107], v[164:167], v[192:195], v[104:107]
	v_mfma_f32_16x16x32_bf16 v[100:103], v[172:175], v[192:195], v[100:103]
	v_mfma_f32_16x16x32_bf16 v[88:91], v[164:167], v[204:207], v[88:91]
	v_mfma_f32_16x16x32_bf16 v[84:87], v[172:175], v[204:207], v[84:87]
	v_mfma_f32_16x16x32_bf16 v[72:75], v[164:167], v[208:211], v[72:75]
	v_mfma_f32_16x16x32_bf16 v[68:71], v[172:175], v[208:211], v[68:71]
	s_barrier
	s_add_i32 s22, s25, s28
	s_add_i32 m0, s22, 0xffffff80
	ds_read_b128 v[176:179], v161 offset:49152
	ds_read_b128 v[184:187], v161 offset:51200
	ds_read_b128 v[188:191], v162 offset:49152
	ds_read_b128 v[192:195], v162 offset:51200
	global_load_lds_dwordx4 v34, s[18:19] offset:128
	s_add_i32 m0, s22, 0x1f80
	s_mov_b64 s[98:99], s[18:19]
	s_add_u32 s18, s18, 0x160080
	s_addc_u32 s19, s19, 0
	s_add_i32 s22, s30, s28
	global_load_lds_dwordx4 v132, s[98:99] offset:128
	s_mov_b32 m0, s22
	ds_read_b128 v[196:199], v161 offset:53248
	global_load_lds_dwordx4 v34, s[18:19]
	s_add_i32 m0, s22, 0x2000
	ds_read_b128 v[200:203], v161 offset:55296
	global_load_lds_dwordx4 v132, s[18:19]
	s_add_i32 m0, s53, 0xffffff80
	ds_read_b128 v[204:207], v162 offset:53248
	global_load_lds_dwordx4 v136, s[100:101] offset:128
	s_add_i32 m0, s54, 0xffffff80
	ds_read_b128 v[208:211], v162 offset:55296
	global_load_lds_dwordx4 v134, s[100:101] offset:128
	s_waitcnt vmcnt(8)
	s_waitcnt lgkmcnt(0)
	s_barrier
	v_mfma_f32_16x16x32_bf16 v[64:67], v[138:141], v[176:179], v[64:67]
	v_mfma_f32_16x16x32_bf16 v[60:63], v[146:149], v[176:179], v[60:63]
	v_mfma_f32_16x16x32_bf16 v[48:51], v[138:141], v[184:187], v[48:51]
	v_mfma_f32_16x16x32_bf16 v[44:47], v[146:149], v[184:187], v[44:47]
	v_mfma_f32_16x16x32_bf16 v[30:33], v[138:141], v[196:199], v[30:33]
	v_mfma_f32_16x16x32_bf16 v[26:29], v[146:149], v[196:199], v[26:29]
	v_mfma_f32_16x16x32_bf16 v[14:17], v[138:141], v[200:203], v[14:17]
	v_mfma_f32_16x16x32_bf16 v[10:13], v[146:149], v[200:203], v[10:13]
	v_mfma_f32_16x16x32_bf16 v[64:67], v[142:145], v[188:191], v[64:67]
	v_mfma_f32_16x16x32_bf16 v[60:63], v[150:153], v[188:191], v[60:63]
	v_mfma_f32_16x16x32_bf16 v[48:51], v[142:145], v[192:195], v[48:51]
	v_mfma_f32_16x16x32_bf16 v[44:47], v[150:153], v[192:195], v[44:47]
	v_mfma_f32_16x16x32_bf16 v[30:33], v[142:145], v[204:207], v[30:33]
	v_mfma_f32_16x16x32_bf16 v[26:29], v[150:153], v[204:207], v[26:29]
	v_mfma_f32_16x16x32_bf16 v[14:17], v[142:145], v[208:211], v[14:17]
	v_mfma_f32_16x16x32_bf16 v[10:13], v[150:153], v[208:211], v[10:13]
	v_mfma_f32_16x16x32_bf16 v[56:59], v[154:157], v[176:179], v[56:59]
	v_mfma_f32_16x16x32_bf16 v[52:55], v[168:171], v[176:179], v[52:55]
	v_mfma_f32_16x16x32_bf16 v[40:43], v[154:157], v[184:187], v[40:43]
	v_mfma_f32_16x16x32_bf16 v[36:39], v[168:171], v[184:187], v[36:39]
	v_mfma_f32_16x16x32_bf16 v[22:25], v[154:157], v[196:199], v[22:25]
	v_mfma_f32_16x16x32_bf16 v[18:21], v[168:171], v[196:199], v[18:21]
	v_mfma_f32_16x16x32_bf16 v[6:9], v[154:157], v[200:203], v[6:9]
	v_mfma_f32_16x16x32_bf16 v[2:5], v[168:171], v[200:203], v[2:5]
	v_mfma_f32_16x16x32_bf16 v[56:59], v[164:167], v[188:191], v[56:59]
	v_mfma_f32_16x16x32_bf16 v[52:55], v[172:175], v[188:191], v[52:55]
	v_mfma_f32_16x16x32_bf16 v[40:43], v[164:167], v[192:195], v[40:43]
	v_mfma_f32_16x16x32_bf16 v[36:39], v[172:175], v[192:195], v[36:39]
	v_mfma_f32_16x16x32_bf16 v[22:25], v[164:167], v[204:207], v[22:25]
	v_mfma_f32_16x16x32_bf16 v[18:21], v[172:175], v[204:207], v[18:21]
	v_mfma_f32_16x16x32_bf16 v[6:9], v[164:167], v[208:211], v[6:9]
	v_mfma_f32_16x16x32_bf16 v[2:5], v[172:175], v[208:211], v[2:5]
	s_barrier
	s_add_i32 s24, s24, 2
	s_add_u32 s8, s8, 0x100
	s_addc_u32 s9, s9, 0
	s_add_u32 s20, s20, 0x100
	s_addc_u32 s21, s21, 0
	s_cmpk_gt_u32 s24, 0x55
	s_cbranch_scc0 .LBB0_1195
